# GEMM K-loops: per-segment s_setprio flips replaced by one static raise for waves 4-7 (set before each K-loop, reset at phase end)
# speedup vs baseline: 1.0030x; 1.0030x over previous
; #define PG8_STAGE(bufoff, gbase, voff) do { _Pragma("unroll") for (int _i = 0; _i < 2; ++_i) \
;     __builtin_amdgcn_global_load_lds((const unsigned*)((const char*)(gbase) + (voff)[_i]), (PG8_LAS unsigned*)(lds + (bufoff) + ldsw + _i * 8192), 16, 0, 0); } while (0)
; #define PG8_LDA(dst, b, h) do { _Pragma("unroll") for (int m = 0; m < 4; ++m) _Pragma("unroll") for (int k = 0; k < 2; ++k) dst[m][k] = *(const PG8_LAS bf16x8*)(lds + PG8_SA(b, h) + aoff + m * 2048 + k * 1024); } while (0)
; #define PG8_LDB(dst, b, h) do { _Pragma("unroll") for (int n = 0; n < 2; ++n) _Pragma("unroll") for (int k = 0; k < 2; ++k) dst[n][k] = *(const PG8_LAS bf16x8*)(lds + PG8_SB(b, h) + boff + n * 2048 + k * 1024); } while (0)
; #define PG8_MMA(ai, bj, At, Bt) do { __builtin_amdgcn_s_setprio(1); _Pragma("unroll") for (int m = 0; m < 4; ++m) _Pragma("unroll") for (int n = 0; n < 2; ++n) _Pragma("unroll") for (int k = 0; k < 2; ++k) \
;     acc[ai][bj][m][n] = __builtin_amdgcn_mfma_f32_16x16x32_bf16(Bt[n][k], At[m][k], acc[ai][bj][m][n], 0, 0, 0); __builtin_amdgcn_s_setprio(0); } while (0)
; #define PG8_WAIT_L(n) asm volatile("s_waitcnt lgkmcnt(" #n ")" ::: "memory")
; template <class Epi>
; __device__ __forceinline__ void gemm_phase(PG8_LAS unsigned char* lds, const Gemm g, const StaticOrder& S, const Epi& E) {
;     ...
;   for (;;) {
;     const bool has_next = S.next(ui + 1, nxt);
;     const char* nA = has_next ? (const char*)g.A + (size_t)nxt.pm * tstep : cA; const char* nB = has_next ? (const char*)g.Bt + (size_t)nxt.pn * tstep : cB;
;     for (int t = 0; t < nt; t += 2) {
;       const bool last = (t == nt - 2);
;       const char* a1 = cA + (size_t)(t + 1) * kstep;
;       const char* a2 = last ? nA : cA + (size_t)(t + 2) * kstep; const char* b2 = last ? nB : cB + (size_t)(t + 2) * kstep;
;       const char* a3 = a2 + kstep; const char* b3 = b2 + kstep;
;       PG8_LDB(B0, 0, 0); PG8_SCHED; PG8_LDA(At, 0, 0); PG8_STAGE(PG8_SA(1, 1), a1 + hstep, voffA);
;       PG8_WAIT_L(8); PG8_BAR; PG8_WAIT_L(0); PG8_MMA(0, 0, At, B0); PG8_BAR; PG8_SCHED;
;     ...
; #pragma unroll
;     for (int a = 0; a < 2; ++a)
; #pragma unroll
;       for (int b = 0; b < 2; ++b)
; #pragma unroll
;         for (int m = 0; m < 4; ++m)
; #pragma unroll
;           for (int n = 0; n < 2; ++n) acc[a][b][m][n] = (f32x4){0.f, 0.f, 0.f, 0.f};
;     cur = nxt; cA = nA; cB = nB; ++ui;
.LBB0_33:
	s_ashr_i32 s11, s10, 31
	v_cmp_lt_i64_e32 vcc, s[30:31], v[132:133]
	s_lshl_b64 s[30:31], s[10:11], 19
	s_add_u32 s30, s88, s30
	s_addc_u32 s31, s89, s31
	s_and_b64 s[44:45], vcc, exec
	s_cselect_b32 s11, s31, s49
	s_cselect_b32 s43, s30, s48
	s_ashr_i32 s9, s8, 31
	s_lshl_b64 s[44:45], s[8:9], 19
	v_readlane_b32 s9, v251, 6
	s_add_u32 s44, s9, s44
	v_readlane_b32 s9, v251, 7
	s_addc_u32 s45, s9, s45
	s_and_b64 s[52:53], vcc, exec
	s_cselect_b32 s9, s45, s51
	s_cselect_b32 s47, s44, s50
	s_add_u32 s63, s50, 0x100
	v_mov_b32_e32 v2, 0
	s_addc_u32 s64, s51, 0
	s_mov_b32 s65, -2
	v_mov_b32_e32 v3, v2
	v_mov_b32_e32 v4, v2
	v_mov_b32_e32 v5, v2
	v_mov_b32_e32 v6, v2
	v_mov_b32_e32 v7, v2
	v_mov_b32_e32 v8, v2
	v_mov_b32_e32 v9, v2
	v_mov_b32_e32 v18, v2
	v_mov_b32_e32 v19, v2
	v_mov_b32_e32 v20, v2
	v_mov_b32_e32 v21, v2
	v_mov_b32_e32 v22, v2
	v_mov_b32_e32 v23, v2
	v_mov_b32_e32 v24, v2
	v_mov_b32_e32 v25, v2
	v_mov_b32_e32 v34, v2
	v_mov_b32_e32 v35, v2
	v_mov_b32_e32 v36, v2
	v_mov_b32_e32 v37, v2
	v_mov_b32_e32 v38, v2
	v_mov_b32_e32 v39, v2
	v_mov_b32_e32 v40, v2
	v_mov_b32_e32 v41, v2
	v_mov_b32_e32 v50, v2
	v_mov_b32_e32 v51, v2
	v_mov_b32_e32 v52, v2
	v_mov_b32_e32 v53, v2
	v_mov_b32_e32 v54, v2
	v_mov_b32_e32 v55, v2
	v_mov_b32_e32 v56, v2
	v_mov_b32_e32 v57, v2
	v_mov_b32_e32 v10, v2
	v_mov_b32_e32 v11, v2
	v_mov_b32_e32 v12, v2
	v_mov_b32_e32 v13, v2
	v_mov_b32_e32 v14, v2
	v_mov_b32_e32 v15, v2
	v_mov_b32_e32 v16, v2
	v_mov_b32_e32 v17, v2
	v_mov_b32_e32 v26, v2
	v_mov_b32_e32 v27, v2
	v_mov_b32_e32 v28, v2
	v_mov_b32_e32 v29, v2
	v_mov_b32_e32 v30, v2
	v_mov_b32_e32 v31, v2
	v_mov_b32_e32 v32, v2
	v_mov_b32_e32 v33, v2
	v_mov_b32_e32 v42, v2
	v_mov_b32_e32 v43, v2
	v_mov_b32_e32 v44, v2
	v_mov_b32_e32 v45, v2
	v_mov_b32_e32 v46, v2
	v_mov_b32_e32 v47, v2
	v_mov_b32_e32 v48, v2
	v_mov_b32_e32 v49, v2
	v_mov_b32_e32 v58, v2
	v_mov_b32_e32 v59, v2
	v_mov_b32_e32 v60, v2
	v_mov_b32_e32 v61, v2
	v_mov_b32_e32 v62, v2
	v_mov_b32_e32 v63, v2
	v_mov_b32_e32 v64, v2
	v_mov_b32_e32 v65, v2
	v_mov_b32_e32 v66, v2
	v_mov_b32_e32 v67, v2
	v_mov_b32_e32 v68, v2
	v_mov_b32_e32 v69, v2
	v_mov_b32_e32 v70, v2
	v_mov_b32_e32 v71, v2
	v_mov_b32_e32 v72, v2
	v_mov_b32_e32 v73, v2
	v_mov_b32_e32 v82, v2
	v_mov_b32_e32 v83, v2
	v_mov_b32_e32 v84, v2
	v_mov_b32_e32 v85, v2
	v_mov_b32_e32 v86, v2
	v_mov_b32_e32 v87, v2
	v_mov_b32_e32 v88, v2
	v_mov_b32_e32 v89, v2
	v_mov_b32_e32 v98, v2
	v_mov_b32_e32 v99, v2
	v_mov_b32_e32 v100, v2
	v_mov_b32_e32 v101, v2
	v_mov_b32_e32 v102, v2
	v_mov_b32_e32 v103, v2
	v_mov_b32_e32 v104, v2
	v_mov_b32_e32 v105, v2
	v_mov_b32_e32 v114, v2
	v_mov_b32_e32 v115, v2
	v_mov_b32_e32 v116, v2
	v_mov_b32_e32 v117, v2
	v_mov_b32_e32 v118, v2
	v_mov_b32_e32 v119, v2
	v_mov_b32_e32 v120, v2
	v_mov_b32_e32 v121, v2
	v_mov_b32_e32 v74, v2
	v_mov_b32_e32 v75, v2
	v_mov_b32_e32 v76, v2
	v_mov_b32_e32 v77, v2
	v_mov_b32_e32 v78, v2
	v_mov_b32_e32 v79, v2
	v_mov_b32_e32 v80, v2
	v_mov_b32_e32 v81, v2
	v_mov_b32_e32 v90, v2
	v_mov_b32_e32 v91, v2
	v_mov_b32_e32 v92, v2
	v_mov_b32_e32 v93, v2
	v_mov_b32_e32 v94, v2
	v_mov_b32_e32 v95, v2
	v_mov_b32_e32 v96, v2
	v_mov_b32_e32 v97, v2
	v_mov_b32_e32 v106, v2
	v_mov_b32_e32 v107, v2
	v_mov_b32_e32 v108, v2
	v_mov_b32_e32 v109, v2
	v_mov_b32_e32 v110, v2
	v_mov_b32_e32 v111, v2
	v_mov_b32_e32 v112, v2
	v_mov_b32_e32 v113, v2
	v_mov_b32_e32 v122, v2
	v_mov_b32_e32 v123, v2
	v_mov_b32_e32 v124, v2
	v_mov_b32_e32 v125, v2
	v_mov_b32_e32 v126, v2
	v_mov_b32_e32 v127, v2
	v_mov_b32_e32 v128, v2
	v_mov_b32_e32 v129, v2
	v_readfirstlane_b32 s100, v168
	s_lshr_b32 s100, s100, 6
	s_cmp_ge_u32 s100, 4
	s_cbranch_scc0 .Lgp_0
	s_setprio 1
.Lgp_0:
.LBB0_34:
	s_add_u32 s50, s48, 0x100
	s_addc_u32 s51, s49, 0
	s_add_i32 s66, 0, 0x10000
	v_add_u32_e32 v158, s66, v160
	ds_read_b128 v[154:157], v158
	ds_read_b128 v[164:167], v158 offset:1024
	ds_read_b128 v[188:191], v158 offset:2048
	ds_read_b128 v[192:195], v158 offset:3072
	s_cmp_eq_u32 s65, 12
	s_cselect_b32 s55, s11, s51
	s_cselect_b32 s54, s43, s50
	s_cselect_b32 s53, s9, s64
	s_cselect_b32 s52, s47, s63
	v_lshl_add_u64 v[158:159], s[48:49], 0, v[150:151]
	s_add_i32 m0, s56, 0xc000
	ds_read_b128 v[196:199], v162
	ds_read_b128 v[200:203], v162 offset:1024
	ds_read_b128 v[204:207], v162 offset:2048
	ds_read_b128 v[208:211], v162 offset:3072
	ds_read_b128 v[212:215], v162 offset:4096
	ds_read_b128 v[216:219], v162 offset:5120
	ds_read_b128 v[220:223], v162 offset:6144
	ds_read_b128 v[224:227], v162 offset:7168
	global_load_lds_dwordx4 v[158:159], off
	v_lshl_add_u64 v[158:159], s[48:49], 0, v[152:153]
	s_add_i32 m0, s56, 0xe000
	s_nop 0
	global_load_lds_dwordx4 v[158:159], off
	s_waitcnt lgkmcnt(8)
	s_barrier
	s_waitcnt lgkmcnt(0)
	s_waitcnt lgkmcnt(0)
	v_mfma_f32_16x16x32_bf16 v[126:129], v[154:157], v[196:199], v[126:129]
	v_mfma_f32_16x16x32_bf16 v[122:125], v[188:191], v[196:199], v[122:125]
	v_mfma_f32_16x16x32_bf16 v[110:113], v[154:157], v[204:207], v[110:113]
	v_mfma_f32_16x16x32_bf16 v[106:109], v[188:191], v[204:207], v[106:109]
	v_mfma_f32_16x16x32_bf16 v[94:97], v[154:157], v[212:215], v[94:97]
	v_mfma_f32_16x16x32_bf16 v[90:93], v[188:191], v[212:215], v[90:93]
	v_mfma_f32_16x16x32_bf16 v[78:81], v[154:157], v[220:223], v[78:81]
	v_mfma_f32_16x16x32_bf16 v[74:77], v[188:191], v[220:223], v[74:77]
	v_mfma_f32_16x16x32_bf16 v[126:129], v[164:167], v[200:203], v[126:129]
	v_mfma_f32_16x16x32_bf16 v[122:125], v[192:195], v[200:203], v[122:125]
	v_mfma_f32_16x16x32_bf16 v[110:113], v[164:167], v[208:211], v[110:113]
	v_mfma_f32_16x16x32_bf16 v[106:109], v[192:195], v[208:211], v[106:109]
	v_mfma_f32_16x16x32_bf16 v[94:97], v[164:167], v[216:219], v[94:97]
	v_mfma_f32_16x16x32_bf16 v[90:93], v[192:195], v[216:219], v[90:93]
	v_mfma_f32_16x16x32_bf16 v[78:81], v[164:167], v[224:227], v[78:81]
	v_mfma_f32_16x16x32_bf16 v[74:77], v[192:195], v[224:227], v[74:77]
	s_barrier
; #define PG8_STAGE(bufoff, gbase, voff) do { _Pragma("unroll") for (int _i = 0; _i < 2; ++_i) \
;     __builtin_amdgcn_global_load_lds((const unsigned*)((const char*)(gbase) + (voff)[_i]), (PG8_LAS unsigned*)(lds + (bufoff) + ldsw + _i * 8192), 16, 0, 0); } while (0)
; #define PG8_LDA(dst, b, h) do { _Pragma("unroll") for (int m = 0; m < 4; ++m) _Pragma("unroll") for (int k = 0; k < 2; ++k) dst[m][k] = *(const PG8_LAS bf16x8*)(lds + PG8_SA(b, h) + aoff + m * 2048 + k * 1024); } while (0)
; #define PG8_LDB(dst, b, h) do { _Pragma("unroll") for (int n = 0; n < 2; ++n) _Pragma("unroll") for (int k = 0; k < 2; ++k) dst[n][k] = *(const PG8_LAS bf16x8*)(lds + PG8_SB(b, h) + boff + n * 2048 + k * 1024); } while (0)
; #define PG8_MMA(ai, bj, At, Bt) do { __builtin_amdgcn_s_setprio(1); _Pragma("unroll") for (int m = 0; m < 4; ++m) _Pragma("unroll") for (int n = 0; n < 2; ++n) _Pragma("unroll") for (int k = 0; k < 2; ++k) \
;     acc[ai][bj][m][n] = __builtin_amdgcn_mfma_f32_16x16x32_bf16(Bt[n][k], At[m][k], acc[ai][bj][m][n], 0, 0, 0); __builtin_amdgcn_s_setprio(0); } while (0)
; #define PG8_WAIT_V(n) asm volatile("s_waitcnt vmcnt(" #n ")" ::: "memory")
; #define PG8_WAIT_L(n) asm volatile("s_waitcnt lgkmcnt(" #n ")" ::: "memory")
; #define PG8_BAR __builtin_amdgcn_s_barrier()
; #define PG8_SCHED __builtin_amdgcn_sched_barrier(0)
; template <class Epi>
; __device__ __forceinline__ void gemm_phase(PG8_LAS unsigned char* lds, const Gemm g, const StaticOrder& S, const Epi& E) {
;     ...
;       PG8_WAIT_L(8); PG8_BAR; PG8_WAIT_L(0); PG8_MMA(0, 0, At, B0); PG8_BAR; PG8_SCHED;
;       PG8_LDB(B1, 0, 1); PG8_STAGE(PG8_SB(0, 0), b2, voffB);
;       PG8_BAR; PG8_WAIT_L(0); PG8_MMA(0, 1, At, B1); PG8_BAR;
;       PG8_LDA(At, 0, 1); PG8_STAGE(PG8_SA(0, 0), a2, voffA);
;       PG8_BAR; PG8_WAIT_L(0); PG8_MMA(1, 0, At, B0); PG8_BAR; PG8_SCHED;
;       PG8_STAGE(PG8_SB(0, 1), b2 + hstep, voffB);
;       PG8_WAIT_V(6); PG8_BAR; PG8_MMA(1, 1, At, B1); PG8_BAR;
;       PG8_LDB(B0, 1, 0); PG8_SCHED; PG8_LDA(At, 1, 0); PG8_STAGE(PG8_SA(0, 1), a2 + hstep, voffA);
;       PG8_WAIT_L(8); PG8_BAR; PG8_WAIT_L(0); PG8_MMA(0, 0, At, B0); PG8_BAR; PG8_SCHED;
	s_add_i32 s67, 0, 0x14000
	v_add_u32_e32 v158, s67, v160
	s_add_i32 s48, s66, s28
	ds_read_b128 v[228:231], v158
	ds_read_b128 v[232:235], v158 offset:1024
	ds_read_b128 v[236:239], v158 offset:2048
	ds_read_b128 v[240:243], v158 offset:3072
	v_lshl_add_u64 v[158:159], s[52:53], 0, v[0:1]
	s_mov_b32 m0, s48
	v_lshl_add_u64 v[178:179], s[52:53], 0, v[148:149]
	global_load_lds_dwordx4 v[158:159], off
	s_add_i32 m0, s48, 0x2000
	s_nop 0
	global_load_lds_dwordx4 v[178:179], off
	s_barrier
	s_waitcnt lgkmcnt(0)
	s_waitcnt lgkmcnt(0)
	v_mfma_f32_16x16x32_bf16 v[118:121], v[228:231], v[196:199], v[118:121]
	v_mfma_f32_16x16x32_bf16 v[114:117], v[236:239], v[196:199], v[114:117]
	v_mfma_f32_16x16x32_bf16 v[102:105], v[228:231], v[204:207], v[102:105]
	v_mfma_f32_16x16x32_bf16 v[98:101], v[236:239], v[204:207], v[98:101]
	v_mfma_f32_16x16x32_bf16 v[86:89], v[228:231], v[212:215], v[86:89]
	v_mfma_f32_16x16x32_bf16 v[82:85], v[236:239], v[212:215], v[82:85]
	v_mfma_f32_16x16x32_bf16 v[70:73], v[228:231], v[220:223], v[70:73]
	v_mfma_f32_16x16x32_bf16 v[66:69], v[236:239], v[220:223], v[66:69]
	v_mfma_f32_16x16x32_bf16 v[118:121], v[232:235], v[200:203], v[118:121]
	v_mfma_f32_16x16x32_bf16 v[114:117], v[240:243], v[200:203], v[114:117]
	v_mfma_f32_16x16x32_bf16 v[102:105], v[232:235], v[208:211], v[102:105]
	v_mfma_f32_16x16x32_bf16 v[98:101], v[240:243], v[208:211], v[98:101]
	v_mfma_f32_16x16x32_bf16 v[86:89], v[232:235], v[216:219], v[86:89]
	v_mfma_f32_16x16x32_bf16 v[82:85], v[240:243], v[216:219], v[82:85]
	v_mfma_f32_16x16x32_bf16 v[70:73], v[232:235], v[224:227], v[70:73]
	v_mfma_f32_16x16x32_bf16 v[66:69], v[240:243], v[224:227], v[66:69]
	s_mov_b32 m0, s56
	v_lshl_add_u64 v[244:245], s[54:55], 0, v[0:1]
	s_barrier
	ds_read_b128 v[196:199], v162 offset:16384
	ds_read_b128 v[200:203], v162 offset:17408
	ds_read_b128 v[204:207], v162 offset:18432
	ds_read_b128 v[208:211], v162 offset:19456
	ds_read_b128 v[212:215], v162 offset:20480
	ds_read_b128 v[216:219], v162 offset:21504
	ds_read_b128 v[220:223], v162 offset:22528
	ds_read_b128 v[224:227], v162 offset:23552
	global_load_lds_dwordx4 v[244:245], off
	v_lshl_add_u64 v[246:247], s[54:55], 0, v[148:149]
	s_mov_b32 m0, s57
	s_nop 0
	global_load_lds_dwordx4 v[246:247], off
	s_barrier
	s_waitcnt lgkmcnt(0)
	s_waitcnt lgkmcnt(0)
	v_mfma_f32_16x16x32_bf16 v[62:65], v[154:157], v[196:199], v[62:65]
	v_mfma_f32_16x16x32_bf16 v[58:61], v[188:191], v[196:199], v[58:61]
	v_mfma_f32_16x16x32_bf16 v[46:49], v[154:157], v[204:207], v[46:49]
	v_mfma_f32_16x16x32_bf16 v[42:45], v[188:191], v[204:207], v[42:45]
	v_mfma_f32_16x16x32_bf16 v[30:33], v[154:157], v[212:215], v[30:33]
	v_mfma_f32_16x16x32_bf16 v[26:29], v[188:191], v[212:215], v[26:29]
	v_mfma_f32_16x16x32_bf16 v[14:17], v[154:157], v[220:223], v[14:17]
	v_mfma_f32_16x16x32_bf16 v[10:13], v[188:191], v[220:223], v[10:13]
	v_mfma_f32_16x16x32_bf16 v[62:65], v[164:167], v[200:203], v[62:65]
	v_mfma_f32_16x16x32_bf16 v[58:61], v[192:195], v[200:203], v[58:61]
	v_mfma_f32_16x16x32_bf16 v[46:49], v[164:167], v[208:211], v[46:49]
	v_mfma_f32_16x16x32_bf16 v[42:45], v[192:195], v[208:211], v[42:45]
	v_mfma_f32_16x16x32_bf16 v[30:33], v[164:167], v[216:219], v[30:33]
	v_mfma_f32_16x16x32_bf16 v[26:29], v[192:195], v[216:219], v[26:29]
	v_mfma_f32_16x16x32_bf16 v[14:17], v[164:167], v[224:227], v[14:17]
	v_mfma_f32_16x16x32_bf16 v[10:13], v[192:195], v[224:227], v[10:13]
	s_barrier
	s_add_u32 s48, s52, 0x40000
	s_addc_u32 s49, s53, 0
	s_add_i32 s66, s67, s28
	v_lshl_add_u64 v[154:155], s[48:49], 0, v[0:1]
	s_mov_b32 m0, s66
	s_nop 0
	global_load_lds_dwordx4 v[154:155], off
	v_lshl_add_u64 v[154:155], s[48:49], 0, v[148:149]
	s_add_i32 m0, s66, 0x2000
	s_nop 0
	global_load_lds_dwordx4 v[154:155], off
	s_waitcnt vmcnt(6)
	s_barrier
	v_mfma_f32_16x16x32_bf16 v[54:57], v[228:231], v[196:199], v[54:57]
	v_mfma_f32_16x16x32_bf16 v[50:53], v[236:239], v[196:199], v[50:53]
	v_mfma_f32_16x16x32_bf16 v[38:41], v[228:231], v[204:207], v[38:41]
	v_mfma_f32_16x16x32_bf16 v[34:37], v[236:239], v[204:207], v[34:37]
	v_mfma_f32_16x16x32_bf16 v[22:25], v[228:231], v[212:215], v[22:25]
	v_mfma_f32_16x16x32_bf16 v[18:21], v[236:239], v[212:215], v[18:21]
	v_mfma_f32_16x16x32_bf16 v[6:9], v[228:231], v[220:223], v[6:9]
	v_mfma_f32_16x16x32_bf16 v[2:5], v[236:239], v[220:223], v[2:5]
	v_mfma_f32_16x16x32_bf16 v[54:57], v[232:235], v[200:203], v[54:57]
	v_mfma_f32_16x16x32_bf16 v[50:53], v[240:243], v[200:203], v[50:53]
	v_mfma_f32_16x16x32_bf16 v[38:41], v[232:235], v[208:211], v[38:41]
	v_mfma_f32_16x16x32_bf16 v[34:37], v[240:243], v[208:211], v[34:37]
	v_mfma_f32_16x16x32_bf16 v[22:25], v[232:235], v[216:219], v[22:25]
	v_mfma_f32_16x16x32_bf16 v[18:21], v[240:243], v[216:219], v[18:21]
	v_mfma_f32_16x16x32_bf16 v[6:9], v[232:235], v[224:227], v[6:9]
	v_mfma_f32_16x16x32_bf16 v[2:5], v[240:243], v[224:227], v[2:5]
	s_add_i32 s66, 0, 0x18000
	v_add_u32_e32 v163, s66, v160
	s_barrier
	ds_read_b128 v[154:157], v163
	ds_read_b128 v[164:167], v163 offset:1024
	ds_read_b128 v[188:191], v163 offset:2048
	ds_read_b128 v[192:195], v163 offset:3072
	s_add_u32 s48, s54, 0x40000
	s_addc_u32 s49, s55, 0
	s_mov_b32 m0, s58
	v_lshl_add_u64 v[228:229], s[48:49], 0, v[0:1]
	ds_read_b128 v[196:199], v162 offset:32768
	ds_read_b128 v[200:203], v162 offset:33792
	ds_read_b128 v[204:207], v162 offset:34816
	ds_read_b128 v[208:211], v162 offset:35840
	ds_read_b128 v[212:215], v162 offset:36864
	ds_read_b128 v[216:219], v162 offset:37888
	ds_read_b128 v[220:223], v162 offset:38912
	ds_read_b128 v[224:227], v162 offset:39936
	global_load_lds_dwordx4 v[228:229], off
	v_lshl_add_u64 v[228:229], s[48:49], 0, v[148:149]
	s_mov_b32 m0, s59
	s_nop 0
	global_load_lds_dwordx4 v[228:229], off
	s_waitcnt lgkmcnt(8)
	s_barrier
; #define PG8_STAGE(bufoff, gbase, voff) do { _Pragma("unroll") for (int _i = 0; _i < 2; ++_i) \
;     __builtin_amdgcn_global_load_lds((const unsigned*)((const char*)(gbase) + (voff)[_i]), (PG8_LAS unsigned*)(lds + (bufoff) + ldsw + _i * 8192), 16, 0, 0); } while (0)
; #define PG8_LDA(dst, b, h) do { _Pragma("unroll") for (int m = 0; m < 4; ++m) _Pragma("unroll") for (int k = 0; k < 2; ++k) dst[m][k] = *(const PG8_LAS bf16x8*)(lds + PG8_SA(b, h) + aoff + m * 2048 + k * 1024); } while (0)
; #define PG8_LDB(dst, b, h) do { _Pragma("unroll") for (int n = 0; n < 2; ++n) _Pragma("unroll") for (int k = 0; k < 2; ++k) dst[n][k] = *(const PG8_LAS bf16x8*)(lds + PG8_SB(b, h) + boff + n * 2048 + k * 1024); } while (0)
; #define PG8_MMA(ai, bj, At, Bt) do { __builtin_amdgcn_s_setprio(1); _Pragma("unroll") for (int m = 0; m < 4; ++m) _Pragma("unroll") for (int n = 0; n < 2; ++n) _Pragma("unroll") for (int k = 0; k < 2; ++k) \
;     acc[ai][bj][m][n] = __builtin_amdgcn_mfma_f32_16x16x32_bf16(Bt[n][k], At[m][k], acc[ai][bj][m][n], 0, 0, 0); __builtin_amdgcn_s_setprio(0); } while (0)
; #define PG8_WAIT_V(n) asm volatile("s_waitcnt vmcnt(" #n ")" ::: "memory")
; #define PG8_WAIT_L(n) asm volatile("s_waitcnt lgkmcnt(" #n ")" ::: "memory")
; #define PG8_BAR __builtin_amdgcn_s_barrier()
; #define PG8_SCHED __builtin_amdgcn_sched_barrier(0)
; template <class Epi>
; __device__ __forceinline__ void gemm_phase(PG8_LAS unsigned char* lds, const Gemm g, const StaticOrder& S, const Epi& E) {
;     ...
;       PG8_WAIT_L(8); PG8_BAR; PG8_WAIT_L(0); PG8_MMA(0, 0, At, B0); PG8_BAR; PG8_SCHED;
;       PG8_LDB(B1, 1, 1); PG8_STAGE(PG8_SB(1, 0), b3, voffB);
;       PG8_BAR; PG8_WAIT_L(0); PG8_MMA(0, 1, At, B1); PG8_BAR;
;       PG8_LDA(At, 1, 1); PG8_STAGE(PG8_SA(1, 0), a3, voffA);
;       PG8_BAR; PG8_WAIT_L(0); PG8_MMA(1, 0, At, B0); PG8_BAR; PG8_SCHED;
;       PG8_STAGE(PG8_SB(1, 1), b3 + hstep, voffB);
;       PG8_WAIT_V(6); PG8_BAR; PG8_MMA(1, 1, At, B1); PG8_BAR;
;     }
;     E(acc, cur, wr, wc, fr, fq);
	s_waitcnt lgkmcnt(0)
	s_waitcnt lgkmcnt(0)
	v_mfma_f32_16x16x32_bf16 v[126:129], v[154:157], v[196:199], v[126:129]
	v_mfma_f32_16x16x32_bf16 v[122:125], v[188:191], v[196:199], v[122:125]
	v_mfma_f32_16x16x32_bf16 v[110:113], v[154:157], v[204:207], v[110:113]
	v_mfma_f32_16x16x32_bf16 v[106:109], v[188:191], v[204:207], v[106:109]
	v_mfma_f32_16x16x32_bf16 v[94:97], v[154:157], v[212:215], v[94:97]
	v_mfma_f32_16x16x32_bf16 v[90:93], v[188:191], v[212:215], v[90:93]
	v_mfma_f32_16x16x32_bf16 v[78:81], v[154:157], v[220:223], v[78:81]
	v_mfma_f32_16x16x32_bf16 v[74:77], v[188:191], v[220:223], v[74:77]
	v_mfma_f32_16x16x32_bf16 v[126:129], v[164:167], v[200:203], v[126:129]
	v_mfma_f32_16x16x32_bf16 v[122:125], v[192:195], v[200:203], v[122:125]
	v_mfma_f32_16x16x32_bf16 v[110:113], v[164:167], v[208:211], v[110:113]
	v_mfma_f32_16x16x32_bf16 v[106:109], v[192:195], v[208:211], v[106:109]
	v_mfma_f32_16x16x32_bf16 v[94:97], v[164:167], v[216:219], v[94:97]
	v_mfma_f32_16x16x32_bf16 v[90:93], v[192:195], v[216:219], v[90:93]
	v_mfma_f32_16x16x32_bf16 v[78:81], v[164:167], v[224:227], v[78:81]
	v_mfma_f32_16x16x32_bf16 v[74:77], v[192:195], v[224:227], v[74:77]
	s_barrier
	s_add_i32 s54, 0, 0x1c000
	s_add_i32 s48, s66, s28
	v_add_u32_e32 v163, s54, v160
	v_lshl_add_u64 v[158:159], v[158:159], 0, s[4:5]
	s_mov_b32 m0, s48
	ds_read_b128 v[228:231], v163
	ds_read_b128 v[232:235], v163 offset:1024
	ds_read_b128 v[236:239], v163 offset:2048
	ds_read_b128 v[240:243], v163 offset:3072
	global_load_lds_dwordx4 v[158:159], off
	v_lshl_add_u64 v[158:159], v[178:179], 0, s[4:5]
	s_add_i32 m0, s48, 0x2000
	s_nop 0
	global_load_lds_dwordx4 v[158:159], off
	s_barrier
	s_waitcnt lgkmcnt(0)
	s_waitcnt lgkmcnt(0)
	v_mfma_f32_16x16x32_bf16 v[118:121], v[228:231], v[196:199], v[118:121]
	v_mfma_f32_16x16x32_bf16 v[114:117], v[236:239], v[196:199], v[114:117]
	v_mfma_f32_16x16x32_bf16 v[102:105], v[228:231], v[204:207], v[102:105]
	v_mfma_f32_16x16x32_bf16 v[98:101], v[236:239], v[204:207], v[98:101]
	v_mfma_f32_16x16x32_bf16 v[86:89], v[228:231], v[212:215], v[86:89]
	v_mfma_f32_16x16x32_bf16 v[82:85], v[236:239], v[212:215], v[82:85]
	v_mfma_f32_16x16x32_bf16 v[70:73], v[228:231], v[220:223], v[70:73]
	v_mfma_f32_16x16x32_bf16 v[66:69], v[236:239], v[220:223], v[66:69]
	v_mfma_f32_16x16x32_bf16 v[118:121], v[232:235], v[200:203], v[118:121]
	v_mfma_f32_16x16x32_bf16 v[114:117], v[240:243], v[200:203], v[114:117]
	v_mfma_f32_16x16x32_bf16 v[102:105], v[232:235], v[208:211], v[102:105]
	v_mfma_f32_16x16x32_bf16 v[98:101], v[240:243], v[208:211], v[98:101]
	v_mfma_f32_16x16x32_bf16 v[86:89], v[232:235], v[216:219], v[86:89]
	v_mfma_f32_16x16x32_bf16 v[82:85], v[240:243], v[216:219], v[82:85]
	v_mfma_f32_16x16x32_bf16 v[70:73], v[232:235], v[224:227], v[70:73]
	v_mfma_f32_16x16x32_bf16 v[66:69], v[240:243], v[224:227], v[66:69]
	s_mov_b32 m0, s60
	v_lshl_add_u64 v[158:159], v[244:245], 0, s[4:5]
	s_barrier
	ds_read_b128 v[196:199], v162 offset:49152
	ds_read_b128 v[200:203], v162 offset:50176
	ds_read_b128 v[204:207], v162 offset:51200
	ds_read_b128 v[208:211], v162 offset:52224
	ds_read_b128 v[212:215], v162 offset:53248
	ds_read_b128 v[216:219], v162 offset:54272
	ds_read_b128 v[220:223], v162 offset:55296
	ds_read_b128 v[224:227], v162 offset:56320
	global_load_lds_dwordx4 v[158:159], off
	v_lshl_add_u64 v[158:159], v[246:247], 0, s[4:5]
	s_mov_b32 m0, s61
	s_nop 0
	global_load_lds_dwordx4 v[158:159], off
	s_barrier
	s_waitcnt lgkmcnt(0)
	s_waitcnt lgkmcnt(0)
	v_mfma_f32_16x16x32_bf16 v[62:65], v[154:157], v[196:199], v[62:65]
	v_mfma_f32_16x16x32_bf16 v[58:61], v[188:191], v[196:199], v[58:61]
	v_mfma_f32_16x16x32_bf16 v[46:49], v[154:157], v[204:207], v[46:49]
	v_mfma_f32_16x16x32_bf16 v[42:45], v[188:191], v[204:207], v[42:45]
	v_mfma_f32_16x16x32_bf16 v[30:33], v[154:157], v[212:215], v[30:33]
	v_mfma_f32_16x16x32_bf16 v[26:29], v[188:191], v[212:215], v[26:29]
	v_mfma_f32_16x16x32_bf16 v[14:17], v[154:157], v[220:223], v[14:17]
	v_mfma_f32_16x16x32_bf16 v[10:13], v[188:191], v[220:223], v[10:13]
	v_mfma_f32_16x16x32_bf16 v[62:65], v[164:167], v[200:203], v[62:65]
	v_mfma_f32_16x16x32_bf16 v[58:61], v[192:195], v[200:203], v[58:61]
	v_mfma_f32_16x16x32_bf16 v[46:49], v[164:167], v[208:211], v[46:49]
	v_mfma_f32_16x16x32_bf16 v[42:45], v[192:195], v[208:211], v[42:45]
	v_mfma_f32_16x16x32_bf16 v[30:33], v[164:167], v[216:219], v[30:33]
	v_mfma_f32_16x16x32_bf16 v[26:29], v[192:195], v[216:219], v[26:29]
	v_mfma_f32_16x16x32_bf16 v[14:17], v[164:167], v[224:227], v[14:17]
	v_mfma_f32_16x16x32_bf16 v[10:13], v[192:195], v[224:227], v[10:13]
	s_barrier
	s_add_u32 s48, s52, 0x40080
	s_addc_u32 s49, s53, 0
	s_add_i32 s52, s54, s28
	v_lshl_add_u64 v[154:155], s[48:49], 0, v[0:1]
	s_mov_b32 m0, s52
	s_nop 0
	global_load_lds_dwordx4 v[154:155], off
	v_lshl_add_u64 v[154:155], s[48:49], 0, v[148:149]
	s_add_i32 m0, s52, 0x2000
	s_nop 0
	global_load_lds_dwordx4 v[154:155], off
	s_waitcnt vmcnt(6)
	s_barrier
	v_mfma_f32_16x16x32_bf16 v[54:57], v[228:231], v[196:199], v[54:57]
	v_mfma_f32_16x16x32_bf16 v[50:53], v[236:239], v[196:199], v[50:53]
	v_mfma_f32_16x16x32_bf16 v[38:41], v[228:231], v[204:207], v[38:41]
	v_mfma_f32_16x16x32_bf16 v[34:37], v[236:239], v[204:207], v[34:37]
	v_mfma_f32_16x16x32_bf16 v[22:25], v[228:231], v[212:215], v[22:25]
	v_mfma_f32_16x16x32_bf16 v[18:21], v[236:239], v[212:215], v[18:21]
	v_mfma_f32_16x16x32_bf16 v[6:9], v[228:231], v[220:223], v[6:9]
	v_mfma_f32_16x16x32_bf16 v[2:5], v[236:239], v[220:223], v[2:5]
	v_mfma_f32_16x16x32_bf16 v[54:57], v[232:235], v[200:203], v[54:57]
	v_mfma_f32_16x16x32_bf16 v[50:53], v[240:243], v[200:203], v[50:53]
	v_mfma_f32_16x16x32_bf16 v[38:41], v[232:235], v[208:211], v[38:41]
	v_mfma_f32_16x16x32_bf16 v[34:37], v[240:243], v[208:211], v[34:37]
	v_mfma_f32_16x16x32_bf16 v[22:25], v[232:235], v[216:219], v[22:25]
	v_mfma_f32_16x16x32_bf16 v[18:21], v[240:243], v[216:219], v[18:21]
	v_mfma_f32_16x16x32_bf16 v[6:9], v[232:235], v[224:227], v[6:9]
	v_mfma_f32_16x16x32_bf16 v[2:5], v[240:243], v[224:227], v[2:5]
	s_add_i32 s65, s65, 2
	s_add_u32 s63, s63, 0x100
	s_addc_u32 s64, s64, 0
	s_cmp_gt_u32 s65, 13
	s_mov_b64 s[48:49], s[50:51]
	s_barrier
	s_cbranch_scc0 .LBB0_34
	v_readlane_b32 s80, v254, 5
	v_readlane_b32 s81, v254, 6
	v_readlane_b32 s82, v254, 7
	v_readlane_b32 s83, v254, 8
	s_cmp_ge_i32 s46, 65
	s_cselect_b32 s68, 1, 0
	s_mul_i32 s69, s68, 65
	s_sub_i32 s69, s46, s69
	s_cmp_eq_u32 s69, 0
	s_cbranch_scc1 .LepiA_ctx
	s_add_i32 s69, s69, -1
	s_lshl_b32 s69, s69, 8
	s_lshl_b32 s70, s68, 14
	s_add_i32 s69, s69, s70
	s_lshl_b32 s69, s69, 12
	s_add_u32 s70, s80, s69
	s_addc_u32 s71, s81, 0
	s_mul_i32 s68, s68, 0x3000
	s_branch .LepiA_go

; #define PG8_WAIT_V(n) asm volatile("s_waitcnt vmcnt(" #n ")" ::: "memory")
; #define PG8_WAIT_L(n) asm volatile("s_waitcnt lgkmcnt(" #n ")" ::: "memory")
; #define PG8_BAR __builtin_amdgcn_s_barrier()
; template <class Epi>
; __device__ __forceinline__ void gemm_phase(PG8_LAS unsigned char* lds, const Gemm g, const StaticOrder& S, const Epi& E) {
;     ...
;   for (;;) {
;     const bool has_next = S.next(ui + 1, nxt);
;     const char* nA = has_next ? (const char*)g.A + (size_t)nxt.pm * tstep : cA; const char* nB = has_next ? (const char*)g.Bt + (size_t)nxt.pn * tstep : cB;
;     for (int t = 0; t < nt; t += 2) {
;       const bool last = (t == nt - 2);
;       const char* a1 = cA + (size_t)(t + 1) * kstep;
;       const char* a2 = last ? nA : cA + (size_t)(t + 2) * kstep; const char* b2 = last ? nB : cB + (size_t)(t + 2) * kstep;
;       const char* a3 = a2 + kstep; const char* b3 = b2 + kstep;
;       PG8_LDB(B0, 0, 0); PG8_SCHED; PG8_LDA(At, 0, 0); PG8_STAGE(PG8_SA(1, 1), a1 + hstep, voffA);
;       PG8_WAIT_L(8); PG8_BAR; PG8_WAIT_L(0); PG8_MMA(0, 0, At, B0); PG8_BAR; PG8_SCHED;
;       PG8_LDB(B1, 0, 1); PG8_STAGE(PG8_SB(0, 0), b2, voffB);
;       PG8_BAR; PG8_WAIT_L(0); PG8_MMA(0, 1, At, B1); PG8_BAR;
;       PG8_LDA(At, 0, 1); PG8_STAGE(PG8_SA(0, 0), a2, voffA);
;       PG8_BAR; PG8_WAIT_L(0); PG8_MMA(1, 0, At, B0); PG8_BAR; PG8_SCHED;
;       PG8_STAGE(PG8_SB(0, 1), b2 + hstep, voffB);
;       PG8_WAIT_V(6); PG8_BAR; PG8_MMA(1, 1, At, B1); PG8_BAR;
;       PG8_LDB(B0, 1, 0); PG8_SCHED; PG8_LDA(At, 1, 0); PG8_STAGE(PG8_SA(0, 1), a2 + hstep, voffA);
;       PG8_WAIT_L(8); PG8_BAR; PG8_WAIT_L(0); PG8_MMA(0, 0, At, B0); PG8_BAR; PG8_SCHED;
;       PG8_LDB(B1, 1, 1); PG8_STAGE(PG8_SB(1, 0), b3, voffB);
;       PG8_BAR; PG8_WAIT_L(0); PG8_MMA(0, 1, At, B1); PG8_BAR;
;       PG8_LDA(At, 1, 1); PG8_STAGE(PG8_SA(1, 0), a3, voffA);
;       PG8_BAR; PG8_WAIT_L(0); PG8_MMA(1, 0, At, B0); PG8_BAR; PG8_SCHED;
;       PG8_STAGE(PG8_SB(1, 1), b3 + hstep, voffB);
;       PG8_WAIT_V(6); PG8_BAR; PG8_MMA(1, 1, At, B1); PG8_BAR;
;     }
;     E(acc, cur, wr, wc, fr, fq);
;     if (!has_next) break;
; #pragma unroll
;     for (int a = 0; a < 2; ++a)
; #pragma unroll
;       for (int b = 0; b < 2; ++b)
; #pragma unroll
;         for (int m = 0; m < 4; ++m)
; #pragma unroll
;           for (int n = 0; n < 2; ++n) acc[a][b][m][n] = (f32x4){0.f, 0.f, 0.f, 0.f};
.LBB0_293:
	s_ashr_i32 s51, s50, 31
	v_cmp_lt_i64_e32 vcc, s[44:45], v[136:137]
	s_lshl_b64 s[44:45], s[50:51], 20
	s_add_u32 s52, s24, s44
	s_addc_u32 s53, s25, s45
	s_and_b64 s[44:45], vcc, exec
	s_cselect_b32 s7, s53, s11
	s_cselect_b32 s9, s52, s10
	s_ashr_i32 s31, s30, 31
	s_lshl_b64 s[44:45], s[30:31], 20
	s_add_u32 s54, s22, s44
	s_addc_u32 s55, s23, s45
	s_and_b64 s[44:45], vcc, exec
	s_cselect_b32 s31, s55, s43
	s_cselect_b32 s46, s54, s42
	s_add_u32 s10, s10, 0x80080
	s_addc_u32 s11, s11, 0
	s_add_u32 s47, s42, 0x100
	v_mov_b32_e32 v2, 0
	s_addc_u32 s48, s43, 0
	s_mov_b32 s49, -2
	v_mov_b32_e32 v3, v2
	v_mov_b32_e32 v4, v2
	v_mov_b32_e32 v5, v2
	v_mov_b32_e32 v6, v2
	v_mov_b32_e32 v7, v2
	v_mov_b32_e32 v8, v2
	v_mov_b32_e32 v9, v2
	v_mov_b32_e32 v18, v2
	v_mov_b32_e32 v19, v2
	v_mov_b32_e32 v20, v2
	v_mov_b32_e32 v21, v2
	v_mov_b32_e32 v22, v2
	v_mov_b32_e32 v23, v2
	v_mov_b32_e32 v24, v2
	v_mov_b32_e32 v25, v2
	v_mov_b32_e32 v34, v2
	v_mov_b32_e32 v35, v2
	v_mov_b32_e32 v36, v2
	v_mov_b32_e32 v37, v2
	v_mov_b32_e32 v38, v2
	v_mov_b32_e32 v39, v2
	v_mov_b32_e32 v40, v2
	v_mov_b32_e32 v41, v2
	v_mov_b32_e32 v50, v2
	v_mov_b32_e32 v51, v2
	v_mov_b32_e32 v52, v2
	v_mov_b32_e32 v53, v2
	v_mov_b32_e32 v54, v2
	v_mov_b32_e32 v55, v2
	v_mov_b32_e32 v56, v2
	v_mov_b32_e32 v57, v2
	v_mov_b32_e32 v10, v2
	v_mov_b32_e32 v11, v2
	v_mov_b32_e32 v12, v2
	v_mov_b32_e32 v13, v2
	v_mov_b32_e32 v14, v2
	v_mov_b32_e32 v15, v2
	v_mov_b32_e32 v16, v2
	v_mov_b32_e32 v17, v2
	v_mov_b32_e32 v26, v2
	v_mov_b32_e32 v27, v2
	v_mov_b32_e32 v28, v2
	v_mov_b32_e32 v29, v2
	v_mov_b32_e32 v30, v2
	v_mov_b32_e32 v31, v2
	v_mov_b32_e32 v32, v2
	v_mov_b32_e32 v33, v2
	v_mov_b32_e32 v42, v2
	v_mov_b32_e32 v43, v2
	v_mov_b32_e32 v44, v2
	v_mov_b32_e32 v45, v2
	v_mov_b32_e32 v46, v2
	v_mov_b32_e32 v47, v2
	v_mov_b32_e32 v48, v2
	v_mov_b32_e32 v49, v2
	v_mov_b32_e32 v58, v2
	v_mov_b32_e32 v59, v2
	v_mov_b32_e32 v60, v2
	v_mov_b32_e32 v61, v2
	v_mov_b32_e32 v62, v2
	v_mov_b32_e32 v63, v2
	v_mov_b32_e32 v64, v2
	v_mov_b32_e32 v65, v2
	v_mov_b32_e32 v66, v2
	v_mov_b32_e32 v67, v2
	v_mov_b32_e32 v68, v2
	v_mov_b32_e32 v69, v2
	v_mov_b32_e32 v70, v2
	v_mov_b32_e32 v71, v2
	v_mov_b32_e32 v72, v2
	v_mov_b32_e32 v73, v2
	v_mov_b32_e32 v82, v2
	v_mov_b32_e32 v83, v2
	v_mov_b32_e32 v84, v2
	v_mov_b32_e32 v85, v2
	v_mov_b32_e32 v86, v2
	v_mov_b32_e32 v87, v2
	v_mov_b32_e32 v88, v2
	v_mov_b32_e32 v89, v2
	v_mov_b32_e32 v98, v2
	v_mov_b32_e32 v99, v2
	v_mov_b32_e32 v100, v2
	v_mov_b32_e32 v101, v2
	v_mov_b32_e32 v102, v2
	v_mov_b32_e32 v103, v2
	v_mov_b32_e32 v104, v2
	v_mov_b32_e32 v105, v2
	v_mov_b32_e32 v114, v2
	v_mov_b32_e32 v115, v2
	v_mov_b32_e32 v116, v2
	v_mov_b32_e32 v117, v2
	v_mov_b32_e32 v118, v2
	v_mov_b32_e32 v119, v2
	v_mov_b32_e32 v120, v2
	v_mov_b32_e32 v121, v2
	v_mov_b32_e32 v74, v2
	v_mov_b32_e32 v75, v2
	v_mov_b32_e32 v76, v2
	v_mov_b32_e32 v77, v2
	v_mov_b32_e32 v78, v2
	v_mov_b32_e32 v79, v2
	v_mov_b32_e32 v80, v2
	v_mov_b32_e32 v81, v2
	v_mov_b32_e32 v90, v2
	v_mov_b32_e32 v91, v2
	v_mov_b32_e32 v92, v2
	v_mov_b32_e32 v93, v2
	v_mov_b32_e32 v94, v2
	v_mov_b32_e32 v95, v2
	v_mov_b32_e32 v96, v2
	v_mov_b32_e32 v97, v2
	v_mov_b32_e32 v106, v2
	v_mov_b32_e32 v107, v2
	v_mov_b32_e32 v108, v2
	v_mov_b32_e32 v109, v2
	v_mov_b32_e32 v110, v2
	v_mov_b32_e32 v111, v2
	v_mov_b32_e32 v112, v2
	v_mov_b32_e32 v113, v2
	v_mov_b32_e32 v122, v2
	v_mov_b32_e32 v123, v2
	v_mov_b32_e32 v124, v2
	v_mov_b32_e32 v125, v2
	v_mov_b32_e32 v126, v2
	v_mov_b32_e32 v127, v2
	v_mov_b32_e32 v128, v2
	v_mov_b32_e32 v129, v2
	v_readfirstlane_b32 s100, v168
	s_lshr_b32 s100, s100, 6
	s_cmp_ge_u32 s100, 4
	s_cbranch_scc0 .Lgp_1
	s_setprio 1
.Lgp_1:
.LBB0_294:
	s_add_u32 s42, s10, 0xfff80080
	s_addc_u32 s43, s11, -1
	s_add_i32 s51, 0, 0x10000
	v_add_u32_e32 v0, s51, v166
	ds_read_b128 v[158:161], v0
	ds_read_b128 v[162:165], v0 offset:1024
	ds_read_b128 v[188:191], v0 offset:2048
	ds_read_b128 v[192:195], v0 offset:3072
	s_cmp_eq_u32 s49, 28
	s_cselect_b32 s45, s7, s43
	s_cselect_b32 s44, s9, s42
	s_cselect_b32 s43, s31, s48
	s_cselect_b32 s42, s46, s47
	v_lshl_add_u64 v[178:179], s[10:11], 0, v[154:155]
	s_add_i32 m0, s58, 0xc000
	ds_read_b128 v[196:199], v167
	ds_read_b128 v[200:203], v167 offset:1024
	ds_read_b128 v[204:207], v167 offset:2048
	ds_read_b128 v[208:211], v167 offset:3072
	ds_read_b128 v[212:215], v167 offset:4096
	ds_read_b128 v[216:219], v167 offset:5120
	ds_read_b128 v[220:223], v167 offset:6144
	ds_read_b128 v[224:227], v167 offset:7168
	global_load_lds_dwordx4 v[178:179], off
	v_lshl_add_u64 v[178:179], s[10:11], 0, v[156:157]
	s_add_i32 m0, s58, 0xe000
	s_nop 0
	global_load_lds_dwordx4 v[178:179], off
	s_waitcnt lgkmcnt(8)
	s_barrier
	s_waitcnt lgkmcnt(0)
	s_waitcnt lgkmcnt(0)
	v_mfma_f32_16x16x32_bf16 v[126:129], v[158:161], v[196:199], v[126:129]
	v_mfma_f32_16x16x32_bf16 v[122:125], v[188:191], v[196:199], v[122:125]
	v_mfma_f32_16x16x32_bf16 v[110:113], v[158:161], v[204:207], v[110:113]
	v_mfma_f32_16x16x32_bf16 v[106:109], v[188:191], v[204:207], v[106:109]
	v_mfma_f32_16x16x32_bf16 v[94:97], v[158:161], v[212:215], v[94:97]
	v_mfma_f32_16x16x32_bf16 v[90:93], v[188:191], v[212:215], v[90:93]
	v_mfma_f32_16x16x32_bf16 v[78:81], v[158:161], v[220:223], v[78:81]
	v_mfma_f32_16x16x32_bf16 v[74:77], v[188:191], v[220:223], v[74:77]
	v_mfma_f32_16x16x32_bf16 v[126:129], v[162:165], v[200:203], v[126:129]
	v_mfma_f32_16x16x32_bf16 v[122:125], v[192:195], v[200:203], v[122:125]
	v_mfma_f32_16x16x32_bf16 v[110:113], v[162:165], v[208:211], v[110:113]
	v_mfma_f32_16x16x32_bf16 v[106:109], v[192:195], v[208:211], v[106:109]
	v_mfma_f32_16x16x32_bf16 v[94:97], v[162:165], v[216:219], v[94:97]
	v_mfma_f32_16x16x32_bf16 v[90:93], v[192:195], v[216:219], v[90:93]
	v_mfma_f32_16x16x32_bf16 v[78:81], v[162:165], v[224:227], v[78:81]
	v_mfma_f32_16x16x32_bf16 v[74:77], v[192:195], v[224:227], v[74:77]
	s_barrier
; #define PG8_STAGE(bufoff, gbase, voff) do { _Pragma("unroll") for (int _i = 0; _i < 2; ++_i) \
;     __builtin_amdgcn_global_load_lds((const unsigned*)((const char*)(gbase) + (voff)[_i]), (PG8_LAS unsigned*)(lds + (bufoff) + ldsw + _i * 8192), 16, 0, 0); } while (0)
; #define PG8_LDA(dst, b, h) do { _Pragma("unroll") for (int m = 0; m < 4; ++m) _Pragma("unroll") for (int k = 0; k < 2; ++k) dst[m][k] = *(const PG8_LAS bf16x8*)(lds + PG8_SA(b, h) + aoff + m * 2048 + k * 1024); } while (0)
; #define PG8_LDB(dst, b, h) do { _Pragma("unroll") for (int n = 0; n < 2; ++n) _Pragma("unroll") for (int k = 0; k < 2; ++k) dst[n][k] = *(const PG8_LAS bf16x8*)(lds + PG8_SB(b, h) + boff + n * 2048 + k * 1024); } while (0)
; #define PG8_MMA(ai, bj, At, Bt) do { __builtin_amdgcn_s_setprio(1); _Pragma("unroll") for (int m = 0; m < 4; ++m) _Pragma("unroll") for (int n = 0; n < 2; ++n) _Pragma("unroll") for (int k = 0; k < 2; ++k) \
;     acc[ai][bj][m][n] = __builtin_amdgcn_mfma_f32_16x16x32_bf16(Bt[n][k], At[m][k], acc[ai][bj][m][n], 0, 0, 0); __builtin_amdgcn_s_setprio(0); } while (0)
; #define PG8_WAIT_V(n) asm volatile("s_waitcnt vmcnt(" #n ")" ::: "memory")
; #define PG8_WAIT_L(n) asm volatile("s_waitcnt lgkmcnt(" #n ")" ::: "memory")
; #define PG8_BAR __builtin_amdgcn_s_barrier()
; #define PG8_SCHED __builtin_amdgcn_sched_barrier(0)
; template <class Epi>
; __device__ __forceinline__ void gemm_phase(PG8_LAS unsigned char* lds, const Gemm g, const StaticOrder& S, const Epi& E) {
;     ...
;       PG8_LDB(B1, 0, 1); PG8_STAGE(PG8_SB(0, 0), b2, voffB);
;       PG8_BAR; PG8_WAIT_L(0); PG8_MMA(0, 1, At, B1); PG8_BAR;
;       PG8_LDA(At, 0, 1); PG8_STAGE(PG8_SA(0, 0), a2, voffA);
;       PG8_BAR; PG8_WAIT_L(0); PG8_MMA(1, 0, At, B0); PG8_BAR; PG8_SCHED;
;       PG8_STAGE(PG8_SB(0, 1), b2 + hstep, voffB);
;       PG8_WAIT_V(6); PG8_BAR; PG8_MMA(1, 1, At, B1); PG8_BAR;
;       PG8_LDB(B0, 1, 0); PG8_SCHED; PG8_LDA(At, 1, 0); PG8_STAGE(PG8_SA(0, 1), a2 + hstep, voffA);
;       PG8_WAIT_L(8); PG8_BAR; PG8_WAIT_L(0); PG8_MMA(0, 0, At, B0); PG8_BAR; PG8_SCHED;
;       PG8_LDB(B1, 1, 1); PG8_STAGE(PG8_SB(1, 0), b3, voffB);
	s_add_i32 s66, 0, 0x14000
	s_add_i32 s51, s51, s28
	v_add_u32_e32 v0, s66, v166
	v_lshl_add_u64 v[178:179], s[42:43], 0, v[148:149]
	s_mov_b32 m0, s51
	ds_read_b128 v[228:231], v0
	ds_read_b128 v[232:235], v0 offset:1024
	ds_read_b128 v[236:239], v0 offset:2048
	ds_read_b128 v[240:243], v0 offset:3072
	global_load_lds_dwordx4 v[178:179], off
	v_lshl_add_u64 v[244:245], s[42:43], 0, v[150:151]
	s_add_i32 m0, s51, 0x2000
	s_nop 0
	global_load_lds_dwordx4 v[244:245], off
	s_barrier
	s_waitcnt lgkmcnt(0)
	s_waitcnt lgkmcnt(0)
	v_mfma_f32_16x16x32_bf16 v[118:121], v[228:231], v[196:199], v[118:121]
	v_mfma_f32_16x16x32_bf16 v[114:117], v[236:239], v[196:199], v[114:117]
	v_mfma_f32_16x16x32_bf16 v[102:105], v[228:231], v[204:207], v[102:105]
	v_mfma_f32_16x16x32_bf16 v[98:101], v[236:239], v[204:207], v[98:101]
	v_mfma_f32_16x16x32_bf16 v[86:89], v[228:231], v[212:215], v[86:89]
	v_mfma_f32_16x16x32_bf16 v[82:85], v[236:239], v[212:215], v[82:85]
	v_mfma_f32_16x16x32_bf16 v[70:73], v[228:231], v[220:223], v[70:73]
	v_mfma_f32_16x16x32_bf16 v[66:69], v[236:239], v[220:223], v[66:69]
	v_mfma_f32_16x16x32_bf16 v[118:121], v[232:235], v[200:203], v[118:121]
	v_mfma_f32_16x16x32_bf16 v[114:117], v[240:243], v[200:203], v[114:117]
	v_mfma_f32_16x16x32_bf16 v[102:105], v[232:235], v[208:211], v[102:105]
	v_mfma_f32_16x16x32_bf16 v[98:101], v[240:243], v[208:211], v[98:101]
	v_mfma_f32_16x16x32_bf16 v[86:89], v[232:235], v[216:219], v[86:89]
	v_mfma_f32_16x16x32_bf16 v[82:85], v[240:243], v[216:219], v[82:85]
	v_mfma_f32_16x16x32_bf16 v[70:73], v[232:235], v[224:227], v[70:73]
	v_mfma_f32_16x16x32_bf16 v[66:69], v[240:243], v[224:227], v[66:69]
	s_mov_b32 m0, s58
	v_lshl_add_u64 v[246:247], s[44:45], 0, v[148:149]
	s_barrier
	ds_read_b128 v[196:199], v167 offset:16384
	ds_read_b128 v[200:203], v167 offset:17408
	ds_read_b128 v[204:207], v167 offset:18432
	ds_read_b128 v[208:211], v167 offset:19456
	ds_read_b128 v[212:215], v167 offset:20480
	ds_read_b128 v[216:219], v167 offset:21504
	ds_read_b128 v[220:223], v167 offset:22528
	ds_read_b128 v[224:227], v167 offset:23552
	global_load_lds_dwordx4 v[246:247], off
	v_lshl_add_u64 v[248:249], s[44:45], 0, v[150:151]
	s_mov_b32 m0, s59
	s_nop 0
	global_load_lds_dwordx4 v[248:249], off
	s_barrier
	s_waitcnt lgkmcnt(0)
	s_waitcnt lgkmcnt(0)
	v_mfma_f32_16x16x32_bf16 v[62:65], v[158:161], v[196:199], v[62:65]
	v_mfma_f32_16x16x32_bf16 v[58:61], v[188:191], v[196:199], v[58:61]
	v_mfma_f32_16x16x32_bf16 v[46:49], v[158:161], v[204:207], v[46:49]
	v_mfma_f32_16x16x32_bf16 v[42:45], v[188:191], v[204:207], v[42:45]
	v_mfma_f32_16x16x32_bf16 v[30:33], v[158:161], v[212:215], v[30:33]
	v_mfma_f32_16x16x32_bf16 v[26:29], v[188:191], v[212:215], v[26:29]
	v_mfma_f32_16x16x32_bf16 v[14:17], v[158:161], v[220:223], v[14:17]
	v_mfma_f32_16x16x32_bf16 v[10:13], v[188:191], v[220:223], v[10:13]
	v_mfma_f32_16x16x32_bf16 v[62:65], v[162:165], v[200:203], v[62:65]
	v_mfma_f32_16x16x32_bf16 v[58:61], v[192:195], v[200:203], v[58:61]
	v_mfma_f32_16x16x32_bf16 v[46:49], v[162:165], v[208:211], v[46:49]
	v_mfma_f32_16x16x32_bf16 v[42:45], v[192:195], v[208:211], v[42:45]
	v_mfma_f32_16x16x32_bf16 v[30:33], v[162:165], v[216:219], v[30:33]
	v_mfma_f32_16x16x32_bf16 v[26:29], v[192:195], v[216:219], v[26:29]
	v_mfma_f32_16x16x32_bf16 v[14:17], v[162:165], v[224:227], v[14:17]
	v_mfma_f32_16x16x32_bf16 v[10:13], v[192:195], v[224:227], v[10:13]
	s_barrier
	s_add_u32 s56, s42, 0x80000
	s_addc_u32 s57, s43, 0
	s_add_i32 s51, s66, s28
	v_lshl_add_u64 v[158:159], s[56:57], 0, v[148:149]
	s_mov_b32 m0, s51
	s_nop 0
	global_load_lds_dwordx4 v[158:159], off
	v_lshl_add_u64 v[158:159], s[56:57], 0, v[150:151]
	s_add_i32 m0, s51, 0x2000
	s_nop 0
	global_load_lds_dwordx4 v[158:159], off
	s_waitcnt vmcnt(6)
	s_barrier
	v_mfma_f32_16x16x32_bf16 v[54:57], v[228:231], v[196:199], v[54:57]
	v_mfma_f32_16x16x32_bf16 v[50:53], v[236:239], v[196:199], v[50:53]
	v_mfma_f32_16x16x32_bf16 v[38:41], v[228:231], v[204:207], v[38:41]
	v_mfma_f32_16x16x32_bf16 v[34:37], v[236:239], v[204:207], v[34:37]
	v_mfma_f32_16x16x32_bf16 v[22:25], v[228:231], v[212:215], v[22:25]
	v_mfma_f32_16x16x32_bf16 v[18:21], v[236:239], v[212:215], v[18:21]
	v_mfma_f32_16x16x32_bf16 v[6:9], v[228:231], v[220:223], v[6:9]
	v_mfma_f32_16x16x32_bf16 v[2:5], v[236:239], v[220:223], v[2:5]
	v_mfma_f32_16x16x32_bf16 v[54:57], v[232:235], v[200:203], v[54:57]
	v_mfma_f32_16x16x32_bf16 v[50:53], v[240:243], v[200:203], v[50:53]
	v_mfma_f32_16x16x32_bf16 v[38:41], v[232:235], v[208:211], v[38:41]
	v_mfma_f32_16x16x32_bf16 v[34:37], v[240:243], v[208:211], v[34:37]
	v_mfma_f32_16x16x32_bf16 v[22:25], v[232:235], v[216:219], v[22:25]
	v_mfma_f32_16x16x32_bf16 v[18:21], v[240:243], v[216:219], v[18:21]
	v_mfma_f32_16x16x32_bf16 v[6:9], v[232:235], v[224:227], v[6:9]
	v_mfma_f32_16x16x32_bf16 v[2:5], v[240:243], v[224:227], v[2:5]
	s_add_i32 s51, 0, 0x18000
	v_add_u32_e32 v0, s51, v166
	s_barrier
	ds_read_b128 v[158:161], v0
	ds_read_b128 v[162:165], v0 offset:1024
	ds_read_b128 v[188:191], v0 offset:2048
	ds_read_b128 v[192:195], v0 offset:3072
	s_add_u32 s44, s44, 0x80000
	s_addc_u32 s45, s45, 0
	s_mov_b32 m0, s60
	v_lshl_add_u64 v[228:229], s[44:45], 0, v[148:149]
	ds_read_b128 v[196:199], v167 offset:32768
	ds_read_b128 v[200:203], v167 offset:33792
	ds_read_b128 v[204:207], v167 offset:34816
	ds_read_b128 v[208:211], v167 offset:35840
	ds_read_b128 v[212:215], v167 offset:36864
	ds_read_b128 v[216:219], v167 offset:37888
	ds_read_b128 v[220:223], v167 offset:38912
	ds_read_b128 v[224:227], v167 offset:39936
	global_load_lds_dwordx4 v[228:229], off
	v_lshl_add_u64 v[228:229], s[44:45], 0, v[150:151]
	s_mov_b32 m0, s61
	s_nop 0
	global_load_lds_dwordx4 v[228:229], off
	s_waitcnt lgkmcnt(8)
	s_barrier
; #define PG8_STAGE(bufoff, gbase, voff) do { _Pragma("unroll") for (int _i = 0; _i < 2; ++_i) \
;     __builtin_amdgcn_global_load_lds((const unsigned*)((const char*)(gbase) + (voff)[_i]), (PG8_LAS unsigned*)(lds + (bufoff) + ldsw + _i * 8192), 16, 0, 0); } while (0)
; #define PG8_LDA(dst, b, h) do { _Pragma("unroll") for (int m = 0; m < 4; ++m) _Pragma("unroll") for (int k = 0; k < 2; ++k) dst[m][k] = *(const PG8_LAS bf16x8*)(lds + PG8_SA(b, h) + aoff + m * 2048 + k * 1024); } while (0)
; #define PG8_LDB(dst, b, h) do { _Pragma("unroll") for (int n = 0; n < 2; ++n) _Pragma("unroll") for (int k = 0; k < 2; ++k) dst[n][k] = *(const PG8_LAS bf16x8*)(lds + PG8_SB(b, h) + boff + n * 2048 + k * 1024); } while (0)
; #define PG8_MMA(ai, bj, At, Bt) do { __builtin_amdgcn_s_setprio(1); _Pragma("unroll") for (int m = 0; m < 4; ++m) _Pragma("unroll") for (int n = 0; n < 2; ++n) _Pragma("unroll") for (int k = 0; k < 2; ++k) \
;     acc[ai][bj][m][n] = __builtin_amdgcn_mfma_f32_16x16x32_bf16(Bt[n][k], At[m][k], acc[ai][bj][m][n], 0, 0, 0); __builtin_amdgcn_s_setprio(0); } while (0)
; #define PG8_WAIT_V(n) asm volatile("s_waitcnt vmcnt(" #n ")" ::: "memory")
; #define PG8_WAIT_L(n) asm volatile("s_waitcnt lgkmcnt(" #n ")" ::: "memory")
; #define PG8_BAR __builtin_amdgcn_s_barrier()
; #define PG8_SCHED __builtin_amdgcn_sched_barrier(0)
; template <class Epi>
; __device__ __forceinline__ void gemm_phase(PG8_LAS unsigned char* lds, const Gemm g, const StaticOrder& S, const Epi& E) {
;     ...
;       PG8_WAIT_L(8); PG8_BAR; PG8_WAIT_L(0); PG8_MMA(0, 0, At, B0); PG8_BAR; PG8_SCHED;
;       PG8_LDB(B1, 1, 1); PG8_STAGE(PG8_SB(1, 0), b3, voffB);
;       PG8_BAR; PG8_WAIT_L(0); PG8_MMA(0, 1, At, B1); PG8_BAR;
;       PG8_LDA(At, 1, 1); PG8_STAGE(PG8_SA(1, 0), a3, voffA);
;       PG8_BAR; PG8_WAIT_L(0); PG8_MMA(1, 0, At, B0); PG8_BAR; PG8_SCHED;
;       PG8_STAGE(PG8_SB(1, 1), b3 + hstep, voffB);
;       PG8_WAIT_V(6); PG8_BAR; PG8_MMA(1, 1, At, B1); PG8_BAR;
	s_waitcnt lgkmcnt(0)
	s_waitcnt lgkmcnt(0)
	v_mfma_f32_16x16x32_bf16 v[126:129], v[158:161], v[196:199], v[126:129]
	v_mfma_f32_16x16x32_bf16 v[122:125], v[188:191], v[196:199], v[122:125]
	v_mfma_f32_16x16x32_bf16 v[110:113], v[158:161], v[204:207], v[110:113]
	v_mfma_f32_16x16x32_bf16 v[106:109], v[188:191], v[204:207], v[106:109]
	v_mfma_f32_16x16x32_bf16 v[94:97], v[158:161], v[212:215], v[94:97]
	v_mfma_f32_16x16x32_bf16 v[90:93], v[188:191], v[212:215], v[90:93]
	v_mfma_f32_16x16x32_bf16 v[78:81], v[158:161], v[220:223], v[78:81]
	v_mfma_f32_16x16x32_bf16 v[74:77], v[188:191], v[220:223], v[74:77]
	v_mfma_f32_16x16x32_bf16 v[126:129], v[162:165], v[200:203], v[126:129]
	v_mfma_f32_16x16x32_bf16 v[122:125], v[192:195], v[200:203], v[122:125]
	v_mfma_f32_16x16x32_bf16 v[110:113], v[162:165], v[208:211], v[110:113]
	v_mfma_f32_16x16x32_bf16 v[106:109], v[192:195], v[208:211], v[106:109]
	v_mfma_f32_16x16x32_bf16 v[94:97], v[162:165], v[216:219], v[94:97]
	v_mfma_f32_16x16x32_bf16 v[90:93], v[192:195], v[216:219], v[90:93]
	v_mfma_f32_16x16x32_bf16 v[78:81], v[162:165], v[224:227], v[78:81]
	v_mfma_f32_16x16x32_bf16 v[74:77], v[192:195], v[224:227], v[74:77]
	s_barrier
	s_add_i32 s44, 0, 0x1c000
	s_add_i32 s45, s51, s28
	v_add_u32_e32 v0, s44, v166
	v_lshl_add_u64 v[178:179], v[178:179], 0, s[4:5]
	s_mov_b32 m0, s45
	ds_read_b128 v[228:231], v0
	ds_read_b128 v[232:235], v0 offset:1024
	ds_read_b128 v[236:239], v0 offset:2048
	ds_read_b128 v[240:243], v0 offset:3072
	global_load_lds_dwordx4 v[178:179], off
	v_lshl_add_u64 v[178:179], v[244:245], 0, s[4:5]
	s_add_i32 m0, s45, 0x2000
	s_nop 0
	global_load_lds_dwordx4 v[178:179], off
	s_barrier
	s_waitcnt lgkmcnt(0)
	s_waitcnt lgkmcnt(0)
	v_mfma_f32_16x16x32_bf16 v[118:121], v[228:231], v[196:199], v[118:121]
	v_mfma_f32_16x16x32_bf16 v[114:117], v[236:239], v[196:199], v[114:117]
	v_mfma_f32_16x16x32_bf16 v[102:105], v[228:231], v[204:207], v[102:105]
	v_mfma_f32_16x16x32_bf16 v[98:101], v[236:239], v[204:207], v[98:101]
	v_mfma_f32_16x16x32_bf16 v[86:89], v[228:231], v[212:215], v[86:89]
	v_mfma_f32_16x16x32_bf16 v[82:85], v[236:239], v[212:215], v[82:85]
	v_mfma_f32_16x16x32_bf16 v[70:73], v[228:231], v[220:223], v[70:73]
	v_mfma_f32_16x16x32_bf16 v[66:69], v[236:239], v[220:223], v[66:69]
	v_mfma_f32_16x16x32_bf16 v[118:121], v[232:235], v[200:203], v[118:121]
	v_mfma_f32_16x16x32_bf16 v[114:117], v[240:243], v[200:203], v[114:117]
	v_mfma_f32_16x16x32_bf16 v[102:105], v[232:235], v[208:211], v[102:105]
	v_mfma_f32_16x16x32_bf16 v[98:101], v[240:243], v[208:211], v[98:101]
	v_mfma_f32_16x16x32_bf16 v[86:89], v[232:235], v[216:219], v[86:89]
	v_mfma_f32_16x16x32_bf16 v[82:85], v[240:243], v[216:219], v[82:85]
	v_mfma_f32_16x16x32_bf16 v[70:73], v[232:235], v[224:227], v[70:73]
	v_mfma_f32_16x16x32_bf16 v[66:69], v[240:243], v[224:227], v[66:69]
	s_mov_b32 m0, s63
	v_lshl_add_u64 v[178:179], v[246:247], 0, s[4:5]
	s_barrier
	ds_read_b128 v[196:199], v167 offset:49152
	ds_read_b128 v[200:203], v167 offset:50176
	ds_read_b128 v[204:207], v167 offset:51200
	ds_read_b128 v[208:211], v167 offset:52224
	ds_read_b128 v[212:215], v167 offset:53248
	ds_read_b128 v[216:219], v167 offset:54272
	ds_read_b128 v[220:223], v167 offset:55296
	ds_read_b128 v[224:227], v167 offset:56320
	global_load_lds_dwordx4 v[178:179], off
	v_lshl_add_u64 v[178:179], v[248:249], 0, s[4:5]
	s_mov_b32 m0, s64
	s_nop 0
	global_load_lds_dwordx4 v[178:179], off
	s_barrier
	s_waitcnt lgkmcnt(0)
	s_waitcnt lgkmcnt(0)
	v_mfma_f32_16x16x32_bf16 v[62:65], v[158:161], v[196:199], v[62:65]
	v_mfma_f32_16x16x32_bf16 v[58:61], v[188:191], v[196:199], v[58:61]
	v_mfma_f32_16x16x32_bf16 v[46:49], v[158:161], v[204:207], v[46:49]
	v_mfma_f32_16x16x32_bf16 v[42:45], v[188:191], v[204:207], v[42:45]
	v_mfma_f32_16x16x32_bf16 v[30:33], v[158:161], v[212:215], v[30:33]
	v_mfma_f32_16x16x32_bf16 v[26:29], v[188:191], v[212:215], v[26:29]
	v_mfma_f32_16x16x32_bf16 v[14:17], v[158:161], v[220:223], v[14:17]
	v_mfma_f32_16x16x32_bf16 v[10:13], v[188:191], v[220:223], v[10:13]
	v_mfma_f32_16x16x32_bf16 v[62:65], v[162:165], v[200:203], v[62:65]
	v_mfma_f32_16x16x32_bf16 v[58:61], v[192:195], v[200:203], v[58:61]
	v_mfma_f32_16x16x32_bf16 v[46:49], v[162:165], v[208:211], v[46:49]
	v_mfma_f32_16x16x32_bf16 v[42:45], v[192:195], v[208:211], v[42:45]
	v_mfma_f32_16x16x32_bf16 v[30:33], v[162:165], v[216:219], v[30:33]
	v_mfma_f32_16x16x32_bf16 v[26:29], v[192:195], v[216:219], v[26:29]
	v_mfma_f32_16x16x32_bf16 v[14:17], v[162:165], v[224:227], v[14:17]
	v_mfma_f32_16x16x32_bf16 v[10:13], v[192:195], v[224:227], v[10:13]
	s_barrier
	s_add_u32 s42, s42, 0x80080
	s_addc_u32 s43, s43, 0
	s_add_i32 s44, s44, s28
	v_lshl_add_u64 v[158:159], s[42:43], 0, v[148:149]
	s_mov_b32 m0, s44
	s_nop 0
	global_load_lds_dwordx4 v[158:159], off
	v_lshl_add_u64 v[158:159], s[42:43], 0, v[150:151]
	s_add_i32 m0, s44, 0x2000
	s_nop 0
	global_load_lds_dwordx4 v[158:159], off
	s_waitcnt vmcnt(6)
	s_barrier
;   __device__ __forceinline__ void operator()(const f32x4 (&acc)[2][2][4][2], const pg8::Unit& u, int wr, int wc, int fr, int fq) const {
; #pragma unroll
;     for (int ai = 0; ai < 2; ++ai)
; #pragma unroll
;       for (int m = 0; m < 4; ++m) { const int row = u.pm * 256 + ai * 128 + wr * 64 + m * 16 + fr;
; #pragma unroll
;         for (int bj = 0; bj < 2; ++bj)
; #pragma unroll
;           for (int n = 0; n < 2; ++n) f(row, u.pn * 256 + bj * 128 + wc * 32 + n * 16 + 4 * fq, acc[ai][bj][m][n]); }
	v_mfma_f32_16x16x32_bf16 v[54:57], v[228:231], v[196:199], v[54:57]
	v_mfma_f32_16x16x32_bf16 v[50:53], v[236:239], v[196:199], v[50:53]
	v_mfma_f32_16x16x32_bf16 v[38:41], v[228:231], v[204:207], v[38:41]
	v_mfma_f32_16x16x32_bf16 v[34:37], v[236:239], v[204:207], v[34:37]
	v_mfma_f32_16x16x32_bf16 v[22:25], v[228:231], v[212:215], v[22:25]
	v_mfma_f32_16x16x32_bf16 v[18:21], v[236:239], v[212:215], v[18:21]
	v_mfma_f32_16x16x32_bf16 v[6:9], v[228:231], v[220:223], v[6:9]
	v_mfma_f32_16x16x32_bf16 v[2:5], v[236:239], v[220:223], v[2:5]
	v_mfma_f32_16x16x32_bf16 v[54:57], v[232:235], v[200:203], v[54:57]
	v_mfma_f32_16x16x32_bf16 v[50:53], v[240:243], v[200:203], v[50:53]
	v_mfma_f32_16x16x32_bf16 v[38:41], v[232:235], v[208:211], v[38:41]
	v_mfma_f32_16x16x32_bf16 v[34:37], v[240:243], v[208:211], v[34:37]
	v_mfma_f32_16x16x32_bf16 v[22:25], v[232:235], v[216:219], v[22:25]
	v_mfma_f32_16x16x32_bf16 v[18:21], v[240:243], v[216:219], v[18:21]
	v_mfma_f32_16x16x32_bf16 v[6:9], v[232:235], v[224:227], v[6:9]
	v_mfma_f32_16x16x32_bf16 v[2:5], v[240:243], v[224:227], v[2:5]
	s_add_i32 s49, s49, 2
	s_add_u32 s10, s10, 0x100
	s_addc_u32 s11, s11, 0
	s_add_u32 s47, s47, 0x100
	s_addc_u32 s48, s48, 0
	s_cmp_gt_u32 s49, 29
	s_barrier
	s_cbranch_scc0 .LBB0_294
	s_cmp_eq_u32 s6, 16
	s_cbranch_scc1 .Lbf_orig_r7in
	s_movk_i32 s7, 0x2000
	v_bfe_u32 v178, v168, 4, 1
	v_mul_u32_u24_e32 v178, 24, v178
	v_lshl_add_u32 v178, v152, 1, v178
	v_mad_u32_u24 v178, v147, s7, v178
	s_lshl_b32 s56, s62, 1
	v_add_u32_e32 v178, s56, v178
	s_lshl_b32 s10, s8, 21
	s_lshl_b32 s56, s6, 9
	s_add_i32 s10, s10, s56
	s_add_u32 s10, s38, s10
	s_addc_u32 s11, s39, 0
	v_cvt_pk_bf16_f32 v125, v124, v125
	v_cvt_pk_bf16_f32 v124, v122, v123
	v_cvt_pk_bf16_f32 v122, v126, v127
	v_cvt_pk_bf16_f32 v123, v128, v129
	v_cvt_pk_bf16_f32 v117, v116, v117
	v_cvt_pk_bf16_f32 v116, v114, v115
	v_cvt_pk_bf16_f32 v114, v118, v119
	v_cvt_pk_bf16_f32 v115, v120, v121
	v_permlane16_swap_b32_e32 v122, v124
	v_permlane16_swap_b32_e32 v123, v125
	v_permlane16_swap_b32_e32 v114, v116
	v_permlane16_swap_b32_e32 v115, v117
	global_store_dwordx4 v178, v[122:125], s[10:11]
	global_store_dwordx4 v178, v[114:117], s[10:11] offset:256
	s_add_u32 s10, s10, 0x20000
	s_addc_u32 s11, s11, 0
	v_cvt_pk_bf16_f32 v109, v108, v109
	v_cvt_pk_bf16_f32 v108, v106, v107
	v_cvt_pk_bf16_f32 v106, v110, v111
	v_cvt_pk_bf16_f32 v107, v112, v113
	v_cvt_pk_bf16_f32 v101, v100, v101
	v_cvt_pk_bf16_f32 v100, v98, v99
	v_cvt_pk_bf16_f32 v98, v102, v103
	v_cvt_pk_bf16_f32 v99, v104, v105
	v_permlane16_swap_b32_e32 v106, v108
	v_permlane16_swap_b32_e32 v107, v109
	v_permlane16_swap_b32_e32 v98, v100
	v_permlane16_swap_b32_e32 v99, v101
	global_store_dwordx4 v178, v[106:109], s[10:11]
	global_store_dwordx4 v178, v[98:101], s[10:11] offset:256
	s_add_u32 s10, s10, 0x20000
	s_addc_u32 s11, s11, 0
	v_cvt_pk_bf16_f32 v93, v92, v93
	v_cvt_pk_bf16_f32 v92, v90, v91
	v_cvt_pk_bf16_f32 v90, v94, v95
	v_cvt_pk_bf16_f32 v91, v96, v97
	v_cvt_pk_bf16_f32 v85, v84, v85
	v_cvt_pk_bf16_f32 v84, v82, v83
	v_cvt_pk_bf16_f32 v82, v86, v87
	v_cvt_pk_bf16_f32 v83, v88, v89
	v_permlane16_swap_b32_e32 v90, v92
	v_permlane16_swap_b32_e32 v91, v93
	v_permlane16_swap_b32_e32 v82, v84
	v_permlane16_swap_b32_e32 v83, v85
	global_store_dwordx4 v178, v[90:93], s[10:11]
	global_store_dwordx4 v178, v[82:85], s[10:11] offset:256
	s_add_u32 s10, s10, 0x20000
	s_addc_u32 s11, s11, 0
	v_cvt_pk_bf16_f32 v77, v76, v77
	v_cvt_pk_bf16_f32 v76, v74, v75
	v_cvt_pk_bf16_f32 v74, v78, v79
	v_cvt_pk_bf16_f32 v75, v80, v81
	v_cvt_pk_bf16_f32 v69, v68, v69
	v_cvt_pk_bf16_f32 v68, v66, v67
	v_cvt_pk_bf16_f32 v66, v70, v71
	v_cvt_pk_bf16_f32 v67, v72, v73
	v_permlane16_swap_b32_e32 v74, v76
	v_permlane16_swap_b32_e32 v75, v77
	v_permlane16_swap_b32_e32 v66, v68
	v_permlane16_swap_b32_e32 v67, v69
	global_store_dwordx4 v178, v[74:77], s[10:11]
	global_store_dwordx4 v178, v[66:69], s[10:11] offset:256
	s_add_u32 s10, s10, 0xa0000
	s_addc_u32 s11, s11, 0
	v_cvt_pk_bf16_f32 v61, v60, v61
	v_cvt_pk_bf16_f32 v60, v58, v59
	v_cvt_pk_bf16_f32 v58, v62, v63
	v_cvt_pk_bf16_f32 v59, v64, v65
	v_cvt_pk_bf16_f32 v53, v52, v53
	v_cvt_pk_bf16_f32 v52, v50, v51
	v_cvt_pk_bf16_f32 v50, v54, v55
	v_cvt_pk_bf16_f32 v51, v56, v57
	v_permlane16_swap_b32_e32 v58, v60
	v_permlane16_swap_b32_e32 v59, v61
	v_permlane16_swap_b32_e32 v50, v52
	v_permlane16_swap_b32_e32 v51, v53
	global_store_dwordx4 v178, v[58:61], s[10:11]
	global_store_dwordx4 v178, v[50:53], s[10:11] offset:256
	s_add_u32 s10, s10, 0x20000
	s_addc_u32 s11, s11, 0
	v_cvt_pk_bf16_f32 v45, v44, v45
	v_cvt_pk_bf16_f32 v44, v42, v43
	v_cvt_pk_bf16_f32 v42, v46, v47
	v_cvt_pk_bf16_f32 v43, v48, v49
	v_cvt_pk_bf16_f32 v37, v36, v37
	v_cvt_pk_bf16_f32 v36, v34, v35
	v_cvt_pk_bf16_f32 v34, v38, v39
	v_cvt_pk_bf16_f32 v35, v40, v41
	v_permlane16_swap_b32_e32 v42, v44
	v_permlane16_swap_b32_e32 v43, v45
	v_permlane16_swap_b32_e32 v34, v36
	v_permlane16_swap_b32_e32 v35, v37
	global_store_dwordx4 v178, v[42:45], s[10:11]
	global_store_dwordx4 v178, v[34:37], s[10:11] offset:256
	s_add_u32 s10, s10, 0x20000
	s_addc_u32 s11, s11, 0
	v_cvt_pk_bf16_f32 v29, v28, v29
	v_cvt_pk_bf16_f32 v28, v26, v27
	v_cvt_pk_bf16_f32 v26, v30, v31
	v_cvt_pk_bf16_f32 v27, v32, v33
	v_cvt_pk_bf16_f32 v21, v20, v21
	v_cvt_pk_bf16_f32 v20, v18, v19
	v_cvt_pk_bf16_f32 v18, v22, v23
	v_cvt_pk_bf16_f32 v19, v24, v25
	v_permlane16_swap_b32_e32 v26, v28
	v_permlane16_swap_b32_e32 v27, v29
	v_permlane16_swap_b32_e32 v18, v20
	v_permlane16_swap_b32_e32 v19, v21
	global_store_dwordx4 v178, v[26:29], s[10:11]
	global_store_dwordx4 v178, v[18:21], s[10:11] offset:256
	s_add_u32 s10, s10, 0x20000
	s_addc_u32 s11, s11, 0
	v_cvt_pk_bf16_f32 v13, v12, v13
	v_cvt_pk_bf16_f32 v12, v10, v11
	v_cvt_pk_bf16_f32 v10, v14, v15
	v_cvt_pk_bf16_f32 v11, v16, v17
	v_cvt_pk_bf16_f32 v5, v4, v5
	v_cvt_pk_bf16_f32 v4, v2, v3
	v_cvt_pk_bf16_f32 v2, v6, v7
	v_cvt_pk_bf16_f32 v3, v8, v9
	v_permlane16_swap_b32_e32 v10, v12
	v_permlane16_swap_b32_e32 v11, v13
	v_permlane16_swap_b32_e32 v2, v4
	v_permlane16_swap_b32_e32 v3, v5
	global_store_dwordx4 v178, v[10:13], s[10:11]
	global_store_dwordx4 v178, v[2:5], s[10:11] offset:256
	s_branch .LBB0_286

; #define PG8_WAIT_V(n) asm volatile("s_waitcnt vmcnt(" #n ")" ::: "memory")
; #define PG8_WAIT_L(n) asm volatile("s_waitcnt lgkmcnt(" #n ")" ::: "memory")
; #define PG8_BAR __builtin_amdgcn_s_barrier()
; template <class Epi>
; __device__ __forceinline__ void gemm_phase(PG8_LAS unsigned char* lds, const Gemm g, const StaticOrder& S, const Epi& E) {
;     ...
;   for (;;) {
;     const bool has_next = S.next(ui + 1, nxt);
;     const char* nA = has_next ? (const char*)g.A + (size_t)nxt.pm * tstep : cA; const char* nB = has_next ? (const char*)g.Bt + (size_t)nxt.pn * tstep : cB;
;     for (int t = 0; t < nt; t += 2) {
;       const bool last = (t == nt - 2);
;       const char* a1 = cA + (size_t)(t + 1) * kstep;
;       const char* a2 = last ? nA : cA + (size_t)(t + 2) * kstep; const char* b2 = last ? nB : cB + (size_t)(t + 2) * kstep;
;       const char* a3 = a2 + kstep; const char* b3 = b2 + kstep;
;       PG8_LDB(B0, 0, 0); PG8_SCHED; PG8_LDA(At, 0, 0); PG8_STAGE(PG8_SA(1, 1), a1 + hstep, voffA);
;       PG8_WAIT_L(8); PG8_BAR; PG8_WAIT_L(0); PG8_MMA(0, 0, At, B0); PG8_BAR; PG8_SCHED;
;       PG8_LDB(B1, 0, 1); PG8_STAGE(PG8_SB(0, 0), b2, voffB);
;       PG8_BAR; PG8_WAIT_L(0); PG8_MMA(0, 1, At, B1); PG8_BAR;
;       PG8_LDA(At, 0, 1); PG8_STAGE(PG8_SA(0, 0), a2, voffA);
;       PG8_BAR; PG8_WAIT_L(0); PG8_MMA(1, 0, At, B0); PG8_BAR; PG8_SCHED;
;       PG8_STAGE(PG8_SB(0, 1), b2 + hstep, voffB);
;       PG8_WAIT_V(6); PG8_BAR; PG8_MMA(1, 1, At, B1); PG8_BAR;
;       PG8_LDB(B0, 1, 0); PG8_SCHED; PG8_LDA(At, 1, 0); PG8_STAGE(PG8_SA(0, 1), a2 + hstep, voffA);
;       PG8_WAIT_L(8); PG8_BAR; PG8_WAIT_L(0); PG8_MMA(0, 0, At, B0); PG8_BAR; PG8_SCHED;
;       PG8_LDB(B1, 1, 1); PG8_STAGE(PG8_SB(1, 0), b3, voffB);
;       PG8_BAR; PG8_WAIT_L(0); PG8_MMA(0, 1, At, B1); PG8_BAR;
;       PG8_LDA(At, 1, 1); PG8_STAGE(PG8_SA(1, 0), a3, voffA);
;       PG8_BAR; PG8_WAIT_L(0); PG8_MMA(1, 0, At, B0); PG8_BAR; PG8_SCHED;
;       PG8_STAGE(PG8_SB(1, 1), b3 + hstep, voffB);
;       PG8_WAIT_V(6); PG8_BAR; PG8_MMA(1, 1, At, B1); PG8_BAR;
;     }
;     E(acc, cur, wr, wc, fr, fq);
;     if (!has_next) break;
; #pragma unroll
;     for (int a = 0; a < 2; ++a)
; #pragma unroll
;       for (int b = 0; b < 2; ++b)
; #pragma unroll
;         for (int m = 0; m < 4; ++m)
; #pragma unroll
;           for (int n = 0; n < 2; ++n) acc[a][b][m][n] = (f32x4){0.f, 0.f, 0.f, 0.f};
.LBB0_1045:
	s_ashr_i32 s11, s10, 31
	v_cmp_lt_i64_e32 vcc, s[30:31], v[132:133]
	s_lshl_b64 s[30:31], s[10:11], 20
	s_add_u32 s30, s90, s30
	s_addc_u32 s31, s91, s31
	s_and_b64 s[44:45], vcc, exec
	s_cselect_b32 s11, s31, s49
	s_cselect_b32 s43, s30, s48
	s_ashr_i32 s9, s8, 31
	s_lshl_b64 s[44:45], s[8:9], 20
	v_readlane_b32 s9, v251, 33
	s_add_u32 s44, s9, s44
	v_readlane_b32 s9, v251, 34
	s_addc_u32 s45, s9, s45
	s_and_b64 s[52:53], vcc, exec
	s_cselect_b32 s9, s45, s51
	s_cselect_b32 s47, s44, s50
	s_add_u32 s63, s50, 0x100
	v_mov_b32_e32 v2, 0
	s_addc_u32 s64, s51, 0
	s_mov_b32 s65, -2
	v_mov_b32_e32 v3, v2
	v_mov_b32_e32 v4, v2
	v_mov_b32_e32 v5, v2
	v_mov_b32_e32 v6, v2
	v_mov_b32_e32 v7, v2
	v_mov_b32_e32 v8, v2
	v_mov_b32_e32 v9, v2
	v_mov_b32_e32 v18, v2
	v_mov_b32_e32 v19, v2
	v_mov_b32_e32 v20, v2
	v_mov_b32_e32 v21, v2
	v_mov_b32_e32 v22, v2
	v_mov_b32_e32 v23, v2
	v_mov_b32_e32 v24, v2
	v_mov_b32_e32 v25, v2
	v_mov_b32_e32 v34, v2
	v_mov_b32_e32 v35, v2
	v_mov_b32_e32 v36, v2
	v_mov_b32_e32 v37, v2
	v_mov_b32_e32 v38, v2
	v_mov_b32_e32 v39, v2
	v_mov_b32_e32 v40, v2
	v_mov_b32_e32 v41, v2
	v_mov_b32_e32 v50, v2
	v_mov_b32_e32 v51, v2
	v_mov_b32_e32 v52, v2
	v_mov_b32_e32 v53, v2
	v_mov_b32_e32 v54, v2
	v_mov_b32_e32 v55, v2
	v_mov_b32_e32 v56, v2
	v_mov_b32_e32 v57, v2
	v_mov_b32_e32 v10, v2
	v_mov_b32_e32 v11, v2
	v_mov_b32_e32 v12, v2
	v_mov_b32_e32 v13, v2
	v_mov_b32_e32 v14, v2
	v_mov_b32_e32 v15, v2
	v_mov_b32_e32 v16, v2
	v_mov_b32_e32 v17, v2
	v_mov_b32_e32 v26, v2
	v_mov_b32_e32 v27, v2
	v_mov_b32_e32 v28, v2
	v_mov_b32_e32 v29, v2
	v_mov_b32_e32 v30, v2
	v_mov_b32_e32 v31, v2
	v_mov_b32_e32 v32, v2
	v_mov_b32_e32 v33, v2
	v_mov_b32_e32 v42, v2
	v_mov_b32_e32 v43, v2
	v_mov_b32_e32 v44, v2
	v_mov_b32_e32 v45, v2
	v_mov_b32_e32 v46, v2
	v_mov_b32_e32 v47, v2
	v_mov_b32_e32 v48, v2
	v_mov_b32_e32 v49, v2
	v_mov_b32_e32 v58, v2
	v_mov_b32_e32 v59, v2
	v_mov_b32_e32 v60, v2
	v_mov_b32_e32 v61, v2
	v_mov_b32_e32 v62, v2
	v_mov_b32_e32 v63, v2
	v_mov_b32_e32 v64, v2
	v_mov_b32_e32 v65, v2
	v_mov_b32_e32 v66, v2
	v_mov_b32_e32 v67, v2
	v_mov_b32_e32 v68, v2
	v_mov_b32_e32 v69, v2
	v_mov_b32_e32 v70, v2
	v_mov_b32_e32 v71, v2
	v_mov_b32_e32 v72, v2
	v_mov_b32_e32 v73, v2
	v_mov_b32_e32 v82, v2
	v_mov_b32_e32 v83, v2
	v_mov_b32_e32 v84, v2
	v_mov_b32_e32 v85, v2
	v_mov_b32_e32 v86, v2
	v_mov_b32_e32 v87, v2
	v_mov_b32_e32 v88, v2
	v_mov_b32_e32 v89, v2
	v_mov_b32_e32 v98, v2
	v_mov_b32_e32 v99, v2
	v_mov_b32_e32 v100, v2
	v_mov_b32_e32 v101, v2
	v_mov_b32_e32 v102, v2
	v_mov_b32_e32 v103, v2
	v_mov_b32_e32 v104, v2
	v_mov_b32_e32 v105, v2
	v_mov_b32_e32 v114, v2
	v_mov_b32_e32 v115, v2
	v_mov_b32_e32 v116, v2
	v_mov_b32_e32 v117, v2
	v_mov_b32_e32 v118, v2
	v_mov_b32_e32 v119, v2
	v_mov_b32_e32 v120, v2
	v_mov_b32_e32 v121, v2
	v_mov_b32_e32 v74, v2
	v_mov_b32_e32 v75, v2
	v_mov_b32_e32 v76, v2
	v_mov_b32_e32 v77, v2
	v_mov_b32_e32 v78, v2
	v_mov_b32_e32 v79, v2
	v_mov_b32_e32 v80, v2
	v_mov_b32_e32 v81, v2
	v_mov_b32_e32 v90, v2
	v_mov_b32_e32 v91, v2
	v_mov_b32_e32 v92, v2
	v_mov_b32_e32 v93, v2
	v_mov_b32_e32 v94, v2
	v_mov_b32_e32 v95, v2
	v_mov_b32_e32 v96, v2
	v_mov_b32_e32 v97, v2
	v_mov_b32_e32 v106, v2
	v_mov_b32_e32 v107, v2
	v_mov_b32_e32 v108, v2
	v_mov_b32_e32 v109, v2
	v_mov_b32_e32 v110, v2
	v_mov_b32_e32 v111, v2
	v_mov_b32_e32 v112, v2
	v_mov_b32_e32 v113, v2
	v_mov_b32_e32 v122, v2
	v_mov_b32_e32 v123, v2
	v_mov_b32_e32 v124, v2
	v_mov_b32_e32 v125, v2
	v_mov_b32_e32 v126, v2
	v_mov_b32_e32 v127, v2
	v_mov_b32_e32 v128, v2
	v_mov_b32_e32 v129, v2
	v_readfirstlane_b32 s100, v168
	s_lshr_b32 s100, s100, 6
	s_cmp_ge_u32 s100, 4
	s_cbranch_scc0 .Lgp_2
	s_setprio 1
.Lgp_2:
.LBB0_1046:
	s_add_u32 s50, s48, 0x100
	s_addc_u32 s51, s49, 0
	s_add_i32 s66, 0, 0x10000
	v_add_u32_e32 v158, s66, v160
	ds_read_b128 v[154:157], v158
	ds_read_b128 v[164:167], v158 offset:1024
	ds_read_b128 v[188:191], v158 offset:2048
	ds_read_b128 v[192:195], v158 offset:3072
	s_cmp_eq_u32 s65, 28
	s_cselect_b32 s55, s11, s51
	s_cselect_b32 s54, s43, s50
	s_cselect_b32 s53, s9, s64
	s_cselect_b32 s52, s47, s63
	v_lshl_add_u64 v[158:159], s[48:49], 0, v[150:151]
	s_add_i32 m0, s56, 0xc000
	ds_read_b128 v[196:199], v162
	ds_read_b128 v[200:203], v162 offset:1024
	ds_read_b128 v[204:207], v162 offset:2048
	ds_read_b128 v[208:211], v162 offset:3072
	ds_read_b128 v[212:215], v162 offset:4096
	ds_read_b128 v[216:219], v162 offset:5120
	ds_read_b128 v[220:223], v162 offset:6144
	ds_read_b128 v[224:227], v162 offset:7168
	global_load_lds_dwordx4 v[158:159], off
	v_lshl_add_u64 v[158:159], s[48:49], 0, v[152:153]
	s_add_i32 m0, s56, 0xe000
	s_nop 0
	global_load_lds_dwordx4 v[158:159], off
	s_waitcnt lgkmcnt(8)
	s_barrier
	s_waitcnt lgkmcnt(0)
	s_waitcnt lgkmcnt(0)
	v_mfma_f32_16x16x32_bf16 v[126:129], v[154:157], v[196:199], v[126:129]
	v_mfma_f32_16x16x32_bf16 v[122:125], v[188:191], v[196:199], v[122:125]
	v_mfma_f32_16x16x32_bf16 v[110:113], v[154:157], v[204:207], v[110:113]
	v_mfma_f32_16x16x32_bf16 v[106:109], v[188:191], v[204:207], v[106:109]
	v_mfma_f32_16x16x32_bf16 v[94:97], v[154:157], v[212:215], v[94:97]
	v_mfma_f32_16x16x32_bf16 v[90:93], v[188:191], v[212:215], v[90:93]
	v_mfma_f32_16x16x32_bf16 v[78:81], v[154:157], v[220:223], v[78:81]
	v_mfma_f32_16x16x32_bf16 v[74:77], v[188:191], v[220:223], v[74:77]
	v_mfma_f32_16x16x32_bf16 v[126:129], v[164:167], v[200:203], v[126:129]
	v_mfma_f32_16x16x32_bf16 v[122:125], v[192:195], v[200:203], v[122:125]
	v_mfma_f32_16x16x32_bf16 v[110:113], v[164:167], v[208:211], v[110:113]
	v_mfma_f32_16x16x32_bf16 v[106:109], v[192:195], v[208:211], v[106:109]
	v_mfma_f32_16x16x32_bf16 v[94:97], v[164:167], v[216:219], v[94:97]
	v_mfma_f32_16x16x32_bf16 v[90:93], v[192:195], v[216:219], v[90:93]
	v_mfma_f32_16x16x32_bf16 v[78:81], v[164:167], v[224:227], v[78:81]
	v_mfma_f32_16x16x32_bf16 v[74:77], v[192:195], v[224:227], v[74:77]
	s_barrier
; #define PG8_STAGE(bufoff, gbase, voff) do { _Pragma("unroll") for (int _i = 0; _i < 2; ++_i) \
;     __builtin_amdgcn_global_load_lds((const unsigned*)((const char*)(gbase) + (voff)[_i]), (PG8_LAS unsigned*)(lds + (bufoff) + ldsw + _i * 8192), 16, 0, 0); } while (0)
; #define PG8_LDA(dst, b, h) do { _Pragma("unroll") for (int m = 0; m < 4; ++m) _Pragma("unroll") for (int k = 0; k < 2; ++k) dst[m][k] = *(const PG8_LAS bf16x8*)(lds + PG8_SA(b, h) + aoff + m * 2048 + k * 1024); } while (0)
; #define PG8_LDB(dst, b, h) do { _Pragma("unroll") for (int n = 0; n < 2; ++n) _Pragma("unroll") for (int k = 0; k < 2; ++k) dst[n][k] = *(const PG8_LAS bf16x8*)(lds + PG8_SB(b, h) + boff + n * 2048 + k * 1024); } while (0)
; #define PG8_MMA(ai, bj, At, Bt) do { __builtin_amdgcn_s_setprio(1); _Pragma("unroll") for (int m = 0; m < 4; ++m) _Pragma("unroll") for (int n = 0; n < 2; ++n) _Pragma("unroll") for (int k = 0; k < 2; ++k) \
;     acc[ai][bj][m][n] = __builtin_amdgcn_mfma_f32_16x16x32_bf16(Bt[n][k], At[m][k], acc[ai][bj][m][n], 0, 0, 0); __builtin_amdgcn_s_setprio(0); } while (0)
; #define PG8_WAIT_V(n) asm volatile("s_waitcnt vmcnt(" #n ")" ::: "memory")
; #define PG8_WAIT_L(n) asm volatile("s_waitcnt lgkmcnt(" #n ")" ::: "memory")
; #define PG8_BAR __builtin_amdgcn_s_barrier()
; #define PG8_SCHED __builtin_amdgcn_sched_barrier(0)
; template <class Epi>
; __device__ __forceinline__ void gemm_phase(PG8_LAS unsigned char* lds, const Gemm g, const StaticOrder& S, const Epi& E) {
;     ...
;       PG8_LDB(B1, 0, 1); PG8_STAGE(PG8_SB(0, 0), b2, voffB);
;       PG8_BAR; PG8_WAIT_L(0); PG8_MMA(0, 1, At, B1); PG8_BAR;
;       PG8_LDA(At, 0, 1); PG8_STAGE(PG8_SA(0, 0), a2, voffA);
;       PG8_BAR; PG8_WAIT_L(0); PG8_MMA(1, 0, At, B0); PG8_BAR; PG8_SCHED;
;       PG8_STAGE(PG8_SB(0, 1), b2 + hstep, voffB);
;       PG8_WAIT_V(6); PG8_BAR; PG8_MMA(1, 1, At, B1); PG8_BAR;
;       PG8_LDB(B0, 1, 0); PG8_SCHED; PG8_LDA(At, 1, 0); PG8_STAGE(PG8_SA(0, 1), a2 + hstep, voffA);
;       PG8_WAIT_L(8); PG8_BAR; PG8_WAIT_L(0); PG8_MMA(0, 0, At, B0); PG8_BAR; PG8_SCHED;
;       PG8_LDB(B1, 1, 1); PG8_STAGE(PG8_SB(1, 0), b3, voffB);
	s_add_i32 s67, 0, 0x14000
	v_add_u32_e32 v158, s67, v160
	s_add_i32 s48, s66, s28
	ds_read_b128 v[228:231], v158
	ds_read_b128 v[232:235], v158 offset:1024
	ds_read_b128 v[236:239], v158 offset:2048
	ds_read_b128 v[240:243], v158 offset:3072
	v_lshl_add_u64 v[158:159], s[52:53], 0, v[0:1]
	s_mov_b32 m0, s48
	v_lshl_add_u64 v[178:179], s[52:53], 0, v[148:149]
	global_load_lds_dwordx4 v[158:159], off
	s_add_i32 m0, s48, 0x2000
	s_nop 0
	global_load_lds_dwordx4 v[178:179], off
	s_barrier
	s_waitcnt lgkmcnt(0)
	s_waitcnt lgkmcnt(0)
	v_mfma_f32_16x16x32_bf16 v[118:121], v[228:231], v[196:199], v[118:121]
	v_mfma_f32_16x16x32_bf16 v[114:117], v[236:239], v[196:199], v[114:117]
	v_mfma_f32_16x16x32_bf16 v[102:105], v[228:231], v[204:207], v[102:105]
	v_mfma_f32_16x16x32_bf16 v[98:101], v[236:239], v[204:207], v[98:101]
	v_mfma_f32_16x16x32_bf16 v[86:89], v[228:231], v[212:215], v[86:89]
	v_mfma_f32_16x16x32_bf16 v[82:85], v[236:239], v[212:215], v[82:85]
	v_mfma_f32_16x16x32_bf16 v[70:73], v[228:231], v[220:223], v[70:73]
	v_mfma_f32_16x16x32_bf16 v[66:69], v[236:239], v[220:223], v[66:69]
	v_mfma_f32_16x16x32_bf16 v[118:121], v[232:235], v[200:203], v[118:121]
	v_mfma_f32_16x16x32_bf16 v[114:117], v[240:243], v[200:203], v[114:117]
	v_mfma_f32_16x16x32_bf16 v[102:105], v[232:235], v[208:211], v[102:105]
	v_mfma_f32_16x16x32_bf16 v[98:101], v[240:243], v[208:211], v[98:101]
	v_mfma_f32_16x16x32_bf16 v[86:89], v[232:235], v[216:219], v[86:89]
	v_mfma_f32_16x16x32_bf16 v[82:85], v[240:243], v[216:219], v[82:85]
	v_mfma_f32_16x16x32_bf16 v[70:73], v[232:235], v[224:227], v[70:73]
	v_mfma_f32_16x16x32_bf16 v[66:69], v[240:243], v[224:227], v[66:69]
	s_mov_b32 m0, s56
	v_lshl_add_u64 v[244:245], s[54:55], 0, v[0:1]
	s_barrier
	ds_read_b128 v[196:199], v162 offset:16384
	ds_read_b128 v[200:203], v162 offset:17408
	ds_read_b128 v[204:207], v162 offset:18432
	ds_read_b128 v[208:211], v162 offset:19456
	ds_read_b128 v[212:215], v162 offset:20480
	ds_read_b128 v[216:219], v162 offset:21504
	ds_read_b128 v[220:223], v162 offset:22528
	ds_read_b128 v[224:227], v162 offset:23552
	global_load_lds_dwordx4 v[244:245], off
	v_lshl_add_u64 v[246:247], s[54:55], 0, v[148:149]
	s_mov_b32 m0, s57
	s_nop 0
	global_load_lds_dwordx4 v[246:247], off
	s_barrier
	s_waitcnt lgkmcnt(0)
	s_waitcnt lgkmcnt(0)
	v_mfma_f32_16x16x32_bf16 v[62:65], v[154:157], v[196:199], v[62:65]
	v_mfma_f32_16x16x32_bf16 v[58:61], v[188:191], v[196:199], v[58:61]
	v_mfma_f32_16x16x32_bf16 v[46:49], v[154:157], v[204:207], v[46:49]
	v_mfma_f32_16x16x32_bf16 v[42:45], v[188:191], v[204:207], v[42:45]
	v_mfma_f32_16x16x32_bf16 v[30:33], v[154:157], v[212:215], v[30:33]
	v_mfma_f32_16x16x32_bf16 v[26:29], v[188:191], v[212:215], v[26:29]
	v_mfma_f32_16x16x32_bf16 v[14:17], v[154:157], v[220:223], v[14:17]
	v_mfma_f32_16x16x32_bf16 v[10:13], v[188:191], v[220:223], v[10:13]
	v_mfma_f32_16x16x32_bf16 v[62:65], v[164:167], v[200:203], v[62:65]
	v_mfma_f32_16x16x32_bf16 v[58:61], v[192:195], v[200:203], v[58:61]
	v_mfma_f32_16x16x32_bf16 v[46:49], v[164:167], v[208:211], v[46:49]
	v_mfma_f32_16x16x32_bf16 v[42:45], v[192:195], v[208:211], v[42:45]
	v_mfma_f32_16x16x32_bf16 v[30:33], v[164:167], v[216:219], v[30:33]
	v_mfma_f32_16x16x32_bf16 v[26:29], v[192:195], v[216:219], v[26:29]
	v_mfma_f32_16x16x32_bf16 v[14:17], v[164:167], v[224:227], v[14:17]
	v_mfma_f32_16x16x32_bf16 v[10:13], v[192:195], v[224:227], v[10:13]
	s_barrier
	s_add_u32 s48, s52, 0x80000
	s_addc_u32 s49, s53, 0
	s_add_i32 s66, s67, s28
	v_lshl_add_u64 v[154:155], s[48:49], 0, v[0:1]
	s_mov_b32 m0, s66
	s_nop 0
	global_load_lds_dwordx4 v[154:155], off
	v_lshl_add_u64 v[154:155], s[48:49], 0, v[148:149]
	s_add_i32 m0, s66, 0x2000
	s_nop 0
	global_load_lds_dwordx4 v[154:155], off
	s_waitcnt vmcnt(6)
	s_barrier
	v_mfma_f32_16x16x32_bf16 v[54:57], v[228:231], v[196:199], v[54:57]
	v_mfma_f32_16x16x32_bf16 v[50:53], v[236:239], v[196:199], v[50:53]
	v_mfma_f32_16x16x32_bf16 v[38:41], v[228:231], v[204:207], v[38:41]
	v_mfma_f32_16x16x32_bf16 v[34:37], v[236:239], v[204:207], v[34:37]
	v_mfma_f32_16x16x32_bf16 v[22:25], v[228:231], v[212:215], v[22:25]
	v_mfma_f32_16x16x32_bf16 v[18:21], v[236:239], v[212:215], v[18:21]
	v_mfma_f32_16x16x32_bf16 v[6:9], v[228:231], v[220:223], v[6:9]
	v_mfma_f32_16x16x32_bf16 v[2:5], v[236:239], v[220:223], v[2:5]
	v_mfma_f32_16x16x32_bf16 v[54:57], v[232:235], v[200:203], v[54:57]
	v_mfma_f32_16x16x32_bf16 v[50:53], v[240:243], v[200:203], v[50:53]
	v_mfma_f32_16x16x32_bf16 v[38:41], v[232:235], v[208:211], v[38:41]
	v_mfma_f32_16x16x32_bf16 v[34:37], v[240:243], v[208:211], v[34:37]
	v_mfma_f32_16x16x32_bf16 v[22:25], v[232:235], v[216:219], v[22:25]
	v_mfma_f32_16x16x32_bf16 v[18:21], v[240:243], v[216:219], v[18:21]
	v_mfma_f32_16x16x32_bf16 v[6:9], v[232:235], v[224:227], v[6:9]
	v_mfma_f32_16x16x32_bf16 v[2:5], v[240:243], v[224:227], v[2:5]
	s_add_i32 s66, 0, 0x18000
	v_add_u32_e32 v163, s66, v160
	s_barrier
	ds_read_b128 v[154:157], v163
	ds_read_b128 v[164:167], v163 offset:1024
	ds_read_b128 v[188:191], v163 offset:2048
	ds_read_b128 v[192:195], v163 offset:3072
	s_add_u32 s48, s54, 0x80000
	s_addc_u32 s49, s55, 0
	s_mov_b32 m0, s58
	v_lshl_add_u64 v[228:229], s[48:49], 0, v[0:1]
	ds_read_b128 v[196:199], v162 offset:32768
	ds_read_b128 v[200:203], v162 offset:33792
	ds_read_b128 v[204:207], v162 offset:34816
	ds_read_b128 v[208:211], v162 offset:35840
	ds_read_b128 v[212:215], v162 offset:36864
	ds_read_b128 v[216:219], v162 offset:37888
	ds_read_b128 v[220:223], v162 offset:38912
	ds_read_b128 v[224:227], v162 offset:39936
	global_load_lds_dwordx4 v[228:229], off
	v_lshl_add_u64 v[228:229], s[48:49], 0, v[148:149]
	s_mov_b32 m0, s59
	s_nop 0
	global_load_lds_dwordx4 v[228:229], off
	s_waitcnt lgkmcnt(8)
	s_barrier
; #define PG8_STAGE(bufoff, gbase, voff) do { _Pragma("unroll") for (int _i = 0; _i < 2; ++_i) \
;     __builtin_amdgcn_global_load_lds((const unsigned*)((const char*)(gbase) + (voff)[_i]), (PG8_LAS unsigned*)(lds + (bufoff) + ldsw + _i * 8192), 16, 0, 0); } while (0)
; #define PG8_LDA(dst, b, h) do { _Pragma("unroll") for (int m = 0; m < 4; ++m) _Pragma("unroll") for (int k = 0; k < 2; ++k) dst[m][k] = *(const PG8_LAS bf16x8*)(lds + PG8_SA(b, h) + aoff + m * 2048 + k * 1024); } while (0)
; #define PG8_MMA(ai, bj, At, Bt) do { __builtin_amdgcn_s_setprio(1); _Pragma("unroll") for (int m = 0; m < 4; ++m) _Pragma("unroll") for (int n = 0; n < 2; ++n) _Pragma("unroll") for (int k = 0; k < 2; ++k) \
;     acc[ai][bj][m][n] = __builtin_amdgcn_mfma_f32_16x16x32_bf16(Bt[n][k], At[m][k], acc[ai][bj][m][n], 0, 0, 0); __builtin_amdgcn_s_setprio(0); } while (0)
; #define PG8_WAIT_V(n) asm volatile("s_waitcnt vmcnt(" #n ")" ::: "memory")
; #define PG8_WAIT_L(n) asm volatile("s_waitcnt lgkmcnt(" #n ")" ::: "memory")
; #define PG8_BAR __builtin_amdgcn_s_barrier()
; #define PG8_SCHED __builtin_amdgcn_sched_barrier(0)
; template <class Epi>
; __device__ __forceinline__ void gemm_phase(PG8_LAS unsigned char* lds, const Gemm g, const StaticOrder& S, const Epi& E) {
;     ...
;       PG8_BAR; PG8_WAIT_L(0); PG8_MMA(0, 1, At, B1); PG8_BAR;
;       PG8_LDA(At, 1, 1); PG8_STAGE(PG8_SA(1, 0), a3, voffA);
;       PG8_BAR; PG8_WAIT_L(0); PG8_MMA(1, 0, At, B0); PG8_BAR; PG8_SCHED;
;       PG8_STAGE(PG8_SB(1, 1), b3 + hstep, voffB);
;       PG8_WAIT_V(6); PG8_BAR; PG8_MMA(1, 1, At, B1); PG8_BAR;
;     }
;     E(acc, cur, wr, wc, fr, fq);
	s_waitcnt lgkmcnt(0)
	s_waitcnt lgkmcnt(0)
	v_mfma_f32_16x16x32_bf16 v[126:129], v[154:157], v[196:199], v[126:129]
	v_mfma_f32_16x16x32_bf16 v[122:125], v[188:191], v[196:199], v[122:125]
	v_mfma_f32_16x16x32_bf16 v[110:113], v[154:157], v[204:207], v[110:113]
	v_mfma_f32_16x16x32_bf16 v[106:109], v[188:191], v[204:207], v[106:109]
	v_mfma_f32_16x16x32_bf16 v[94:97], v[154:157], v[212:215], v[94:97]
	v_mfma_f32_16x16x32_bf16 v[90:93], v[188:191], v[212:215], v[90:93]
	v_mfma_f32_16x16x32_bf16 v[78:81], v[154:157], v[220:223], v[78:81]
	v_mfma_f32_16x16x32_bf16 v[74:77], v[188:191], v[220:223], v[74:77]
	v_mfma_f32_16x16x32_bf16 v[126:129], v[164:167], v[200:203], v[126:129]
	v_mfma_f32_16x16x32_bf16 v[122:125], v[192:195], v[200:203], v[122:125]
	v_mfma_f32_16x16x32_bf16 v[110:113], v[164:167], v[208:211], v[110:113]
	v_mfma_f32_16x16x32_bf16 v[106:109], v[192:195], v[208:211], v[106:109]
	v_mfma_f32_16x16x32_bf16 v[94:97], v[164:167], v[216:219], v[94:97]
	v_mfma_f32_16x16x32_bf16 v[90:93], v[192:195], v[216:219], v[90:93]
	v_mfma_f32_16x16x32_bf16 v[78:81], v[164:167], v[224:227], v[78:81]
	v_mfma_f32_16x16x32_bf16 v[74:77], v[192:195], v[224:227], v[74:77]
	s_barrier
	s_add_i32 s54, 0, 0x1c000
	s_add_i32 s48, s66, s28
	v_add_u32_e32 v163, s54, v160
	v_lshl_add_u64 v[158:159], v[158:159], 0, s[4:5]
	s_mov_b32 m0, s48
	ds_read_b128 v[228:231], v163
	ds_read_b128 v[232:235], v163 offset:1024
	ds_read_b128 v[236:239], v163 offset:2048
	ds_read_b128 v[240:243], v163 offset:3072
	global_load_lds_dwordx4 v[158:159], off
	v_lshl_add_u64 v[158:159], v[178:179], 0, s[4:5]
	s_add_i32 m0, s48, 0x2000
	s_nop 0
	global_load_lds_dwordx4 v[158:159], off
	s_barrier
	s_waitcnt lgkmcnt(0)
	s_waitcnt lgkmcnt(0)
	v_mfma_f32_16x16x32_bf16 v[118:121], v[228:231], v[196:199], v[118:121]
	v_mfma_f32_16x16x32_bf16 v[114:117], v[236:239], v[196:199], v[114:117]
	v_mfma_f32_16x16x32_bf16 v[102:105], v[228:231], v[204:207], v[102:105]
	v_mfma_f32_16x16x32_bf16 v[98:101], v[236:239], v[204:207], v[98:101]
	v_mfma_f32_16x16x32_bf16 v[86:89], v[228:231], v[212:215], v[86:89]
	v_mfma_f32_16x16x32_bf16 v[82:85], v[236:239], v[212:215], v[82:85]
	v_mfma_f32_16x16x32_bf16 v[70:73], v[228:231], v[220:223], v[70:73]
	v_mfma_f32_16x16x32_bf16 v[66:69], v[236:239], v[220:223], v[66:69]
	v_mfma_f32_16x16x32_bf16 v[118:121], v[232:235], v[200:203], v[118:121]
	v_mfma_f32_16x16x32_bf16 v[114:117], v[240:243], v[200:203], v[114:117]
	v_mfma_f32_16x16x32_bf16 v[102:105], v[232:235], v[208:211], v[102:105]
	v_mfma_f32_16x16x32_bf16 v[98:101], v[240:243], v[208:211], v[98:101]
	v_mfma_f32_16x16x32_bf16 v[86:89], v[232:235], v[216:219], v[86:89]
	v_mfma_f32_16x16x32_bf16 v[82:85], v[240:243], v[216:219], v[82:85]
	v_mfma_f32_16x16x32_bf16 v[70:73], v[232:235], v[224:227], v[70:73]
	v_mfma_f32_16x16x32_bf16 v[66:69], v[240:243], v[224:227], v[66:69]
	s_mov_b32 m0, s60
	v_lshl_add_u64 v[158:159], v[244:245], 0, s[4:5]
	s_barrier
	ds_read_b128 v[196:199], v162 offset:49152
	ds_read_b128 v[200:203], v162 offset:50176
	ds_read_b128 v[204:207], v162 offset:51200
	ds_read_b128 v[208:211], v162 offset:52224
	ds_read_b128 v[212:215], v162 offset:53248
	ds_read_b128 v[216:219], v162 offset:54272
	ds_read_b128 v[220:223], v162 offset:55296
	ds_read_b128 v[224:227], v162 offset:56320
	global_load_lds_dwordx4 v[158:159], off
	v_lshl_add_u64 v[158:159], v[246:247], 0, s[4:5]
	s_mov_b32 m0, s61
	s_nop 0
	global_load_lds_dwordx4 v[158:159], off
	s_barrier
	s_waitcnt lgkmcnt(0)
	s_waitcnt lgkmcnt(0)
	v_mfma_f32_16x16x32_bf16 v[62:65], v[154:157], v[196:199], v[62:65]
	v_mfma_f32_16x16x32_bf16 v[58:61], v[188:191], v[196:199], v[58:61]
	v_mfma_f32_16x16x32_bf16 v[46:49], v[154:157], v[204:207], v[46:49]
	v_mfma_f32_16x16x32_bf16 v[42:45], v[188:191], v[204:207], v[42:45]
	v_mfma_f32_16x16x32_bf16 v[30:33], v[154:157], v[212:215], v[30:33]
	v_mfma_f32_16x16x32_bf16 v[26:29], v[188:191], v[212:215], v[26:29]
	v_mfma_f32_16x16x32_bf16 v[14:17], v[154:157], v[220:223], v[14:17]
	v_mfma_f32_16x16x32_bf16 v[10:13], v[188:191], v[220:223], v[10:13]
	v_mfma_f32_16x16x32_bf16 v[62:65], v[164:167], v[200:203], v[62:65]
	v_mfma_f32_16x16x32_bf16 v[58:61], v[192:195], v[200:203], v[58:61]
	v_mfma_f32_16x16x32_bf16 v[46:49], v[164:167], v[208:211], v[46:49]
	v_mfma_f32_16x16x32_bf16 v[42:45], v[192:195], v[208:211], v[42:45]
	v_mfma_f32_16x16x32_bf16 v[30:33], v[164:167], v[216:219], v[30:33]
	v_mfma_f32_16x16x32_bf16 v[26:29], v[192:195], v[216:219], v[26:29]
	v_mfma_f32_16x16x32_bf16 v[14:17], v[164:167], v[224:227], v[14:17]
	v_mfma_f32_16x16x32_bf16 v[10:13], v[192:195], v[224:227], v[10:13]
	s_barrier
	s_add_u32 s48, s52, 0x80080
	s_addc_u32 s49, s53, 0
	s_add_i32 s52, s54, s28
	v_lshl_add_u64 v[154:155], s[48:49], 0, v[0:1]
	s_mov_b32 m0, s52
	s_nop 0
	global_load_lds_dwordx4 v[154:155], off
	v_lshl_add_u64 v[154:155], s[48:49], 0, v[148:149]
	s_add_i32 m0, s52, 0x2000
	s_nop 0
	global_load_lds_dwordx4 v[154:155], off
	s_waitcnt vmcnt(6)
	s_barrier
	v_mfma_f32_16x16x32_bf16 v[54:57], v[228:231], v[196:199], v[54:57]
	v_mfma_f32_16x16x32_bf16 v[50:53], v[236:239], v[196:199], v[50:53]
	v_mfma_f32_16x16x32_bf16 v[38:41], v[228:231], v[204:207], v[38:41]
	v_mfma_f32_16x16x32_bf16 v[34:37], v[236:239], v[204:207], v[34:37]
	v_mfma_f32_16x16x32_bf16 v[22:25], v[228:231], v[212:215], v[22:25]
	v_mfma_f32_16x16x32_bf16 v[18:21], v[236:239], v[212:215], v[18:21]
	v_mfma_f32_16x16x32_bf16 v[6:9], v[228:231], v[220:223], v[6:9]
	v_mfma_f32_16x16x32_bf16 v[2:5], v[236:239], v[220:223], v[2:5]
	v_mfma_f32_16x16x32_bf16 v[54:57], v[232:235], v[200:203], v[54:57]
	v_mfma_f32_16x16x32_bf16 v[50:53], v[240:243], v[200:203], v[50:53]
	v_mfma_f32_16x16x32_bf16 v[38:41], v[232:235], v[208:211], v[38:41]
	v_mfma_f32_16x16x32_bf16 v[34:37], v[240:243], v[208:211], v[34:37]
	v_mfma_f32_16x16x32_bf16 v[22:25], v[232:235], v[216:219], v[22:25]
	v_mfma_f32_16x16x32_bf16 v[18:21], v[240:243], v[216:219], v[18:21]
	v_mfma_f32_16x16x32_bf16 v[6:9], v[232:235], v[224:227], v[6:9]
	v_mfma_f32_16x16x32_bf16 v[2:5], v[240:243], v[224:227], v[2:5]
	s_add_i32 s65, s65, 2
	s_add_u32 s63, s63, 0x100
	s_addc_u32 s64, s64, 0
	s_cmp_gt_u32 s65, 29
	s_mov_b64 s[48:49], s[50:51]
	s_barrier
	s_cbranch_scc0 .LBB0_1046
	v_readlane_b32 s80, v254, 5
	v_readlane_b32 s81, v254, 6
	v_readlane_b32 s82, v254, 7
	v_readlane_b32 s83, v254, 8
	s_cmp_ge_i32 s46, 65
	s_cselect_b32 s68, 1, 0
	s_mul_i32 s69, s68, 65
	s_sub_i32 s69, s46, s69
	s_cmp_eq_u32 s69, 0
	s_cbranch_scc1 .LepiB_ctx
	s_add_i32 s69, s69, -1
	s_lshl_b32 s69, s69, 8
	s_lshl_b32 s70, s68, 14
	s_add_i32 s69, s69, s70
	s_lshl_b32 s69, s69, 12
	s_add_u32 s70, s80, s69
	s_addc_u32 s71, s81, 0
	s_mul_i32 s68, s68, 0x3000
	s_branch .LepiB_go

; #define PG8_WAIT_V(n) asm volatile("s_waitcnt vmcnt(" #n ")" ::: "memory")
; #define PG8_WAIT_L(n) asm volatile("s_waitcnt lgkmcnt(" #n ")" ::: "memory")
; #define PG8_BAR __builtin_amdgcn_s_barrier()
; template <class Epi>
; __device__ __forceinline__ void gemm_phase(PG8_LAS unsigned char* lds, const Gemm g, const StaticOrder& S, const Epi& E) {
;     ...
;   for (;;) {
;     const bool has_next = S.next(ui + 1, nxt);
;     const char* nA = has_next ? (const char*)g.A + (size_t)nxt.pm * tstep : cA; const char* nB = has_next ? (const char*)g.Bt + (size_t)nxt.pn * tstep : cB;
;     for (int t = 0; t < nt; t += 2) {
;       const bool last = (t == nt - 2);
;       const char* a1 = cA + (size_t)(t + 1) * kstep;
;       const char* a2 = last ? nA : cA + (size_t)(t + 2) * kstep; const char* b2 = last ? nB : cB + (size_t)(t + 2) * kstep;
;       const char* a3 = a2 + kstep; const char* b3 = b2 + kstep;
;       PG8_LDB(B0, 0, 0); PG8_SCHED; PG8_LDA(At, 0, 0); PG8_STAGE(PG8_SA(1, 1), a1 + hstep, voffA);
;       PG8_WAIT_L(8); PG8_BAR; PG8_WAIT_L(0); PG8_MMA(0, 0, At, B0); PG8_BAR; PG8_SCHED;
;       PG8_LDB(B1, 0, 1); PG8_STAGE(PG8_SB(0, 0), b2, voffB);
;       PG8_BAR; PG8_WAIT_L(0); PG8_MMA(0, 1, At, B1); PG8_BAR;
;       PG8_LDA(At, 0, 1); PG8_STAGE(PG8_SA(0, 0), a2, voffA);
;       PG8_BAR; PG8_WAIT_L(0); PG8_MMA(1, 0, At, B0); PG8_BAR; PG8_SCHED;
;       PG8_STAGE(PG8_SB(0, 1), b2 + hstep, voffB);
;       PG8_WAIT_V(6); PG8_BAR; PG8_MMA(1, 1, At, B1); PG8_BAR;
;       PG8_LDB(B0, 1, 0); PG8_SCHED; PG8_LDA(At, 1, 0); PG8_STAGE(PG8_SA(0, 1), a2 + hstep, voffA);
;       PG8_WAIT_L(8); PG8_BAR; PG8_WAIT_L(0); PG8_MMA(0, 0, At, B0); PG8_BAR; PG8_SCHED;
;       PG8_LDB(B1, 1, 1); PG8_STAGE(PG8_SB(1, 0), b3, voffB);
;       PG8_BAR; PG8_WAIT_L(0); PG8_MMA(0, 1, At, B1); PG8_BAR;
;       PG8_LDA(At, 1, 1); PG8_STAGE(PG8_SA(1, 0), a3, voffA);
;       PG8_BAR; PG8_WAIT_L(0); PG8_MMA(1, 0, At, B0); PG8_BAR; PG8_SCHED;
;       PG8_STAGE(PG8_SB(1, 1), b3 + hstep, voffB);
;       PG8_WAIT_V(6); PG8_BAR; PG8_MMA(1, 1, At, B1); PG8_BAR;
;     }
;     E(acc, cur, wr, wc, fr, fq);
;     if (!has_next) break;
; #pragma unroll
;     for (int a = 0; a < 2; ++a)
; #pragma unroll
;       for (int b = 0; b < 2; ++b)
; #pragma unroll
;         for (int m = 0; m < 4; ++m)
; #pragma unroll
;           for (int n = 0; n < 2; ++n) acc[a][b][m][n] = (f32x4){0.f, 0.f, 0.f, 0.f};
.LBB0_1122:
	s_ashr_i32 s45, s44, 31
	v_cmp_lt_i64_e32 vcc, s[46:47], v[140:141]
	s_lshl_b64 s[46:47], s[44:45], 19
	s_add_u32 s46, s24, s46
	s_addc_u32 s47, s25, s47
	s_and_b64 s[48:49], vcc, exec
	s_cselect_b32 s45, s47, s9
	s_cselect_b32 s59, s46, s8
	s_ashr_i32 s43, s42, 31
	s_lshl_b64 s[48:49], s[42:43], 19
	v_readlane_b32 s43, v252, 58
	s_add_u32 s48, s43, s48
	v_readlane_b32 s43, v252, 59
	s_addc_u32 s49, s43, s49
	s_and_b64 s[50:51], vcc, exec
	s_cselect_b32 s43, s49, s11
	s_cselect_b32 s60, s48, s10
	s_add_u32 s8, s8, 0x40080
	s_addc_u32 s9, s9, 0
	s_add_u32 s61, s10, 0x100
	v_mov_b32_e32 v2, 0
	s_addc_u32 s62, s11, 0
	s_mov_b32 s63, -2
	v_mov_b32_e32 v3, v2
	v_mov_b32_e32 v4, v2
	v_mov_b32_e32 v5, v2
	v_mov_b32_e32 v6, v2
	v_mov_b32_e32 v7, v2
	v_mov_b32_e32 v8, v2
	v_mov_b32_e32 v9, v2
	v_mov_b32_e32 v18, v2
	v_mov_b32_e32 v19, v2
	v_mov_b32_e32 v20, v2
	v_mov_b32_e32 v21, v2
	v_mov_b32_e32 v22, v2
	v_mov_b32_e32 v23, v2
	v_mov_b32_e32 v24, v2
	v_mov_b32_e32 v25, v2
	v_mov_b32_e32 v34, v2
	v_mov_b32_e32 v35, v2
	v_mov_b32_e32 v36, v2
	v_mov_b32_e32 v37, v2
	v_mov_b32_e32 v38, v2
	v_mov_b32_e32 v39, v2
	v_mov_b32_e32 v40, v2
	v_mov_b32_e32 v41, v2
	v_mov_b32_e32 v50, v2
	v_mov_b32_e32 v51, v2
	v_mov_b32_e32 v52, v2
	v_mov_b32_e32 v53, v2
	v_mov_b32_e32 v54, v2
	v_mov_b32_e32 v55, v2
	v_mov_b32_e32 v56, v2
	v_mov_b32_e32 v57, v2
	v_mov_b32_e32 v10, v2
	v_mov_b32_e32 v11, v2
	v_mov_b32_e32 v12, v2
	v_mov_b32_e32 v13, v2
	v_mov_b32_e32 v14, v2
	v_mov_b32_e32 v15, v2
	v_mov_b32_e32 v16, v2
	v_mov_b32_e32 v17, v2
	v_mov_b32_e32 v26, v2
	v_mov_b32_e32 v27, v2
	v_mov_b32_e32 v28, v2
	v_mov_b32_e32 v29, v2
	v_mov_b32_e32 v30, v2
	v_mov_b32_e32 v31, v2
	v_mov_b32_e32 v32, v2
	v_mov_b32_e32 v33, v2
	v_mov_b32_e32 v42, v2
	v_mov_b32_e32 v43, v2
	v_mov_b32_e32 v44, v2
	v_mov_b32_e32 v45, v2
	v_mov_b32_e32 v46, v2
	v_mov_b32_e32 v47, v2
	v_mov_b32_e32 v48, v2
	v_mov_b32_e32 v49, v2
	v_mov_b32_e32 v58, v2
	v_mov_b32_e32 v59, v2
	v_mov_b32_e32 v60, v2
	v_mov_b32_e32 v61, v2
	v_mov_b32_e32 v62, v2
	v_mov_b32_e32 v63, v2
	v_mov_b32_e32 v64, v2
	v_mov_b32_e32 v65, v2
	v_mov_b32_e32 v66, v2
	v_mov_b32_e32 v67, v2
	v_mov_b32_e32 v68, v2
	v_mov_b32_e32 v69, v2
	v_mov_b32_e32 v70, v2
	v_mov_b32_e32 v71, v2
	v_mov_b32_e32 v72, v2
	v_mov_b32_e32 v73, v2
	v_mov_b32_e32 v82, v2
	v_mov_b32_e32 v83, v2
	v_mov_b32_e32 v84, v2
	v_mov_b32_e32 v85, v2
	v_mov_b32_e32 v86, v2
	v_mov_b32_e32 v87, v2
	v_mov_b32_e32 v88, v2
	v_mov_b32_e32 v89, v2
	v_mov_b32_e32 v98, v2
	v_mov_b32_e32 v99, v2
	v_mov_b32_e32 v100, v2
	v_mov_b32_e32 v101, v2
	v_mov_b32_e32 v102, v2
	v_mov_b32_e32 v103, v2
	v_mov_b32_e32 v104, v2
	v_mov_b32_e32 v105, v2
	v_mov_b32_e32 v114, v2
	v_mov_b32_e32 v115, v2
	v_mov_b32_e32 v116, v2
	v_mov_b32_e32 v117, v2
	v_mov_b32_e32 v118, v2
	v_mov_b32_e32 v119, v2
	v_mov_b32_e32 v120, v2
	v_mov_b32_e32 v121, v2
	v_mov_b32_e32 v74, v2
	v_mov_b32_e32 v75, v2
	v_mov_b32_e32 v76, v2
	v_mov_b32_e32 v77, v2
	v_mov_b32_e32 v78, v2
	v_mov_b32_e32 v79, v2
	v_mov_b32_e32 v80, v2
	v_mov_b32_e32 v81, v2
	v_mov_b32_e32 v90, v2
	v_mov_b32_e32 v91, v2
	v_mov_b32_e32 v92, v2
	v_mov_b32_e32 v93, v2
	v_mov_b32_e32 v94, v2
	v_mov_b32_e32 v95, v2
	v_mov_b32_e32 v96, v2
	v_mov_b32_e32 v97, v2
	v_mov_b32_e32 v106, v2
	v_mov_b32_e32 v107, v2
	v_mov_b32_e32 v108, v2
	v_mov_b32_e32 v109, v2
	v_mov_b32_e32 v110, v2
	v_mov_b32_e32 v111, v2
	v_mov_b32_e32 v112, v2
	v_mov_b32_e32 v113, v2
	v_mov_b32_e32 v122, v2
	v_mov_b32_e32 v123, v2
	v_mov_b32_e32 v124, v2
	v_mov_b32_e32 v125, v2
	v_mov_b32_e32 v126, v2
	v_mov_b32_e32 v127, v2
	v_mov_b32_e32 v128, v2
	v_mov_b32_e32 v129, v2
	v_readfirstlane_b32 s100, v168
	s_lshr_b32 s100, s100, 6
	s_cmp_ge_u32 s100, 4
	s_cbranch_scc0 .Lgp_3
	s_setprio 1
.Lgp_3:
.LBB0_1123:
	s_add_u32 s10, s8, 0xfffc0080
	s_addc_u32 s11, s9, -1
	s_add_i32 s64, 0, 0x10000
	v_add_u32_e32 v162, s64, v164
	ds_read_b128 v[154:157], v162
	ds_read_b128 v[158:161], v162 offset:1024
	ds_read_b128 v[188:191], v162 offset:2048
	ds_read_b128 v[192:195], v162 offset:3072
	s_cmp_eq_u32 s63, 12
	s_cselect_b32 s51, s45, s11
	s_cselect_b32 s50, s59, s10
	s_cselect_b32 s11, s43, s62
	s_cselect_b32 s10, s60, s61
	v_lshl_add_u64 v[162:163], s[8:9], 0, v[150:151]
	s_add_i32 m0, s52, 0xc000
	ds_read_b128 v[196:199], v166
	ds_read_b128 v[200:203], v166 offset:1024
	ds_read_b128 v[204:207], v166 offset:2048
	ds_read_b128 v[208:211], v166 offset:3072
	ds_read_b128 v[212:215], v166 offset:4096
	ds_read_b128 v[216:219], v166 offset:5120
	ds_read_b128 v[220:223], v166 offset:6144
	ds_read_b128 v[224:227], v166 offset:7168
	global_load_lds_dwordx4 v[162:163], off
	v_lshl_add_u64 v[162:163], s[8:9], 0, v[152:153]
	s_add_i32 m0, s52, 0xe000
	s_nop 0
	global_load_lds_dwordx4 v[162:163], off
	s_waitcnt lgkmcnt(8)
	s_barrier
	s_waitcnt lgkmcnt(0)
	s_waitcnt lgkmcnt(0)
	v_mfma_f32_16x16x32_bf16 v[126:129], v[154:157], v[196:199], v[126:129]
	v_mfma_f32_16x16x32_bf16 v[122:125], v[188:191], v[196:199], v[122:125]
	v_mfma_f32_16x16x32_bf16 v[110:113], v[154:157], v[204:207], v[110:113]
	v_mfma_f32_16x16x32_bf16 v[106:109], v[188:191], v[204:207], v[106:109]
	v_mfma_f32_16x16x32_bf16 v[94:97], v[154:157], v[212:215], v[94:97]
	v_mfma_f32_16x16x32_bf16 v[90:93], v[188:191], v[212:215], v[90:93]
	v_mfma_f32_16x16x32_bf16 v[78:81], v[154:157], v[220:223], v[78:81]
	v_mfma_f32_16x16x32_bf16 v[74:77], v[188:191], v[220:223], v[74:77]
	v_mfma_f32_16x16x32_bf16 v[126:129], v[158:161], v[200:203], v[126:129]
	v_mfma_f32_16x16x32_bf16 v[122:125], v[192:195], v[200:203], v[122:125]
	v_mfma_f32_16x16x32_bf16 v[110:113], v[158:161], v[208:211], v[110:113]
	v_mfma_f32_16x16x32_bf16 v[106:109], v[192:195], v[208:211], v[106:109]
	v_mfma_f32_16x16x32_bf16 v[94:97], v[158:161], v[216:219], v[94:97]
	v_mfma_f32_16x16x32_bf16 v[90:93], v[192:195], v[216:219], v[90:93]
	v_mfma_f32_16x16x32_bf16 v[78:81], v[158:161], v[224:227], v[78:81]
	v_mfma_f32_16x16x32_bf16 v[74:77], v[192:195], v[224:227], v[74:77]
	s_barrier
; #define PG8_STAGE(bufoff, gbase, voff) do { _Pragma("unroll") for (int _i = 0; _i < 2; ++_i) \
;     __builtin_amdgcn_global_load_lds((const unsigned*)((const char*)(gbase) + (voff)[_i]), (PG8_LAS unsigned*)(lds + (bufoff) + ldsw + _i * 8192), 16, 0, 0); } while (0)
; #define PG8_LDA(dst, b, h) do { _Pragma("unroll") for (int m = 0; m < 4; ++m) _Pragma("unroll") for (int k = 0; k < 2; ++k) dst[m][k] = *(const PG8_LAS bf16x8*)(lds + PG8_SA(b, h) + aoff + m * 2048 + k * 1024); } while (0)
; #define PG8_LDB(dst, b, h) do { _Pragma("unroll") for (int n = 0; n < 2; ++n) _Pragma("unroll") for (int k = 0; k < 2; ++k) dst[n][k] = *(const PG8_LAS bf16x8*)(lds + PG8_SB(b, h) + boff + n * 2048 + k * 1024); } while (0)
; #define PG8_MMA(ai, bj, At, Bt) do { __builtin_amdgcn_s_setprio(1); _Pragma("unroll") for (int m = 0; m < 4; ++m) _Pragma("unroll") for (int n = 0; n < 2; ++n) _Pragma("unroll") for (int k = 0; k < 2; ++k) \
;     acc[ai][bj][m][n] = __builtin_amdgcn_mfma_f32_16x16x32_bf16(Bt[n][k], At[m][k], acc[ai][bj][m][n], 0, 0, 0); __builtin_amdgcn_s_setprio(0); } while (0)
; #define PG8_WAIT_V(n) asm volatile("s_waitcnt vmcnt(" #n ")" ::: "memory")
; #define PG8_WAIT_L(n) asm volatile("s_waitcnt lgkmcnt(" #n ")" ::: "memory")
; #define PG8_BAR __builtin_amdgcn_s_barrier()
; #define PG8_SCHED __builtin_amdgcn_sched_barrier(0)
; template <class Epi>
; __device__ __forceinline__ void gemm_phase(PG8_LAS unsigned char* lds, const Gemm g, const StaticOrder& S, const Epi& E) {
;     ...
;       PG8_LDB(B1, 0, 1); PG8_STAGE(PG8_SB(0, 0), b2, voffB);
;       PG8_BAR; PG8_WAIT_L(0); PG8_MMA(0, 1, At, B1); PG8_BAR;
;       PG8_LDA(At, 0, 1); PG8_STAGE(PG8_SA(0, 0), a2, voffA);
;       PG8_BAR; PG8_WAIT_L(0); PG8_MMA(1, 0, At, B0); PG8_BAR; PG8_SCHED;
;       PG8_STAGE(PG8_SB(0, 1), b2 + hstep, voffB);
;       PG8_WAIT_V(6); PG8_BAR; PG8_MMA(1, 1, At, B1); PG8_BAR;
;       PG8_LDB(B0, 1, 0); PG8_SCHED; PG8_LDA(At, 1, 0); PG8_STAGE(PG8_SA(0, 1), a2 + hstep, voffA);
;       PG8_WAIT_L(8); PG8_BAR; PG8_WAIT_L(0); PG8_MMA(0, 0, At, B0); PG8_BAR; PG8_SCHED;
;       PG8_LDB(B1, 1, 1); PG8_STAGE(PG8_SB(1, 0), b3, voffB);
	s_add_i32 s66, 0, 0x14000
	v_add_u32_e32 v162, s66, v164
	s_add_i32 s64, s64, s28
	ds_read_b128 v[228:231], v162
	ds_read_b128 v[232:235], v162 offset:1024
	ds_read_b128 v[236:239], v162 offset:2048
	ds_read_b128 v[240:243], v162 offset:3072
	v_lshl_add_u64 v[162:163], s[10:11], 0, v[0:1]
	s_mov_b32 m0, s64
	v_lshl_add_u64 v[178:179], s[10:11], 0, v[148:149]
	global_load_lds_dwordx4 v[162:163], off
	s_add_i32 m0, s64, 0x2000
	s_nop 0
	global_load_lds_dwordx4 v[178:179], off
	s_barrier
	s_waitcnt lgkmcnt(0)
	s_waitcnt lgkmcnt(0)
	v_mfma_f32_16x16x32_bf16 v[118:121], v[228:231], v[196:199], v[118:121]
	v_mfma_f32_16x16x32_bf16 v[114:117], v[236:239], v[196:199], v[114:117]
	v_mfma_f32_16x16x32_bf16 v[102:105], v[228:231], v[204:207], v[102:105]
	v_mfma_f32_16x16x32_bf16 v[98:101], v[236:239], v[204:207], v[98:101]
	v_mfma_f32_16x16x32_bf16 v[86:89], v[228:231], v[212:215], v[86:89]
	v_mfma_f32_16x16x32_bf16 v[82:85], v[236:239], v[212:215], v[82:85]
	v_mfma_f32_16x16x32_bf16 v[70:73], v[228:231], v[220:223], v[70:73]
	v_mfma_f32_16x16x32_bf16 v[66:69], v[236:239], v[220:223], v[66:69]
	v_mfma_f32_16x16x32_bf16 v[118:121], v[232:235], v[200:203], v[118:121]
	v_mfma_f32_16x16x32_bf16 v[114:117], v[240:243], v[200:203], v[114:117]
	v_mfma_f32_16x16x32_bf16 v[102:105], v[232:235], v[208:211], v[102:105]
	v_mfma_f32_16x16x32_bf16 v[98:101], v[240:243], v[208:211], v[98:101]
	v_mfma_f32_16x16x32_bf16 v[86:89], v[232:235], v[216:219], v[86:89]
	v_mfma_f32_16x16x32_bf16 v[82:85], v[240:243], v[216:219], v[82:85]
	v_mfma_f32_16x16x32_bf16 v[70:73], v[232:235], v[224:227], v[70:73]
	v_mfma_f32_16x16x32_bf16 v[66:69], v[240:243], v[224:227], v[66:69]
	s_mov_b32 m0, s52
	v_lshl_add_u64 v[244:245], s[50:51], 0, v[0:1]
	s_barrier
	ds_read_b128 v[196:199], v166 offset:16384
	ds_read_b128 v[200:203], v166 offset:17408
	ds_read_b128 v[204:207], v166 offset:18432
	ds_read_b128 v[208:211], v166 offset:19456
	ds_read_b128 v[212:215], v166 offset:20480
	ds_read_b128 v[216:219], v166 offset:21504
	ds_read_b128 v[220:223], v166 offset:22528
	ds_read_b128 v[224:227], v166 offset:23552
	global_load_lds_dwordx4 v[244:245], off
	v_lshl_add_u64 v[246:247], s[50:51], 0, v[148:149]
	s_mov_b32 m0, s53
	s_nop 0
	global_load_lds_dwordx4 v[246:247], off
	s_barrier
	s_waitcnt lgkmcnt(0)
	s_waitcnt lgkmcnt(0)
	v_mfma_f32_16x16x32_bf16 v[62:65], v[154:157], v[196:199], v[62:65]
	v_mfma_f32_16x16x32_bf16 v[58:61], v[188:191], v[196:199], v[58:61]
	v_mfma_f32_16x16x32_bf16 v[46:49], v[154:157], v[204:207], v[46:49]
	v_mfma_f32_16x16x32_bf16 v[42:45], v[188:191], v[204:207], v[42:45]
	v_mfma_f32_16x16x32_bf16 v[30:33], v[154:157], v[212:215], v[30:33]
	v_mfma_f32_16x16x32_bf16 v[26:29], v[188:191], v[212:215], v[26:29]
	v_mfma_f32_16x16x32_bf16 v[14:17], v[154:157], v[220:223], v[14:17]
	v_mfma_f32_16x16x32_bf16 v[10:13], v[188:191], v[220:223], v[10:13]
	v_mfma_f32_16x16x32_bf16 v[62:65], v[158:161], v[200:203], v[62:65]
	v_mfma_f32_16x16x32_bf16 v[58:61], v[192:195], v[200:203], v[58:61]
	v_mfma_f32_16x16x32_bf16 v[46:49], v[158:161], v[208:211], v[46:49]
	v_mfma_f32_16x16x32_bf16 v[42:45], v[192:195], v[208:211], v[42:45]
	v_mfma_f32_16x16x32_bf16 v[30:33], v[158:161], v[216:219], v[30:33]
	v_mfma_f32_16x16x32_bf16 v[26:29], v[192:195], v[216:219], v[26:29]
	v_mfma_f32_16x16x32_bf16 v[14:17], v[158:161], v[224:227], v[14:17]
	v_mfma_f32_16x16x32_bf16 v[10:13], v[192:195], v[224:227], v[10:13]
	s_barrier
	s_add_u32 s64, s10, 0x40000
	s_addc_u32 s65, s11, 0
	s_add_i32 s66, s66, s28
	v_lshl_add_u64 v[154:155], s[64:65], 0, v[0:1]
	s_mov_b32 m0, s66
	s_nop 0
	global_load_lds_dwordx4 v[154:155], off
	v_lshl_add_u64 v[154:155], s[64:65], 0, v[148:149]
	s_add_i32 m0, s66, 0x2000
	s_nop 0
	global_load_lds_dwordx4 v[154:155], off
	s_waitcnt vmcnt(6)
	s_barrier
	v_mfma_f32_16x16x32_bf16 v[54:57], v[228:231], v[196:199], v[54:57]
	v_mfma_f32_16x16x32_bf16 v[50:53], v[236:239], v[196:199], v[50:53]
	v_mfma_f32_16x16x32_bf16 v[38:41], v[228:231], v[204:207], v[38:41]
	v_mfma_f32_16x16x32_bf16 v[34:37], v[236:239], v[204:207], v[34:37]
	v_mfma_f32_16x16x32_bf16 v[22:25], v[228:231], v[212:215], v[22:25]
	v_mfma_f32_16x16x32_bf16 v[18:21], v[236:239], v[212:215], v[18:21]
	v_mfma_f32_16x16x32_bf16 v[6:9], v[228:231], v[220:223], v[6:9]
	v_mfma_f32_16x16x32_bf16 v[2:5], v[236:239], v[220:223], v[2:5]
	v_mfma_f32_16x16x32_bf16 v[54:57], v[232:235], v[200:203], v[54:57]
	v_mfma_f32_16x16x32_bf16 v[50:53], v[240:243], v[200:203], v[50:53]
	v_mfma_f32_16x16x32_bf16 v[38:41], v[232:235], v[208:211], v[38:41]
	v_mfma_f32_16x16x32_bf16 v[34:37], v[240:243], v[208:211], v[34:37]
	v_mfma_f32_16x16x32_bf16 v[22:25], v[232:235], v[216:219], v[22:25]
	v_mfma_f32_16x16x32_bf16 v[18:21], v[240:243], v[216:219], v[18:21]
	v_mfma_f32_16x16x32_bf16 v[6:9], v[232:235], v[224:227], v[6:9]
	v_mfma_f32_16x16x32_bf16 v[2:5], v[240:243], v[224:227], v[2:5]
	s_add_i32 s64, 0, 0x18000
	v_add_u32_e32 v167, s64, v164
	s_barrier
	ds_read_b128 v[154:157], v167
	ds_read_b128 v[158:161], v167 offset:1024
	ds_read_b128 v[188:191], v167 offset:2048
	ds_read_b128 v[192:195], v167 offset:3072
	s_add_u32 s50, s50, 0x40000
	s_addc_u32 s51, s51, 0
	s_mov_b32 m0, s54
	v_lshl_add_u64 v[228:229], s[50:51], 0, v[0:1]
	ds_read_b128 v[196:199], v166 offset:32768
	ds_read_b128 v[200:203], v166 offset:33792
	ds_read_b128 v[204:207], v166 offset:34816
	ds_read_b128 v[208:211], v166 offset:35840
	ds_read_b128 v[212:215], v166 offset:36864
	ds_read_b128 v[216:219], v166 offset:37888
	ds_read_b128 v[220:223], v166 offset:38912
	ds_read_b128 v[224:227], v166 offset:39936
	global_load_lds_dwordx4 v[228:229], off
	v_lshl_add_u64 v[228:229], s[50:51], 0, v[148:149]
	s_mov_b32 m0, s55
	s_nop 0
	global_load_lds_dwordx4 v[228:229], off
	s_waitcnt lgkmcnt(8)
	s_barrier
; #define PG8_STAGE(bufoff, gbase, voff) do { _Pragma("unroll") for (int _i = 0; _i < 2; ++_i) \
;     __builtin_amdgcn_global_load_lds((const unsigned*)((const char*)(gbase) + (voff)[_i]), (PG8_LAS unsigned*)(lds + (bufoff) + ldsw + _i * 8192), 16, 0, 0); } while (0)
; #define PG8_LDA(dst, b, h) do { _Pragma("unroll") for (int m = 0; m < 4; ++m) _Pragma("unroll") for (int k = 0; k < 2; ++k) dst[m][k] = *(const PG8_LAS bf16x8*)(lds + PG8_SA(b, h) + aoff + m * 2048 + k * 1024); } while (0)
; #define PG8_LDB(dst, b, h) do { _Pragma("unroll") for (int n = 0; n < 2; ++n) _Pragma("unroll") for (int k = 0; k < 2; ++k) dst[n][k] = *(const PG8_LAS bf16x8*)(lds + PG8_SB(b, h) + boff + n * 2048 + k * 1024); } while (0)
; #define PG8_MMA(ai, bj, At, Bt) do { __builtin_amdgcn_s_setprio(1); _Pragma("unroll") for (int m = 0; m < 4; ++m) _Pragma("unroll") for (int n = 0; n < 2; ++n) _Pragma("unroll") for (int k = 0; k < 2; ++k) \
;     acc[ai][bj][m][n] = __builtin_amdgcn_mfma_f32_16x16x32_bf16(Bt[n][k], At[m][k], acc[ai][bj][m][n], 0, 0, 0); __builtin_amdgcn_s_setprio(0); } while (0)
; #define PG8_WAIT_V(n) asm volatile("s_waitcnt vmcnt(" #n ")" ::: "memory")
; #define PG8_WAIT_L(n) asm volatile("s_waitcnt lgkmcnt(" #n ")" ::: "memory")
; #define PG8_BAR __builtin_amdgcn_s_barrier()
; #define PG8_SCHED __builtin_amdgcn_sched_barrier(0)
; template <class Epi>
; __device__ __forceinline__ void gemm_phase(PG8_LAS unsigned char* lds, const Gemm g, const StaticOrder& S, const Epi& E) {
;     ...
;       PG8_WAIT_L(8); PG8_BAR; PG8_WAIT_L(0); PG8_MMA(0, 0, At, B0); PG8_BAR; PG8_SCHED;
;       PG8_LDB(B1, 1, 1); PG8_STAGE(PG8_SB(1, 0), b3, voffB);
;       PG8_BAR; PG8_WAIT_L(0); PG8_MMA(0, 1, At, B1); PG8_BAR;
;       PG8_LDA(At, 1, 1); PG8_STAGE(PG8_SA(1, 0), a3, voffA);
;       PG8_BAR; PG8_WAIT_L(0); PG8_MMA(1, 0, At, B0); PG8_BAR; PG8_SCHED;
;       PG8_STAGE(PG8_SB(1, 1), b3 + hstep, voffB);
;       PG8_WAIT_V(6); PG8_BAR; PG8_MMA(1, 1, At, B1); PG8_BAR;
	s_waitcnt lgkmcnt(0)
	s_waitcnt lgkmcnt(0)
	v_mfma_f32_16x16x32_bf16 v[126:129], v[154:157], v[196:199], v[126:129]
	v_mfma_f32_16x16x32_bf16 v[122:125], v[188:191], v[196:199], v[122:125]
	v_mfma_f32_16x16x32_bf16 v[110:113], v[154:157], v[204:207], v[110:113]
	v_mfma_f32_16x16x32_bf16 v[106:109], v[188:191], v[204:207], v[106:109]
	v_mfma_f32_16x16x32_bf16 v[94:97], v[154:157], v[212:215], v[94:97]
	v_mfma_f32_16x16x32_bf16 v[90:93], v[188:191], v[212:215], v[90:93]
	v_mfma_f32_16x16x32_bf16 v[78:81], v[154:157], v[220:223], v[78:81]
	v_mfma_f32_16x16x32_bf16 v[74:77], v[188:191], v[220:223], v[74:77]
	v_mfma_f32_16x16x32_bf16 v[126:129], v[158:161], v[200:203], v[126:129]
	v_mfma_f32_16x16x32_bf16 v[122:125], v[192:195], v[200:203], v[122:125]
	v_mfma_f32_16x16x32_bf16 v[110:113], v[158:161], v[208:211], v[110:113]
	v_mfma_f32_16x16x32_bf16 v[106:109], v[192:195], v[208:211], v[106:109]
	v_mfma_f32_16x16x32_bf16 v[94:97], v[158:161], v[216:219], v[94:97]
	v_mfma_f32_16x16x32_bf16 v[90:93], v[192:195], v[216:219], v[90:93]
	v_mfma_f32_16x16x32_bf16 v[78:81], v[158:161], v[224:227], v[78:81]
	v_mfma_f32_16x16x32_bf16 v[74:77], v[192:195], v[224:227], v[74:77]
	s_barrier
	s_add_i32 s50, 0, 0x1c000
	s_add_i32 s51, s64, s28
	v_add_u32_e32 v167, s50, v164
	v_lshl_add_u64 v[162:163], v[162:163], 0, s[4:5]
	s_mov_b32 m0, s51
	ds_read_b128 v[228:231], v167
	ds_read_b128 v[232:235], v167 offset:1024
	ds_read_b128 v[236:239], v167 offset:2048
	ds_read_b128 v[240:243], v167 offset:3072
	global_load_lds_dwordx4 v[162:163], off
	v_lshl_add_u64 v[162:163], v[178:179], 0, s[4:5]
	s_add_i32 m0, s51, 0x2000
	s_nop 0
	global_load_lds_dwordx4 v[162:163], off
	s_barrier
	s_waitcnt lgkmcnt(0)
	s_waitcnt lgkmcnt(0)
	v_mfma_f32_16x16x32_bf16 v[118:121], v[228:231], v[196:199], v[118:121]
	v_mfma_f32_16x16x32_bf16 v[114:117], v[236:239], v[196:199], v[114:117]
	v_mfma_f32_16x16x32_bf16 v[102:105], v[228:231], v[204:207], v[102:105]
	v_mfma_f32_16x16x32_bf16 v[98:101], v[236:239], v[204:207], v[98:101]
	v_mfma_f32_16x16x32_bf16 v[86:89], v[228:231], v[212:215], v[86:89]
	v_mfma_f32_16x16x32_bf16 v[82:85], v[236:239], v[212:215], v[82:85]
	v_mfma_f32_16x16x32_bf16 v[70:73], v[228:231], v[220:223], v[70:73]
	v_mfma_f32_16x16x32_bf16 v[66:69], v[236:239], v[220:223], v[66:69]
	v_mfma_f32_16x16x32_bf16 v[118:121], v[232:235], v[200:203], v[118:121]
	v_mfma_f32_16x16x32_bf16 v[114:117], v[240:243], v[200:203], v[114:117]
	v_mfma_f32_16x16x32_bf16 v[102:105], v[232:235], v[208:211], v[102:105]
	v_mfma_f32_16x16x32_bf16 v[98:101], v[240:243], v[208:211], v[98:101]
	v_mfma_f32_16x16x32_bf16 v[86:89], v[232:235], v[216:219], v[86:89]
	v_mfma_f32_16x16x32_bf16 v[82:85], v[240:243], v[216:219], v[82:85]
	v_mfma_f32_16x16x32_bf16 v[70:73], v[232:235], v[224:227], v[70:73]
	v_mfma_f32_16x16x32_bf16 v[66:69], v[240:243], v[224:227], v[66:69]
	s_mov_b32 m0, s56
	v_lshl_add_u64 v[162:163], v[244:245], 0, s[4:5]
	s_barrier
	ds_read_b128 v[196:199], v166 offset:49152
	ds_read_b128 v[200:203], v166 offset:50176
	ds_read_b128 v[204:207], v166 offset:51200
	ds_read_b128 v[208:211], v166 offset:52224
	ds_read_b128 v[212:215], v166 offset:53248
	ds_read_b128 v[216:219], v166 offset:54272
	ds_read_b128 v[220:223], v166 offset:55296
	ds_read_b128 v[224:227], v166 offset:56320
	global_load_lds_dwordx4 v[162:163], off
	v_lshl_add_u64 v[162:163], v[246:247], 0, s[4:5]
	s_mov_b32 m0, s57
	s_nop 0
	global_load_lds_dwordx4 v[162:163], off
	s_barrier
	s_waitcnt lgkmcnt(0)
	s_waitcnt lgkmcnt(0)
	v_mfma_f32_16x16x32_bf16 v[62:65], v[154:157], v[196:199], v[62:65]
	v_mfma_f32_16x16x32_bf16 v[58:61], v[188:191], v[196:199], v[58:61]
	v_mfma_f32_16x16x32_bf16 v[46:49], v[154:157], v[204:207], v[46:49]
	v_mfma_f32_16x16x32_bf16 v[42:45], v[188:191], v[204:207], v[42:45]
	v_mfma_f32_16x16x32_bf16 v[30:33], v[154:157], v[212:215], v[30:33]
	v_mfma_f32_16x16x32_bf16 v[26:29], v[188:191], v[212:215], v[26:29]
	v_mfma_f32_16x16x32_bf16 v[14:17], v[154:157], v[220:223], v[14:17]
	v_mfma_f32_16x16x32_bf16 v[10:13], v[188:191], v[220:223], v[10:13]
	v_mfma_f32_16x16x32_bf16 v[62:65], v[158:161], v[200:203], v[62:65]
	v_mfma_f32_16x16x32_bf16 v[58:61], v[192:195], v[200:203], v[58:61]
	v_mfma_f32_16x16x32_bf16 v[46:49], v[158:161], v[208:211], v[46:49]
	v_mfma_f32_16x16x32_bf16 v[42:45], v[192:195], v[208:211], v[42:45]
	v_mfma_f32_16x16x32_bf16 v[30:33], v[158:161], v[216:219], v[30:33]
	v_mfma_f32_16x16x32_bf16 v[26:29], v[192:195], v[216:219], v[26:29]
	v_mfma_f32_16x16x32_bf16 v[14:17], v[158:161], v[224:227], v[14:17]
	v_mfma_f32_16x16x32_bf16 v[10:13], v[192:195], v[224:227], v[10:13]
	s_barrier
	s_add_u32 s10, s10, 0x40080
	s_addc_u32 s11, s11, 0
	s_add_i32 s50, s50, s28
	v_lshl_add_u64 v[154:155], s[10:11], 0, v[0:1]
	s_mov_b32 m0, s50
	s_nop 0
	global_load_lds_dwordx4 v[154:155], off
	v_lshl_add_u64 v[154:155], s[10:11], 0, v[148:149]
	s_add_i32 m0, s50, 0x2000
	s_nop 0
	global_load_lds_dwordx4 v[154:155], off
	s_waitcnt vmcnt(6)
	s_barrier
	v_mfma_f32_16x16x32_bf16 v[54:57], v[228:231], v[196:199], v[54:57]
	v_mfma_f32_16x16x32_bf16 v[50:53], v[236:239], v[196:199], v[50:53]
	v_mfma_f32_16x16x32_bf16 v[38:41], v[228:231], v[204:207], v[38:41]
	v_mfma_f32_16x16x32_bf16 v[34:37], v[236:239], v[204:207], v[34:37]
	v_mfma_f32_16x16x32_bf16 v[22:25], v[228:231], v[212:215], v[22:25]
	v_mfma_f32_16x16x32_bf16 v[18:21], v[236:239], v[212:215], v[18:21]
	v_mfma_f32_16x16x32_bf16 v[6:9], v[228:231], v[220:223], v[6:9]
	v_mfma_f32_16x16x32_bf16 v[2:5], v[236:239], v[220:223], v[2:5]
	v_mfma_f32_16x16x32_bf16 v[54:57], v[232:235], v[200:203], v[54:57]
	v_mfma_f32_16x16x32_bf16 v[50:53], v[240:243], v[200:203], v[50:53]
	v_mfma_f32_16x16x32_bf16 v[38:41], v[232:235], v[208:211], v[38:41]
	v_mfma_f32_16x16x32_bf16 v[34:37], v[240:243], v[208:211], v[34:37]
	v_mfma_f32_16x16x32_bf16 v[22:25], v[232:235], v[216:219], v[22:25]
	v_mfma_f32_16x16x32_bf16 v[18:21], v[240:243], v[216:219], v[18:21]
	v_mfma_f32_16x16x32_bf16 v[6:9], v[232:235], v[224:227], v[6:9]
	v_mfma_f32_16x16x32_bf16 v[2:5], v[240:243], v[224:227], v[2:5]
	s_add_i32 s63, s63, 2
	s_add_u32 s8, s8, 0x100
	s_addc_u32 s9, s9, 0
	s_add_u32 s61, s61, 0x100
	s_addc_u32 s62, s62, 0
	s_cmp_gt_u32 s63, 13
	s_barrier
;   __device__ __forceinline__ void operator()(const f32x4 (&acc)[2][2][4][2], const pg8::Unit& u, int wr, int wc, int fr, int fq) const {
; #pragma unroll
;     for (int ai = 0; ai < 2; ++ai)
; #pragma unroll
;       for (int m = 0; m < 4; ++m) { const int row = u.pm * 256 + ai * 128 + wr * 64 + m * 16 + fr;
; #pragma unroll
;         for (int bj = 0; bj < 2; ++bj)
; #pragma unroll
;           for (int n = 0; n < 2; ++n) f(row, u.pn * 256 + bj * 128 + wc * 32 + n * 16 + 4 * fq, acc[ai][bj][m][n]); }
	s_cbranch_scc0 .LBB0_1123
	v_bfe_u32 v154, v168, 4, 1
	v_mul_u32_u24_e32 v154, 24, v154
	v_lshl_add_u32 v154, v165, 1, v154
	v_lshl_add_u32 v154, v147, 12, v154
	v_lshlrev_b32_e32 v155, 5, v147
	v_lshl_or_b32 v160, s6, 8, v165
	v_lshlrev_b32_e32 v162, 2, v160
	v_mov_b32_e32 v163, 0
	v_lshl_add_u64 v[162:163], v[162:163], 0, s[30:31]
	global_load_dwordx4 v[228:231], v[162:163], off
	global_load_dwordx4 v[232:235], v[162:163], off offset:64
	global_load_dwordx4 v[236:239], v[162:163], off offset:512
	global_load_dwordx4 v[240:243], v[162:163], off offset:576
	v_readlane_b32 s50, v251, 37
	v_readlane_b32 s51, v251, 38
	s_lshl_b32 s8, s7, 13
	s_lshl_b32 s9, s6, 2
	s_add_i32 s8, s8, s9
	s_add_u32 s50, s50, s8
	s_addc_u32 s51, s51, 0
	s_lshl_b32 s8, s7, 20
	s_lshl_b32 s9, s6, 9
	s_add_i32 s8, s8, s9
	s_add_u32 s8, s90, s8
	s_addc_u32 s9, s91, 0
	s_mov_b64 s[10:11], s[8:9]
	s_mov_b32 s6, s42
	s_mov_b32 s7, s44
	global_load_dword v188, v155, s[50:51]
	global_load_dwordx4 v[190:193], v154, s[8:9]
	global_load_dwordx4 v[194:197], v154, s[8:9] offset:256
	s_add_u32 s50, s50, 512
	s_addc_u32 s51, s51, 0
	s_add_u32 s8, s8, 0x10000
	s_addc_u32 s9, s9, 0
	global_load_dword v198, v155, s[50:51]
	global_load_dwordx4 v[200:203], v154, s[8:9]
	global_load_dwordx4 v[204:207], v154, s[8:9] offset:256
	s_add_u32 s50, s50, 512
	s_addc_u32 s51, s51, 0
	s_add_u32 s8, s8, 0x10000
	s_addc_u32 s9, s9, 0
	s_waitcnt vmcnt(3)
	v_mul_f32_e32 v208, 0xbfb8aa3b, v126
	v_mul_f32_e32 v209, 0xbfb8aa3b, v127
	v_mul_f32_e32 v210, 0xbfb8aa3b, v128
	v_mul_f32_e32 v211, 0xbfb8aa3b, v129
	v_exp_f32_e32 v208, v208
	v_exp_f32_e32 v209, v209
	v_exp_f32_e32 v210, v210
	v_exp_f32_e32 v211, v211
	v_add_f32_e32 v208, 1.0, v208
	v_add_f32_e32 v209, 1.0, v209
	v_add_f32_e32 v210, 1.0, v210
	v_add_f32_e32 v211, 1.0, v211
	v_rcp_f32_e32 v208, v208
	v_rcp_f32_e32 v209, v209
	v_rcp_f32_e32 v210, v210
	v_rcp_f32_e32 v211, v211
	v_pk_mul_f32 v[126:127], v[126:127], v[208:209]
	v_pk_mul_f32 v[128:129], v[128:129], v[210:211]
	v_pk_mul_f32 v[126:127], v[126:127], v[228:229]
	v_pk_mul_f32 v[128:129], v[128:129], v[230:231]
	v_pk_mul_f32 v[126:127], v[188:189], v[126:127] op_sel_hi:[0,1]
	v_pk_mul_f32 v[128:129], v[188:189], v[128:129] op_sel_hi:[0,1]
	v_mul_f32_e32 v208, 0xbfb8aa3b, v122
	v_mul_f32_e32 v209, 0xbfb8aa3b, v123
	v_mul_f32_e32 v210, 0xbfb8aa3b, v124
	v_mul_f32_e32 v211, 0xbfb8aa3b, v125
	v_exp_f32_e32 v208, v208
	v_exp_f32_e32 v209, v209
	v_exp_f32_e32 v210, v210
	v_exp_f32_e32 v211, v211
	v_add_f32_e32 v208, 1.0, v208
	v_add_f32_e32 v209, 1.0, v209
	v_add_f32_e32 v210, 1.0, v210
	v_add_f32_e32 v211, 1.0, v211
	v_rcp_f32_e32 v208, v208
	v_rcp_f32_e32 v209, v209
	v_rcp_f32_e32 v210, v210
	v_rcp_f32_e32 v211, v211
	v_pk_mul_f32 v[122:123], v[122:123], v[208:209]
	v_pk_mul_f32 v[124:125], v[124:125], v[210:211]
	v_pk_mul_f32 v[122:123], v[122:123], v[232:233]
	v_pk_mul_f32 v[124:125], v[124:125], v[234:235]
	v_pk_mul_f32 v[122:123], v[188:189], v[122:123] op_sel_hi:[0,1]
	v_pk_mul_f32 v[124:125], v[188:189], v[124:125] op_sel_hi:[0,1]
	v_mul_f32_e32 v208, 0xbfb8aa3b, v118
	v_mul_f32_e32 v209, 0xbfb8aa3b, v119
	v_mul_f32_e32 v210, 0xbfb8aa3b, v120
	v_mul_f32_e32 v211, 0xbfb8aa3b, v121
	v_exp_f32_e32 v208, v208
	v_exp_f32_e32 v209, v209
	v_exp_f32_e32 v210, v210
	v_exp_f32_e32 v211, v211
	v_add_f32_e32 v208, 1.0, v208
	v_add_f32_e32 v209, 1.0, v209
	v_add_f32_e32 v210, 1.0, v210
	v_add_f32_e32 v211, 1.0, v211
	v_rcp_f32_e32 v208, v208
	v_rcp_f32_e32 v209, v209
	v_rcp_f32_e32 v210, v210
	v_rcp_f32_e32 v211, v211
	v_pk_mul_f32 v[118:119], v[118:119], v[208:209]
	v_pk_mul_f32 v[120:121], v[120:121], v[210:211]
	v_pk_mul_f32 v[118:119], v[118:119], v[236:237]
	v_pk_mul_f32 v[120:121], v[120:121], v[238:239]
	v_pk_mul_f32 v[118:119], v[188:189], v[118:119] op_sel_hi:[0,1]
	v_pk_mul_f32 v[120:121], v[188:189], v[120:121] op_sel_hi:[0,1]
	v_mul_f32_e32 v208, 0xbfb8aa3b, v114
	v_mul_f32_e32 v209, 0xbfb8aa3b, v115
	v_mul_f32_e32 v210, 0xbfb8aa3b, v116
	v_mul_f32_e32 v211, 0xbfb8aa3b, v117
	v_exp_f32_e32 v208, v208
	v_exp_f32_e32 v209, v209
	v_exp_f32_e32 v210, v210
	v_exp_f32_e32 v211, v211
	v_add_f32_e32 v208, 1.0, v208
	v_add_f32_e32 v209, 1.0, v209
	v_add_f32_e32 v210, 1.0, v210
	v_add_f32_e32 v211, 1.0, v211
	v_rcp_f32_e32 v208, v208
	v_rcp_f32_e32 v209, v209
	v_rcp_f32_e32 v210, v210
	v_rcp_f32_e32 v211, v211
	v_pk_mul_f32 v[114:115], v[114:115], v[208:209]
	v_pk_mul_f32 v[116:117], v[116:117], v[210:211]
	v_pk_mul_f32 v[114:115], v[114:115], v[240:241]
	v_pk_mul_f32 v[116:117], v[116:117], v[242:243]
	v_pk_mul_f32 v[114:115], v[188:189], v[114:115] op_sel_hi:[0,1]
	v_pk_mul_f32 v[116:117], v[188:189], v[116:117] op_sel_hi:[0,1]
	v_permlane16_swap_b32_e32 v126, v122
	v_permlane16_swap_b32_e32 v127, v123
	v_permlane16_swap_b32_e32 v128, v124
	v_permlane16_swap_b32_e32 v129, v125
	v_lshlrev_b32_e32 v208, 16, v190
	v_and_b32_e32 v209, 0xffff0000, v190
	v_lshlrev_b32_e32 v210, 16, v191
	v_and_b32_e32 v211, 0xffff0000, v191
	v_lshlrev_b32_e32 v212, 16, v192
	v_and_b32_e32 v213, 0xffff0000, v192
	v_lshlrev_b32_e32 v214, 16, v193
	v_and_b32_e32 v215, 0xffff0000, v193
	v_pk_mul_f32 v[208:209], v[208:209], v[126:127]
	v_pk_mul_f32 v[210:211], v[210:211], v[128:129]
	v_pk_mul_f32 v[212:213], v[212:213], v[122:123]
	v_pk_mul_f32 v[214:215], v[214:215], v[124:125]
	v_cvt_pk_bf16_f32 v190, v208, v209
	v_cvt_pk_bf16_f32 v191, v210, v211
	v_cvt_pk_bf16_f32 v192, v212, v213
	v_cvt_pk_bf16_f32 v193, v214, v215
	v_permlane16_swap_b32_e32 v118, v114
	v_permlane16_swap_b32_e32 v119, v115
	v_permlane16_swap_b32_e32 v120, v116
	v_permlane16_swap_b32_e32 v121, v117
	v_lshlrev_b32_e32 v208, 16, v194
	v_and_b32_e32 v209, 0xffff0000, v194
	v_lshlrev_b32_e32 v210, 16, v195
	v_and_b32_e32 v211, 0xffff0000, v195
	v_lshlrev_b32_e32 v212, 16, v196
	v_and_b32_e32 v213, 0xffff0000, v196
	v_lshlrev_b32_e32 v214, 16, v197
	v_and_b32_e32 v215, 0xffff0000, v197
	v_pk_mul_f32 v[208:209], v[208:209], v[118:119]
	v_pk_mul_f32 v[210:211], v[210:211], v[120:121]
	v_pk_mul_f32 v[212:213], v[212:213], v[114:115]
	v_pk_mul_f32 v[214:215], v[214:215], v[116:117]
	v_cvt_pk_bf16_f32 v194, v208, v209
	v_cvt_pk_bf16_f32 v195, v210, v211
	v_cvt_pk_bf16_f32 v196, v212, v213
	v_cvt_pk_bf16_f32 v197, v214, v215
	global_store_dwordx4 v154, v[190:193], s[10:11]
	global_store_dwordx4 v154, v[194:197], s[10:11] offset:256
	s_add_u32 s10, s10, 0x10000
	s_addc_u32 s11, s11, 0
	global_load_dword v118, v155, s[50:51]
	global_load_dwordx4 v[126:129], v154, s[8:9]
	global_load_dwordx4 v[122:125], v154, s[8:9] offset:256
	s_add_u32 s50, s50, 512
	s_addc_u32 s51, s51, 0
	s_add_u32 s8, s8, 0x10000
	s_addc_u32 s9, s9, 0
	s_waitcnt vmcnt(5)
;   __device__ __forceinline__ void operator()(const f32x4 (&acc)[2][2][4][2], const pg8::Unit& u, int wr, int wc, int fr, int fq) const {
; #pragma unroll
;     for (int ai = 0; ai < 2; ++ai)
; #pragma unroll
;       for (int m = 0; m < 4; ++m) { const int row = u.pm * 256 + ai * 128 + wr * 64 + m * 16 + fr;
; #pragma unroll
;         for (int bj = 0; bj < 2; ++bj)
; #pragma unroll
;           for (int n = 0; n < 2; ++n) f(row, u.pn * 256 + bj * 128 + wc * 32 + n * 16 + 4 * fq, acc[ai][bj][m][n]); }
	v_mul_f32_e32 v208, 0xbfb8aa3b, v110
	v_mul_f32_e32 v209, 0xbfb8aa3b, v111
	v_mul_f32_e32 v210, 0xbfb8aa3b, v112
	v_mul_f32_e32 v211, 0xbfb8aa3b, v113
	v_exp_f32_e32 v208, v208
	v_exp_f32_e32 v209, v209
	v_exp_f32_e32 v210, v210
	v_exp_f32_e32 v211, v211
	v_add_f32_e32 v208, 1.0, v208
	v_add_f32_e32 v209, 1.0, v209
	v_add_f32_e32 v210, 1.0, v210
	v_add_f32_e32 v211, 1.0, v211
	v_rcp_f32_e32 v208, v208
	v_rcp_f32_e32 v209, v209
	v_rcp_f32_e32 v210, v210
	v_rcp_f32_e32 v211, v211
	v_pk_mul_f32 v[110:111], v[110:111], v[208:209]
	v_pk_mul_f32 v[112:113], v[112:113], v[210:211]
	v_pk_mul_f32 v[110:111], v[110:111], v[228:229]
	v_pk_mul_f32 v[112:113], v[112:113], v[230:231]
	v_pk_mul_f32 v[110:111], v[198:199], v[110:111] op_sel_hi:[0,1]
	v_pk_mul_f32 v[112:113], v[198:199], v[112:113] op_sel_hi:[0,1]
	v_mul_f32_e32 v208, 0xbfb8aa3b, v106
	v_mul_f32_e32 v209, 0xbfb8aa3b, v107
	v_mul_f32_e32 v210, 0xbfb8aa3b, v108
	v_mul_f32_e32 v211, 0xbfb8aa3b, v109
	v_exp_f32_e32 v208, v208
	v_exp_f32_e32 v209, v209
	v_exp_f32_e32 v210, v210
	v_exp_f32_e32 v211, v211
	v_add_f32_e32 v208, 1.0, v208
	v_add_f32_e32 v209, 1.0, v209
	v_add_f32_e32 v210, 1.0, v210
	v_add_f32_e32 v211, 1.0, v211
	v_rcp_f32_e32 v208, v208
	v_rcp_f32_e32 v209, v209
	v_rcp_f32_e32 v210, v210
	v_rcp_f32_e32 v211, v211
	v_pk_mul_f32 v[106:107], v[106:107], v[208:209]
	v_pk_mul_f32 v[108:109], v[108:109], v[210:211]
	v_pk_mul_f32 v[106:107], v[106:107], v[232:233]
	v_pk_mul_f32 v[108:109], v[108:109], v[234:235]
	v_pk_mul_f32 v[106:107], v[198:199], v[106:107] op_sel_hi:[0,1]
	v_pk_mul_f32 v[108:109], v[198:199], v[108:109] op_sel_hi:[0,1]
	v_mul_f32_e32 v208, 0xbfb8aa3b, v102
	v_mul_f32_e32 v209, 0xbfb8aa3b, v103
	v_mul_f32_e32 v210, 0xbfb8aa3b, v104
	v_mul_f32_e32 v211, 0xbfb8aa3b, v105
	v_exp_f32_e32 v208, v208
	v_exp_f32_e32 v209, v209
	v_exp_f32_e32 v210, v210
	v_exp_f32_e32 v211, v211
	v_add_f32_e32 v208, 1.0, v208
	v_add_f32_e32 v209, 1.0, v209
	v_add_f32_e32 v210, 1.0, v210
	v_add_f32_e32 v211, 1.0, v211
	v_rcp_f32_e32 v208, v208
	v_rcp_f32_e32 v209, v209
	v_rcp_f32_e32 v210, v210
	v_rcp_f32_e32 v211, v211
	v_pk_mul_f32 v[102:103], v[102:103], v[208:209]
	v_pk_mul_f32 v[104:105], v[104:105], v[210:211]
	v_pk_mul_f32 v[102:103], v[102:103], v[236:237]
	v_pk_mul_f32 v[104:105], v[104:105], v[238:239]
	v_pk_mul_f32 v[102:103], v[198:199], v[102:103] op_sel_hi:[0,1]
	v_pk_mul_f32 v[104:105], v[198:199], v[104:105] op_sel_hi:[0,1]
	v_mul_f32_e32 v208, 0xbfb8aa3b, v98
	v_mul_f32_e32 v209, 0xbfb8aa3b, v99
	v_mul_f32_e32 v210, 0xbfb8aa3b, v100
	v_mul_f32_e32 v211, 0xbfb8aa3b, v101
	v_exp_f32_e32 v208, v208
	v_exp_f32_e32 v209, v209
	v_exp_f32_e32 v210, v210
	v_exp_f32_e32 v211, v211
	v_add_f32_e32 v208, 1.0, v208
	v_add_f32_e32 v209, 1.0, v209
	v_add_f32_e32 v210, 1.0, v210
	v_add_f32_e32 v211, 1.0, v211
	v_rcp_f32_e32 v208, v208
	v_rcp_f32_e32 v209, v209
	v_rcp_f32_e32 v210, v210
	v_rcp_f32_e32 v211, v211
	v_pk_mul_f32 v[98:99], v[98:99], v[208:209]
	v_pk_mul_f32 v[100:101], v[100:101], v[210:211]
	v_pk_mul_f32 v[98:99], v[98:99], v[240:241]
	v_pk_mul_f32 v[100:101], v[100:101], v[242:243]
	v_pk_mul_f32 v[98:99], v[198:199], v[98:99] op_sel_hi:[0,1]
	v_pk_mul_f32 v[100:101], v[198:199], v[100:101] op_sel_hi:[0,1]
	v_permlane16_swap_b32_e32 v110, v106
	v_permlane16_swap_b32_e32 v111, v107
	v_permlane16_swap_b32_e32 v112, v108
	v_permlane16_swap_b32_e32 v113, v109
	v_lshlrev_b32_e32 v208, 16, v200
	v_and_b32_e32 v209, 0xffff0000, v200
	v_lshlrev_b32_e32 v210, 16, v201
	v_and_b32_e32 v211, 0xffff0000, v201
	v_lshlrev_b32_e32 v212, 16, v202
	v_and_b32_e32 v213, 0xffff0000, v202
	v_lshlrev_b32_e32 v214, 16, v203
	v_and_b32_e32 v215, 0xffff0000, v203
	v_pk_mul_f32 v[208:209], v[208:209], v[110:111]
	v_pk_mul_f32 v[210:211], v[210:211], v[112:113]
	v_pk_mul_f32 v[212:213], v[212:213], v[106:107]
	v_pk_mul_f32 v[214:215], v[214:215], v[108:109]
	v_cvt_pk_bf16_f32 v200, v208, v209
	v_cvt_pk_bf16_f32 v201, v210, v211
	v_cvt_pk_bf16_f32 v202, v212, v213
	v_cvt_pk_bf16_f32 v203, v214, v215
	v_permlane16_swap_b32_e32 v102, v98
	v_permlane16_swap_b32_e32 v103, v99
	v_permlane16_swap_b32_e32 v104, v100
	v_permlane16_swap_b32_e32 v105, v101
	v_lshlrev_b32_e32 v208, 16, v204
	v_and_b32_e32 v209, 0xffff0000, v204
	v_lshlrev_b32_e32 v210, 16, v205
	v_and_b32_e32 v211, 0xffff0000, v205
	v_lshlrev_b32_e32 v212, 16, v206
	v_and_b32_e32 v213, 0xffff0000, v206
	v_lshlrev_b32_e32 v214, 16, v207
	v_and_b32_e32 v215, 0xffff0000, v207
	v_pk_mul_f32 v[208:209], v[208:209], v[102:103]
	v_pk_mul_f32 v[210:211], v[210:211], v[104:105]
	v_pk_mul_f32 v[212:213], v[212:213], v[98:99]
	v_pk_mul_f32 v[214:215], v[214:215], v[100:101]
	v_cvt_pk_bf16_f32 v204, v208, v209
	v_cvt_pk_bf16_f32 v205, v210, v211
	v_cvt_pk_bf16_f32 v206, v212, v213
	v_cvt_pk_bf16_f32 v207, v214, v215
	global_store_dwordx4 v154, v[200:203], s[10:11]
	global_store_dwordx4 v154, v[204:207], s[10:11] offset:256
	s_add_u32 s10, s10, 0x10000
	s_addc_u32 s11, s11, 0
	global_load_dword v102, v155, s[50:51]
	global_load_dwordx4 v[110:113], v154, s[8:9]
	global_load_dwordx4 v[106:109], v154, s[8:9] offset:256
	s_add_u32 s50, s50, 2560
	s_addc_u32 s51, s51, 0
	s_add_u32 s8, s8, 0x50000
	s_addc_u32 s9, s9, 0
	s_waitcnt vmcnt(5)
;   __device__ __forceinline__ void operator()(const f32x4 (&acc)[2][2][4][2], const pg8::Unit& u, int wr, int wc, int fr, int fq) const {
; #pragma unroll
;     for (int ai = 0; ai < 2; ++ai)
; #pragma unroll
;       for (int m = 0; m < 4; ++m) { const int row = u.pm * 256 + ai * 128 + wr * 64 + m * 16 + fr;
; #pragma unroll
;         for (int bj = 0; bj < 2; ++bj)
; #pragma unroll
;           for (int n = 0; n < 2; ++n) f(row, u.pn * 256 + bj * 128 + wc * 32 + n * 16 + 4 * fq, acc[ai][bj][m][n]); }
	v_mul_f32_e32 v208, 0xbfb8aa3b, v94
	v_mul_f32_e32 v209, 0xbfb8aa3b, v95
	v_mul_f32_e32 v210, 0xbfb8aa3b, v96
	v_mul_f32_e32 v211, 0xbfb8aa3b, v97
	v_exp_f32_e32 v208, v208
	v_exp_f32_e32 v209, v209
	v_exp_f32_e32 v210, v210
	v_exp_f32_e32 v211, v211
	v_add_f32_e32 v208, 1.0, v208
	v_add_f32_e32 v209, 1.0, v209
	v_add_f32_e32 v210, 1.0, v210
	v_add_f32_e32 v211, 1.0, v211
	v_rcp_f32_e32 v208, v208
	v_rcp_f32_e32 v209, v209
	v_rcp_f32_e32 v210, v210
	v_rcp_f32_e32 v211, v211
	v_pk_mul_f32 v[94:95], v[94:95], v[208:209]
	v_pk_mul_f32 v[96:97], v[96:97], v[210:211]
	v_pk_mul_f32 v[94:95], v[94:95], v[228:229]
	v_pk_mul_f32 v[96:97], v[96:97], v[230:231]
	v_pk_mul_f32 v[94:95], v[118:119], v[94:95] op_sel_hi:[0,1]
	v_pk_mul_f32 v[96:97], v[118:119], v[96:97] op_sel_hi:[0,1]
	v_mul_f32_e32 v208, 0xbfb8aa3b, v90
	v_mul_f32_e32 v209, 0xbfb8aa3b, v91
	v_mul_f32_e32 v210, 0xbfb8aa3b, v92
	v_mul_f32_e32 v211, 0xbfb8aa3b, v93
	v_exp_f32_e32 v208, v208
	v_exp_f32_e32 v209, v209
	v_exp_f32_e32 v210, v210
	v_exp_f32_e32 v211, v211
	v_add_f32_e32 v208, 1.0, v208
	v_add_f32_e32 v209, 1.0, v209
	v_add_f32_e32 v210, 1.0, v210
	v_add_f32_e32 v211, 1.0, v211
	v_rcp_f32_e32 v208, v208
	v_rcp_f32_e32 v209, v209
	v_rcp_f32_e32 v210, v210
	v_rcp_f32_e32 v211, v211
	v_pk_mul_f32 v[90:91], v[90:91], v[208:209]
	v_pk_mul_f32 v[92:93], v[92:93], v[210:211]
	v_pk_mul_f32 v[90:91], v[90:91], v[232:233]
	v_pk_mul_f32 v[92:93], v[92:93], v[234:235]
	v_pk_mul_f32 v[90:91], v[118:119], v[90:91] op_sel_hi:[0,1]
	v_pk_mul_f32 v[92:93], v[118:119], v[92:93] op_sel_hi:[0,1]
	v_mul_f32_e32 v208, 0xbfb8aa3b, v86
	v_mul_f32_e32 v209, 0xbfb8aa3b, v87
	v_mul_f32_e32 v210, 0xbfb8aa3b, v88
	v_mul_f32_e32 v211, 0xbfb8aa3b, v89
	v_exp_f32_e32 v208, v208
	v_exp_f32_e32 v209, v209
	v_exp_f32_e32 v210, v210
	v_exp_f32_e32 v211, v211
	v_add_f32_e32 v208, 1.0, v208
	v_add_f32_e32 v209, 1.0, v209
	v_add_f32_e32 v210, 1.0, v210
	v_add_f32_e32 v211, 1.0, v211
	v_rcp_f32_e32 v208, v208
	v_rcp_f32_e32 v209, v209
	v_rcp_f32_e32 v210, v210
	v_rcp_f32_e32 v211, v211
	v_pk_mul_f32 v[86:87], v[86:87], v[208:209]
	v_pk_mul_f32 v[88:89], v[88:89], v[210:211]
	v_pk_mul_f32 v[86:87], v[86:87], v[236:237]
	v_pk_mul_f32 v[88:89], v[88:89], v[238:239]
	v_pk_mul_f32 v[86:87], v[118:119], v[86:87] op_sel_hi:[0,1]
	v_pk_mul_f32 v[88:89], v[118:119], v[88:89] op_sel_hi:[0,1]
	v_mul_f32_e32 v208, 0xbfb8aa3b, v82
	v_mul_f32_e32 v209, 0xbfb8aa3b, v83
	v_mul_f32_e32 v210, 0xbfb8aa3b, v84
	v_mul_f32_e32 v211, 0xbfb8aa3b, v85
	v_exp_f32_e32 v208, v208
	v_exp_f32_e32 v209, v209
	v_exp_f32_e32 v210, v210
	v_exp_f32_e32 v211, v211
	v_add_f32_e32 v208, 1.0, v208
	v_add_f32_e32 v209, 1.0, v209
	v_add_f32_e32 v210, 1.0, v210
	v_add_f32_e32 v211, 1.0, v211
	v_rcp_f32_e32 v208, v208
	v_rcp_f32_e32 v209, v209
	v_rcp_f32_e32 v210, v210
	v_rcp_f32_e32 v211, v211
	v_pk_mul_f32 v[82:83], v[82:83], v[208:209]
	v_pk_mul_f32 v[84:85], v[84:85], v[210:211]
	v_pk_mul_f32 v[82:83], v[82:83], v[240:241]
	v_pk_mul_f32 v[84:85], v[84:85], v[242:243]
	v_pk_mul_f32 v[82:83], v[118:119], v[82:83] op_sel_hi:[0,1]
	v_pk_mul_f32 v[84:85], v[118:119], v[84:85] op_sel_hi:[0,1]
	v_permlane16_swap_b32_e32 v94, v90
	v_permlane16_swap_b32_e32 v95, v91
	v_permlane16_swap_b32_e32 v96, v92
	v_permlane16_swap_b32_e32 v97, v93
	v_lshlrev_b32_e32 v208, 16, v126
	v_and_b32_e32 v209, 0xffff0000, v126
	v_lshlrev_b32_e32 v210, 16, v127
	v_and_b32_e32 v211, 0xffff0000, v127
	v_lshlrev_b32_e32 v212, 16, v128
	v_and_b32_e32 v213, 0xffff0000, v128
	v_lshlrev_b32_e32 v214, 16, v129
	v_and_b32_e32 v215, 0xffff0000, v129
	v_pk_mul_f32 v[208:209], v[208:209], v[94:95]
	v_pk_mul_f32 v[210:211], v[210:211], v[96:97]
	v_pk_mul_f32 v[212:213], v[212:213], v[90:91]
	v_pk_mul_f32 v[214:215], v[214:215], v[92:93]
	v_cvt_pk_bf16_f32 v126, v208, v209
	v_cvt_pk_bf16_f32 v127, v210, v211
	v_cvt_pk_bf16_f32 v128, v212, v213
	v_cvt_pk_bf16_f32 v129, v214, v215
	v_permlane16_swap_b32_e32 v86, v82
	v_permlane16_swap_b32_e32 v87, v83
	v_permlane16_swap_b32_e32 v88, v84
	v_permlane16_swap_b32_e32 v89, v85
	v_lshlrev_b32_e32 v208, 16, v122
	v_and_b32_e32 v209, 0xffff0000, v122
	v_lshlrev_b32_e32 v210, 16, v123
	v_and_b32_e32 v211, 0xffff0000, v123
	v_lshlrev_b32_e32 v212, 16, v124
	v_and_b32_e32 v213, 0xffff0000, v124
	v_lshlrev_b32_e32 v214, 16, v125
	v_and_b32_e32 v215, 0xffff0000, v125
	v_pk_mul_f32 v[208:209], v[208:209], v[86:87]
	v_pk_mul_f32 v[210:211], v[210:211], v[88:89]
	v_pk_mul_f32 v[212:213], v[212:213], v[82:83]
	v_pk_mul_f32 v[214:215], v[214:215], v[84:85]
	v_cvt_pk_bf16_f32 v122, v208, v209
	v_cvt_pk_bf16_f32 v123, v210, v211
	v_cvt_pk_bf16_f32 v124, v212, v213
	v_cvt_pk_bf16_f32 v125, v214, v215
	global_store_dwordx4 v154, v[126:129], s[10:11]
	global_store_dwordx4 v154, v[122:125], s[10:11] offset:256
	s_add_u32 s10, s10, 0x10000
	s_addc_u32 s11, s11, 0
	global_load_dword v86, v155, s[50:51]
	global_load_dwordx4 v[94:97], v154, s[8:9]
	global_load_dwordx4 v[90:93], v154, s[8:9] offset:256
	s_add_u32 s50, s50, 512
	s_addc_u32 s51, s51, 0
	s_add_u32 s8, s8, 0x10000
	s_addc_u32 s9, s9, 0
	s_waitcnt vmcnt(5)
;   __device__ __forceinline__ void operator()(const f32x4 (&acc)[2][2][4][2], const pg8::Unit& u, int wr, int wc, int fr, int fq) const {
; #pragma unroll
;     for (int ai = 0; ai < 2; ++ai)
; #pragma unroll
;       for (int m = 0; m < 4; ++m) { const int row = u.pm * 256 + ai * 128 + wr * 64 + m * 16 + fr;
; #pragma unroll
;         for (int bj = 0; bj < 2; ++bj)
; #pragma unroll
;           for (int n = 0; n < 2; ++n) f(row, u.pn * 256 + bj * 128 + wc * 32 + n * 16 + 4 * fq, acc[ai][bj][m][n]); }
	v_mul_f32_e32 v208, 0xbfb8aa3b, v78
	v_mul_f32_e32 v209, 0xbfb8aa3b, v79
	v_mul_f32_e32 v210, 0xbfb8aa3b, v80
	v_mul_f32_e32 v211, 0xbfb8aa3b, v81
	v_exp_f32_e32 v208, v208
	v_exp_f32_e32 v209, v209
	v_exp_f32_e32 v210, v210
	v_exp_f32_e32 v211, v211
	v_add_f32_e32 v208, 1.0, v208
	v_add_f32_e32 v209, 1.0, v209
	v_add_f32_e32 v210, 1.0, v210
	v_add_f32_e32 v211, 1.0, v211
	v_rcp_f32_e32 v208, v208
	v_rcp_f32_e32 v209, v209
	v_rcp_f32_e32 v210, v210
	v_rcp_f32_e32 v211, v211
	v_pk_mul_f32 v[78:79], v[78:79], v[208:209]
	v_pk_mul_f32 v[80:81], v[80:81], v[210:211]
	v_pk_mul_f32 v[78:79], v[78:79], v[228:229]
	v_pk_mul_f32 v[80:81], v[80:81], v[230:231]
	v_pk_mul_f32 v[78:79], v[102:103], v[78:79] op_sel_hi:[0,1]
	v_pk_mul_f32 v[80:81], v[102:103], v[80:81] op_sel_hi:[0,1]
	v_mul_f32_e32 v208, 0xbfb8aa3b, v74
	v_mul_f32_e32 v209, 0xbfb8aa3b, v75
	v_mul_f32_e32 v210, 0xbfb8aa3b, v76
	v_mul_f32_e32 v211, 0xbfb8aa3b, v77
	v_exp_f32_e32 v208, v208
	v_exp_f32_e32 v209, v209
	v_exp_f32_e32 v210, v210
	v_exp_f32_e32 v211, v211
	v_add_f32_e32 v208, 1.0, v208
	v_add_f32_e32 v209, 1.0, v209
	v_add_f32_e32 v210, 1.0, v210
	v_add_f32_e32 v211, 1.0, v211
	v_rcp_f32_e32 v208, v208
	v_rcp_f32_e32 v209, v209
	v_rcp_f32_e32 v210, v210
	v_rcp_f32_e32 v211, v211
	v_pk_mul_f32 v[74:75], v[74:75], v[208:209]
	v_pk_mul_f32 v[76:77], v[76:77], v[210:211]
	v_pk_mul_f32 v[74:75], v[74:75], v[232:233]
	v_pk_mul_f32 v[76:77], v[76:77], v[234:235]
	v_pk_mul_f32 v[74:75], v[102:103], v[74:75] op_sel_hi:[0,1]
	v_pk_mul_f32 v[76:77], v[102:103], v[76:77] op_sel_hi:[0,1]
	v_mul_f32_e32 v208, 0xbfb8aa3b, v70
	v_mul_f32_e32 v209, 0xbfb8aa3b, v71
	v_mul_f32_e32 v210, 0xbfb8aa3b, v72
	v_mul_f32_e32 v211, 0xbfb8aa3b, v73
	v_exp_f32_e32 v208, v208
	v_exp_f32_e32 v209, v209
	v_exp_f32_e32 v210, v210
	v_exp_f32_e32 v211, v211
	v_add_f32_e32 v208, 1.0, v208
	v_add_f32_e32 v209, 1.0, v209
	v_add_f32_e32 v210, 1.0, v210
	v_add_f32_e32 v211, 1.0, v211
	v_rcp_f32_e32 v208, v208
	v_rcp_f32_e32 v209, v209
	v_rcp_f32_e32 v210, v210
	v_rcp_f32_e32 v211, v211
	v_pk_mul_f32 v[70:71], v[70:71], v[208:209]
	v_pk_mul_f32 v[72:73], v[72:73], v[210:211]
	v_pk_mul_f32 v[70:71], v[70:71], v[236:237]
	v_pk_mul_f32 v[72:73], v[72:73], v[238:239]
	v_pk_mul_f32 v[70:71], v[102:103], v[70:71] op_sel_hi:[0,1]
	v_pk_mul_f32 v[72:73], v[102:103], v[72:73] op_sel_hi:[0,1]
	v_mul_f32_e32 v208, 0xbfb8aa3b, v66
	v_mul_f32_e32 v209, 0xbfb8aa3b, v67
	v_mul_f32_e32 v210, 0xbfb8aa3b, v68
	v_mul_f32_e32 v211, 0xbfb8aa3b, v69
	v_exp_f32_e32 v208, v208
	v_exp_f32_e32 v209, v209
	v_exp_f32_e32 v210, v210
	v_exp_f32_e32 v211, v211
	v_add_f32_e32 v208, 1.0, v208
	v_add_f32_e32 v209, 1.0, v209
	v_add_f32_e32 v210, 1.0, v210
	v_add_f32_e32 v211, 1.0, v211
	v_rcp_f32_e32 v208, v208
	v_rcp_f32_e32 v209, v209
	v_rcp_f32_e32 v210, v210
	v_rcp_f32_e32 v211, v211
	v_pk_mul_f32 v[66:67], v[66:67], v[208:209]
	v_pk_mul_f32 v[68:69], v[68:69], v[210:211]
	v_pk_mul_f32 v[66:67], v[66:67], v[240:241]
	v_pk_mul_f32 v[68:69], v[68:69], v[242:243]
	v_pk_mul_f32 v[66:67], v[102:103], v[66:67] op_sel_hi:[0,1]
	v_pk_mul_f32 v[68:69], v[102:103], v[68:69] op_sel_hi:[0,1]
	v_permlane16_swap_b32_e32 v78, v74
	v_permlane16_swap_b32_e32 v79, v75
	v_permlane16_swap_b32_e32 v80, v76
	v_permlane16_swap_b32_e32 v81, v77
	v_lshlrev_b32_e32 v208, 16, v110
	v_and_b32_e32 v209, 0xffff0000, v110
	v_lshlrev_b32_e32 v210, 16, v111
	v_and_b32_e32 v211, 0xffff0000, v111
	v_lshlrev_b32_e32 v212, 16, v112
	v_and_b32_e32 v213, 0xffff0000, v112
	v_lshlrev_b32_e32 v214, 16, v113
	v_and_b32_e32 v215, 0xffff0000, v113
	v_pk_mul_f32 v[208:209], v[208:209], v[78:79]
	v_pk_mul_f32 v[210:211], v[210:211], v[80:81]
	v_pk_mul_f32 v[212:213], v[212:213], v[74:75]
	v_pk_mul_f32 v[214:215], v[214:215], v[76:77]
	v_cvt_pk_bf16_f32 v110, v208, v209
	v_cvt_pk_bf16_f32 v111, v210, v211
	v_cvt_pk_bf16_f32 v112, v212, v213
	v_cvt_pk_bf16_f32 v113, v214, v215
	v_permlane16_swap_b32_e32 v70, v66
	v_permlane16_swap_b32_e32 v71, v67
	v_permlane16_swap_b32_e32 v72, v68
	v_permlane16_swap_b32_e32 v73, v69
	v_lshlrev_b32_e32 v208, 16, v106
	v_and_b32_e32 v209, 0xffff0000, v106
	v_lshlrev_b32_e32 v210, 16, v107
	v_and_b32_e32 v211, 0xffff0000, v107
	v_lshlrev_b32_e32 v212, 16, v108
	v_and_b32_e32 v213, 0xffff0000, v108
	v_lshlrev_b32_e32 v214, 16, v109
	v_and_b32_e32 v215, 0xffff0000, v109
	v_pk_mul_f32 v[208:209], v[208:209], v[70:71]
	v_pk_mul_f32 v[210:211], v[210:211], v[72:73]
	v_pk_mul_f32 v[212:213], v[212:213], v[66:67]
	v_pk_mul_f32 v[214:215], v[214:215], v[68:69]
	v_cvt_pk_bf16_f32 v106, v208, v209
	v_cvt_pk_bf16_f32 v107, v210, v211
	v_cvt_pk_bf16_f32 v108, v212, v213
	v_cvt_pk_bf16_f32 v109, v214, v215
	global_store_dwordx4 v154, v[110:113], s[10:11]
	global_store_dwordx4 v154, v[106:109], s[10:11] offset:256
	s_add_u32 s10, s10, 0x50000
	s_addc_u32 s11, s11, 0
	global_load_dword v70, v155, s[50:51]
	global_load_dwordx4 v[78:81], v154, s[8:9]
	global_load_dwordx4 v[74:77], v154, s[8:9] offset:256
	s_add_u32 s50, s50, 512
	s_addc_u32 s51, s51, 0
	s_add_u32 s8, s8, 0x10000
	s_addc_u32 s9, s9, 0
	s_waitcnt vmcnt(5)
;   __device__ __forceinline__ void operator()(const f32x4 (&acc)[2][2][4][2], const pg8::Unit& u, int wr, int wc, int fr, int fq) const {
; #pragma unroll
;     for (int ai = 0; ai < 2; ++ai)
; #pragma unroll
;       for (int m = 0; m < 4; ++m) { const int row = u.pm * 256 + ai * 128 + wr * 64 + m * 16 + fr;
; #pragma unroll
;         for (int bj = 0; bj < 2; ++bj)
; #pragma unroll
;           for (int n = 0; n < 2; ++n) f(row, u.pn * 256 + bj * 128 + wc * 32 + n * 16 + 4 * fq, acc[ai][bj][m][n]); }
	v_mul_f32_e32 v208, 0xbfb8aa3b, v62
	v_mul_f32_e32 v209, 0xbfb8aa3b, v63
	v_mul_f32_e32 v210, 0xbfb8aa3b, v64
	v_mul_f32_e32 v211, 0xbfb8aa3b, v65
	v_exp_f32_e32 v208, v208
	v_exp_f32_e32 v209, v209
	v_exp_f32_e32 v210, v210
	v_exp_f32_e32 v211, v211
	v_add_f32_e32 v208, 1.0, v208
	v_add_f32_e32 v209, 1.0, v209
	v_add_f32_e32 v210, 1.0, v210
	v_add_f32_e32 v211, 1.0, v211
	v_rcp_f32_e32 v208, v208
	v_rcp_f32_e32 v209, v209
	v_rcp_f32_e32 v210, v210
	v_rcp_f32_e32 v211, v211
	v_pk_mul_f32 v[62:63], v[62:63], v[208:209]
	v_pk_mul_f32 v[64:65], v[64:65], v[210:211]
	v_pk_mul_f32 v[62:63], v[62:63], v[228:229]
	v_pk_mul_f32 v[64:65], v[64:65], v[230:231]
	v_pk_mul_f32 v[62:63], v[86:87], v[62:63] op_sel_hi:[0,1]
	v_pk_mul_f32 v[64:65], v[86:87], v[64:65] op_sel_hi:[0,1]
	v_mul_f32_e32 v208, 0xbfb8aa3b, v58
	v_mul_f32_e32 v209, 0xbfb8aa3b, v59
	v_mul_f32_e32 v210, 0xbfb8aa3b, v60
	v_mul_f32_e32 v211, 0xbfb8aa3b, v61
	v_exp_f32_e32 v208, v208
	v_exp_f32_e32 v209, v209
	v_exp_f32_e32 v210, v210
	v_exp_f32_e32 v211, v211
	v_add_f32_e32 v208, 1.0, v208
	v_add_f32_e32 v209, 1.0, v209
	v_add_f32_e32 v210, 1.0, v210
	v_add_f32_e32 v211, 1.0, v211
	v_rcp_f32_e32 v208, v208
	v_rcp_f32_e32 v209, v209
	v_rcp_f32_e32 v210, v210
	v_rcp_f32_e32 v211, v211
	v_pk_mul_f32 v[58:59], v[58:59], v[208:209]
	v_pk_mul_f32 v[60:61], v[60:61], v[210:211]
	v_pk_mul_f32 v[58:59], v[58:59], v[232:233]
	v_pk_mul_f32 v[60:61], v[60:61], v[234:235]
	v_pk_mul_f32 v[58:59], v[86:87], v[58:59] op_sel_hi:[0,1]
	v_pk_mul_f32 v[60:61], v[86:87], v[60:61] op_sel_hi:[0,1]
	v_mul_f32_e32 v208, 0xbfb8aa3b, v54
	v_mul_f32_e32 v209, 0xbfb8aa3b, v55
	v_mul_f32_e32 v210, 0xbfb8aa3b, v56
	v_mul_f32_e32 v211, 0xbfb8aa3b, v57
	v_exp_f32_e32 v208, v208
	v_exp_f32_e32 v209, v209
	v_exp_f32_e32 v210, v210
	v_exp_f32_e32 v211, v211
	v_add_f32_e32 v208, 1.0, v208
	v_add_f32_e32 v209, 1.0, v209
	v_add_f32_e32 v210, 1.0, v210
	v_add_f32_e32 v211, 1.0, v211
	v_rcp_f32_e32 v208, v208
	v_rcp_f32_e32 v209, v209
	v_rcp_f32_e32 v210, v210
	v_rcp_f32_e32 v211, v211
	v_pk_mul_f32 v[54:55], v[54:55], v[208:209]
	v_pk_mul_f32 v[56:57], v[56:57], v[210:211]
	v_pk_mul_f32 v[54:55], v[54:55], v[236:237]
	v_pk_mul_f32 v[56:57], v[56:57], v[238:239]
	v_pk_mul_f32 v[54:55], v[86:87], v[54:55] op_sel_hi:[0,1]
	v_pk_mul_f32 v[56:57], v[86:87], v[56:57] op_sel_hi:[0,1]
	v_mul_f32_e32 v208, 0xbfb8aa3b, v50
	v_mul_f32_e32 v209, 0xbfb8aa3b, v51
	v_mul_f32_e32 v210, 0xbfb8aa3b, v52
	v_mul_f32_e32 v211, 0xbfb8aa3b, v53
	v_exp_f32_e32 v208, v208
	v_exp_f32_e32 v209, v209
	v_exp_f32_e32 v210, v210
	v_exp_f32_e32 v211, v211
	v_add_f32_e32 v208, 1.0, v208
	v_add_f32_e32 v209, 1.0, v209
	v_add_f32_e32 v210, 1.0, v210
	v_add_f32_e32 v211, 1.0, v211
	v_rcp_f32_e32 v208, v208
	v_rcp_f32_e32 v209, v209
	v_rcp_f32_e32 v210, v210
	v_rcp_f32_e32 v211, v211
	v_pk_mul_f32 v[50:51], v[50:51], v[208:209]
	v_pk_mul_f32 v[52:53], v[52:53], v[210:211]
	v_pk_mul_f32 v[50:51], v[50:51], v[240:241]
	v_pk_mul_f32 v[52:53], v[52:53], v[242:243]
	v_pk_mul_f32 v[50:51], v[86:87], v[50:51] op_sel_hi:[0,1]
	v_pk_mul_f32 v[52:53], v[86:87], v[52:53] op_sel_hi:[0,1]
	v_permlane16_swap_b32_e32 v62, v58
	v_permlane16_swap_b32_e32 v63, v59
	v_permlane16_swap_b32_e32 v64, v60
	v_permlane16_swap_b32_e32 v65, v61
	v_lshlrev_b32_e32 v208, 16, v94
	v_and_b32_e32 v209, 0xffff0000, v94
	v_lshlrev_b32_e32 v210, 16, v95
	v_and_b32_e32 v211, 0xffff0000, v95
	v_lshlrev_b32_e32 v212, 16, v96
	v_and_b32_e32 v213, 0xffff0000, v96
	v_lshlrev_b32_e32 v214, 16, v97
	v_and_b32_e32 v215, 0xffff0000, v97
	v_pk_mul_f32 v[208:209], v[208:209], v[62:63]
	v_pk_mul_f32 v[210:211], v[210:211], v[64:65]
	v_pk_mul_f32 v[212:213], v[212:213], v[58:59]
	v_pk_mul_f32 v[214:215], v[214:215], v[60:61]
	v_cvt_pk_bf16_f32 v94, v208, v209
	v_cvt_pk_bf16_f32 v95, v210, v211
	v_cvt_pk_bf16_f32 v96, v212, v213
	v_cvt_pk_bf16_f32 v97, v214, v215
	v_permlane16_swap_b32_e32 v54, v50
	v_permlane16_swap_b32_e32 v55, v51
	v_permlane16_swap_b32_e32 v56, v52
	v_permlane16_swap_b32_e32 v57, v53
	v_lshlrev_b32_e32 v208, 16, v90
	v_and_b32_e32 v209, 0xffff0000, v90
	v_lshlrev_b32_e32 v210, 16, v91
	v_and_b32_e32 v211, 0xffff0000, v91
	v_lshlrev_b32_e32 v212, 16, v92
	v_and_b32_e32 v213, 0xffff0000, v92
	v_lshlrev_b32_e32 v214, 16, v93
	v_and_b32_e32 v215, 0xffff0000, v93
	v_pk_mul_f32 v[208:209], v[208:209], v[54:55]
	v_pk_mul_f32 v[210:211], v[210:211], v[56:57]
	v_pk_mul_f32 v[212:213], v[212:213], v[50:51]
	v_pk_mul_f32 v[214:215], v[214:215], v[52:53]
	v_cvt_pk_bf16_f32 v90, v208, v209
	v_cvt_pk_bf16_f32 v91, v210, v211
	v_cvt_pk_bf16_f32 v92, v212, v213
	v_cvt_pk_bf16_f32 v93, v214, v215
	global_store_dwordx4 v154, v[94:97], s[10:11]
	global_store_dwordx4 v154, v[90:93], s[10:11] offset:256
	s_add_u32 s10, s10, 0x10000
	s_addc_u32 s11, s11, 0
	global_load_dword v54, v155, s[50:51]
	global_load_dwordx4 v[62:65], v154, s[8:9]
	global_load_dwordx4 v[58:61], v154, s[8:9] offset:256
	s_add_u32 s50, s50, 512
	s_addc_u32 s51, s51, 0
	s_add_u32 s8, s8, 0x10000
	s_addc_u32 s9, s9, 0
	s_waitcnt vmcnt(5)
;   __device__ __forceinline__ void operator()(const f32x4 (&acc)[2][2][4][2], const pg8::Unit& u, int wr, int wc, int fr, int fq) const {
; #pragma unroll
;     for (int ai = 0; ai < 2; ++ai)
; #pragma unroll
;       for (int m = 0; m < 4; ++m) { const int row = u.pm * 256 + ai * 128 + wr * 64 + m * 16 + fr;
; #pragma unroll
;         for (int bj = 0; bj < 2; ++bj)
; #pragma unroll
;           for (int n = 0; n < 2; ++n) f(row, u.pn * 256 + bj * 128 + wc * 32 + n * 16 + 4 * fq, acc[ai][bj][m][n]); }
	v_mul_f32_e32 v208, 0xbfb8aa3b, v46
	v_mul_f32_e32 v209, 0xbfb8aa3b, v47
	v_mul_f32_e32 v210, 0xbfb8aa3b, v48
	v_mul_f32_e32 v211, 0xbfb8aa3b, v49
	v_exp_f32_e32 v208, v208
	v_exp_f32_e32 v209, v209
	v_exp_f32_e32 v210, v210
	v_exp_f32_e32 v211, v211
	v_add_f32_e32 v208, 1.0, v208
	v_add_f32_e32 v209, 1.0, v209
	v_add_f32_e32 v210, 1.0, v210
	v_add_f32_e32 v211, 1.0, v211
	v_rcp_f32_e32 v208, v208
	v_rcp_f32_e32 v209, v209
	v_rcp_f32_e32 v210, v210
	v_rcp_f32_e32 v211, v211
	v_pk_mul_f32 v[46:47], v[46:47], v[208:209]
	v_pk_mul_f32 v[48:49], v[48:49], v[210:211]
	v_pk_mul_f32 v[46:47], v[46:47], v[228:229]
	v_pk_mul_f32 v[48:49], v[48:49], v[230:231]
	v_pk_mul_f32 v[46:47], v[70:71], v[46:47] op_sel_hi:[0,1]
	v_pk_mul_f32 v[48:49], v[70:71], v[48:49] op_sel_hi:[0,1]
	v_mul_f32_e32 v208, 0xbfb8aa3b, v42
	v_mul_f32_e32 v209, 0xbfb8aa3b, v43
	v_mul_f32_e32 v210, 0xbfb8aa3b, v44
	v_mul_f32_e32 v211, 0xbfb8aa3b, v45
	v_exp_f32_e32 v208, v208
	v_exp_f32_e32 v209, v209
	v_exp_f32_e32 v210, v210
	v_exp_f32_e32 v211, v211
	v_add_f32_e32 v208, 1.0, v208
	v_add_f32_e32 v209, 1.0, v209
	v_add_f32_e32 v210, 1.0, v210
	v_add_f32_e32 v211, 1.0, v211
	v_rcp_f32_e32 v208, v208
	v_rcp_f32_e32 v209, v209
	v_rcp_f32_e32 v210, v210
	v_rcp_f32_e32 v211, v211
	v_pk_mul_f32 v[42:43], v[42:43], v[208:209]
	v_pk_mul_f32 v[44:45], v[44:45], v[210:211]
	v_pk_mul_f32 v[42:43], v[42:43], v[232:233]
	v_pk_mul_f32 v[44:45], v[44:45], v[234:235]
	v_pk_mul_f32 v[42:43], v[70:71], v[42:43] op_sel_hi:[0,1]
	v_pk_mul_f32 v[44:45], v[70:71], v[44:45] op_sel_hi:[0,1]
	v_mul_f32_e32 v208, 0xbfb8aa3b, v38
	v_mul_f32_e32 v209, 0xbfb8aa3b, v39
	v_mul_f32_e32 v210, 0xbfb8aa3b, v40
	v_mul_f32_e32 v211, 0xbfb8aa3b, v41
	v_exp_f32_e32 v208, v208
	v_exp_f32_e32 v209, v209
	v_exp_f32_e32 v210, v210
	v_exp_f32_e32 v211, v211
	v_add_f32_e32 v208, 1.0, v208
	v_add_f32_e32 v209, 1.0, v209
	v_add_f32_e32 v210, 1.0, v210
	v_add_f32_e32 v211, 1.0, v211
	v_rcp_f32_e32 v208, v208
	v_rcp_f32_e32 v209, v209
	v_rcp_f32_e32 v210, v210
	v_rcp_f32_e32 v211, v211
	v_pk_mul_f32 v[38:39], v[38:39], v[208:209]
	v_pk_mul_f32 v[40:41], v[40:41], v[210:211]
	v_pk_mul_f32 v[38:39], v[38:39], v[236:237]
	v_pk_mul_f32 v[40:41], v[40:41], v[238:239]
	v_pk_mul_f32 v[38:39], v[70:71], v[38:39] op_sel_hi:[0,1]
	v_pk_mul_f32 v[40:41], v[70:71], v[40:41] op_sel_hi:[0,1]
	v_mul_f32_e32 v208, 0xbfb8aa3b, v34
	v_mul_f32_e32 v209, 0xbfb8aa3b, v35
	v_mul_f32_e32 v210, 0xbfb8aa3b, v36
	v_mul_f32_e32 v211, 0xbfb8aa3b, v37
	v_exp_f32_e32 v208, v208
	v_exp_f32_e32 v209, v209
	v_exp_f32_e32 v210, v210
	v_exp_f32_e32 v211, v211
	v_add_f32_e32 v208, 1.0, v208
	v_add_f32_e32 v209, 1.0, v209
	v_add_f32_e32 v210, 1.0, v210
	v_add_f32_e32 v211, 1.0, v211
	v_rcp_f32_e32 v208, v208
	v_rcp_f32_e32 v209, v209
	v_rcp_f32_e32 v210, v210
	v_rcp_f32_e32 v211, v211
	v_pk_mul_f32 v[34:35], v[34:35], v[208:209]
	v_pk_mul_f32 v[36:37], v[36:37], v[210:211]
	v_pk_mul_f32 v[34:35], v[34:35], v[240:241]
	v_pk_mul_f32 v[36:37], v[36:37], v[242:243]
	v_pk_mul_f32 v[34:35], v[70:71], v[34:35] op_sel_hi:[0,1]
	v_pk_mul_f32 v[36:37], v[70:71], v[36:37] op_sel_hi:[0,1]
	v_permlane16_swap_b32_e32 v46, v42
	v_permlane16_swap_b32_e32 v47, v43
	v_permlane16_swap_b32_e32 v48, v44
	v_permlane16_swap_b32_e32 v49, v45
	v_lshlrev_b32_e32 v208, 16, v78
	v_and_b32_e32 v209, 0xffff0000, v78
	v_lshlrev_b32_e32 v210, 16, v79
	v_and_b32_e32 v211, 0xffff0000, v79
	v_lshlrev_b32_e32 v212, 16, v80
	v_and_b32_e32 v213, 0xffff0000, v80
	v_lshlrev_b32_e32 v214, 16, v81
	v_and_b32_e32 v215, 0xffff0000, v81
	v_pk_mul_f32 v[208:209], v[208:209], v[46:47]
	v_pk_mul_f32 v[210:211], v[210:211], v[48:49]
	v_pk_mul_f32 v[212:213], v[212:213], v[42:43]
	v_pk_mul_f32 v[214:215], v[214:215], v[44:45]
	v_cvt_pk_bf16_f32 v78, v208, v209
	v_cvt_pk_bf16_f32 v79, v210, v211
	v_cvt_pk_bf16_f32 v80, v212, v213
	v_cvt_pk_bf16_f32 v81, v214, v215
	v_permlane16_swap_b32_e32 v38, v34
	v_permlane16_swap_b32_e32 v39, v35
	v_permlane16_swap_b32_e32 v40, v36
	v_permlane16_swap_b32_e32 v41, v37
	v_lshlrev_b32_e32 v208, 16, v74
	v_and_b32_e32 v209, 0xffff0000, v74
	v_lshlrev_b32_e32 v210, 16, v75
	v_and_b32_e32 v211, 0xffff0000, v75
	v_lshlrev_b32_e32 v212, 16, v76
	v_and_b32_e32 v213, 0xffff0000, v76
	v_lshlrev_b32_e32 v214, 16, v77
	v_and_b32_e32 v215, 0xffff0000, v77
	v_pk_mul_f32 v[208:209], v[208:209], v[38:39]
	v_pk_mul_f32 v[210:211], v[210:211], v[40:41]
	v_pk_mul_f32 v[212:213], v[212:213], v[34:35]
	v_pk_mul_f32 v[214:215], v[214:215], v[36:37]
	v_cvt_pk_bf16_f32 v74, v208, v209
	v_cvt_pk_bf16_f32 v75, v210, v211
	v_cvt_pk_bf16_f32 v76, v212, v213
	v_cvt_pk_bf16_f32 v77, v214, v215
	global_store_dwordx4 v154, v[78:81], s[10:11]
	global_store_dwordx4 v154, v[74:77], s[10:11] offset:256
	s_add_u32 s10, s10, 0x10000
	s_addc_u32 s11, s11, 0
	global_load_dword v38, v155, s[50:51]
	global_load_dwordx4 v[46:49], v154, s[8:9]
	global_load_dwordx4 v[42:45], v154, s[8:9] offset:256
	s_waitcnt vmcnt(5)
;   __device__ __forceinline__ void operator()(const f32x4 (&acc)[2][2][4][2], const pg8::Unit& u, int wr, int wc, int fr, int fq) const {
; #pragma unroll
;     for (int ai = 0; ai < 2; ++ai)
; #pragma unroll
;       for (int m = 0; m < 4; ++m) { const int row = u.pm * 256 + ai * 128 + wr * 64 + m * 16 + fr;
; #pragma unroll
;         for (int bj = 0; bj < 2; ++bj)
; #pragma unroll
;           for (int n = 0; n < 2; ++n) f(row, u.pn * 256 + bj * 128 + wc * 32 + n * 16 + 4 * fq, acc[ai][bj][m][n]); }
	v_mul_f32_e32 v208, 0xbfb8aa3b, v30
	v_mul_f32_e32 v209, 0xbfb8aa3b, v31
	v_mul_f32_e32 v210, 0xbfb8aa3b, v32
	v_mul_f32_e32 v211, 0xbfb8aa3b, v33
	v_exp_f32_e32 v208, v208
	v_exp_f32_e32 v209, v209
	v_exp_f32_e32 v210, v210
	v_exp_f32_e32 v211, v211
	v_add_f32_e32 v208, 1.0, v208
	v_add_f32_e32 v209, 1.0, v209
	v_add_f32_e32 v210, 1.0, v210
	v_add_f32_e32 v211, 1.0, v211
	v_rcp_f32_e32 v208, v208
	v_rcp_f32_e32 v209, v209
	v_rcp_f32_e32 v210, v210
	v_rcp_f32_e32 v211, v211
	v_pk_mul_f32 v[30:31], v[30:31], v[208:209]
	v_pk_mul_f32 v[32:33], v[32:33], v[210:211]
	v_pk_mul_f32 v[30:31], v[30:31], v[228:229]
	v_pk_mul_f32 v[32:33], v[32:33], v[230:231]
	v_pk_mul_f32 v[30:31], v[54:55], v[30:31] op_sel_hi:[0,1]
	v_pk_mul_f32 v[32:33], v[54:55], v[32:33] op_sel_hi:[0,1]
	v_mul_f32_e32 v208, 0xbfb8aa3b, v26
	v_mul_f32_e32 v209, 0xbfb8aa3b, v27
	v_mul_f32_e32 v210, 0xbfb8aa3b, v28
	v_mul_f32_e32 v211, 0xbfb8aa3b, v29
	v_exp_f32_e32 v208, v208
	v_exp_f32_e32 v209, v209
	v_exp_f32_e32 v210, v210
	v_exp_f32_e32 v211, v211
	v_add_f32_e32 v208, 1.0, v208
	v_add_f32_e32 v209, 1.0, v209
	v_add_f32_e32 v210, 1.0, v210
	v_add_f32_e32 v211, 1.0, v211
	v_rcp_f32_e32 v208, v208
	v_rcp_f32_e32 v209, v209
	v_rcp_f32_e32 v210, v210
	v_rcp_f32_e32 v211, v211
	v_pk_mul_f32 v[26:27], v[26:27], v[208:209]
	v_pk_mul_f32 v[28:29], v[28:29], v[210:211]
	v_pk_mul_f32 v[26:27], v[26:27], v[232:233]
	v_pk_mul_f32 v[28:29], v[28:29], v[234:235]
	v_pk_mul_f32 v[26:27], v[54:55], v[26:27] op_sel_hi:[0,1]
	v_pk_mul_f32 v[28:29], v[54:55], v[28:29] op_sel_hi:[0,1]
	v_mul_f32_e32 v208, 0xbfb8aa3b, v22
	v_mul_f32_e32 v209, 0xbfb8aa3b, v23
	v_mul_f32_e32 v210, 0xbfb8aa3b, v24
	v_mul_f32_e32 v211, 0xbfb8aa3b, v25
	v_exp_f32_e32 v208, v208
	v_exp_f32_e32 v209, v209
	v_exp_f32_e32 v210, v210
	v_exp_f32_e32 v211, v211
	v_add_f32_e32 v208, 1.0, v208
	v_add_f32_e32 v209, 1.0, v209
	v_add_f32_e32 v210, 1.0, v210
	v_add_f32_e32 v211, 1.0, v211
	v_rcp_f32_e32 v208, v208
	v_rcp_f32_e32 v209, v209
	v_rcp_f32_e32 v210, v210
	v_rcp_f32_e32 v211, v211
	v_pk_mul_f32 v[22:23], v[22:23], v[208:209]
	v_pk_mul_f32 v[24:25], v[24:25], v[210:211]
	v_pk_mul_f32 v[22:23], v[22:23], v[236:237]
	v_pk_mul_f32 v[24:25], v[24:25], v[238:239]
	v_pk_mul_f32 v[22:23], v[54:55], v[22:23] op_sel_hi:[0,1]
	v_pk_mul_f32 v[24:25], v[54:55], v[24:25] op_sel_hi:[0,1]
	v_mul_f32_e32 v208, 0xbfb8aa3b, v18
	v_mul_f32_e32 v209, 0xbfb8aa3b, v19
	v_mul_f32_e32 v210, 0xbfb8aa3b, v20
	v_mul_f32_e32 v211, 0xbfb8aa3b, v21
	v_exp_f32_e32 v208, v208
	v_exp_f32_e32 v209, v209
	v_exp_f32_e32 v210, v210
	v_exp_f32_e32 v211, v211
	v_add_f32_e32 v208, 1.0, v208
	v_add_f32_e32 v209, 1.0, v209
	v_add_f32_e32 v210, 1.0, v210
	v_add_f32_e32 v211, 1.0, v211
	v_rcp_f32_e32 v208, v208
	v_rcp_f32_e32 v209, v209
	v_rcp_f32_e32 v210, v210
	v_rcp_f32_e32 v211, v211
	v_pk_mul_f32 v[18:19], v[18:19], v[208:209]
	v_pk_mul_f32 v[20:21], v[20:21], v[210:211]
	v_pk_mul_f32 v[18:19], v[18:19], v[240:241]
	v_pk_mul_f32 v[20:21], v[20:21], v[242:243]
	v_pk_mul_f32 v[18:19], v[54:55], v[18:19] op_sel_hi:[0,1]
	v_pk_mul_f32 v[20:21], v[54:55], v[20:21] op_sel_hi:[0,1]
	v_permlane16_swap_b32_e32 v30, v26
	v_permlane16_swap_b32_e32 v31, v27
	v_permlane16_swap_b32_e32 v32, v28
	v_permlane16_swap_b32_e32 v33, v29
	v_lshlrev_b32_e32 v208, 16, v62
	v_and_b32_e32 v209, 0xffff0000, v62
	v_lshlrev_b32_e32 v210, 16, v63
	v_and_b32_e32 v211, 0xffff0000, v63
	v_lshlrev_b32_e32 v212, 16, v64
	v_and_b32_e32 v213, 0xffff0000, v64
	v_lshlrev_b32_e32 v214, 16, v65
	v_and_b32_e32 v215, 0xffff0000, v65
	v_pk_mul_f32 v[208:209], v[208:209], v[30:31]
	v_pk_mul_f32 v[210:211], v[210:211], v[32:33]
	v_pk_mul_f32 v[212:213], v[212:213], v[26:27]
	v_pk_mul_f32 v[214:215], v[214:215], v[28:29]
	v_cvt_pk_bf16_f32 v62, v208, v209
	v_cvt_pk_bf16_f32 v63, v210, v211
	v_cvt_pk_bf16_f32 v64, v212, v213
	v_cvt_pk_bf16_f32 v65, v214, v215
	v_permlane16_swap_b32_e32 v22, v18
	v_permlane16_swap_b32_e32 v23, v19
	v_permlane16_swap_b32_e32 v24, v20
	v_permlane16_swap_b32_e32 v25, v21
	v_lshlrev_b32_e32 v208, 16, v58
	v_and_b32_e32 v209, 0xffff0000, v58
	v_lshlrev_b32_e32 v210, 16, v59
	v_and_b32_e32 v211, 0xffff0000, v59
	v_lshlrev_b32_e32 v212, 16, v60
	v_and_b32_e32 v213, 0xffff0000, v60
	v_lshlrev_b32_e32 v214, 16, v61
	v_and_b32_e32 v215, 0xffff0000, v61
	v_pk_mul_f32 v[208:209], v[208:209], v[22:23]
	v_pk_mul_f32 v[210:211], v[210:211], v[24:25]
	v_pk_mul_f32 v[212:213], v[212:213], v[18:19]
	v_pk_mul_f32 v[214:215], v[214:215], v[20:21]
	v_cvt_pk_bf16_f32 v58, v208, v209
	v_cvt_pk_bf16_f32 v59, v210, v211
	v_cvt_pk_bf16_f32 v60, v212, v213
	v_cvt_pk_bf16_f32 v61, v214, v215
	global_store_dwordx4 v154, v[62:65], s[10:11]
	global_store_dwordx4 v154, v[58:61], s[10:11] offset:256
	s_add_u32 s10, s10, 0x10000
	s_addc_u32 s11, s11, 0
	s_waitcnt vmcnt(2)
; #define PG8_WAIT_V(n) asm volatile("s_waitcnt vmcnt(" #n ")" ::: "memory")
; #define PG8_BAR __builtin_amdgcn_s_barrier()
; template <class Epi>
; __device__ __forceinline__ void gemm_phase(PG8_LAS unsigned char* lds, const Gemm g, const StaticOrder& S, const Epi& E) {
;     ...
;     E(acc, cur, wr, wc, fr, fq);
;     if (!has_next) break;
; #pragma unroll
;     for (int a = 0; a < 2; ++a)
; #pragma unroll
;       for (int b = 0; b < 2; ++b)
; #pragma unroll
;         for (int m = 0; m < 4; ++m)
; #pragma unroll
;           for (int n = 0; n < 2; ++n) acc[a][b][m][n] = (f32x4){0.f, 0.f, 0.f, 0.f};
;     cur = nxt; cA = nA; cB = nB; ++ui;
;   }
;   PG8_WAIT_V(0);
;   if (wr == 0) PG8_BAR;
;   PG8_BAR;
	v_mul_f32_e32 v208, 0xbfb8aa3b, v14
	v_mul_f32_e32 v209, 0xbfb8aa3b, v15
	v_mul_f32_e32 v210, 0xbfb8aa3b, v16
	v_mul_f32_e32 v211, 0xbfb8aa3b, v17
	v_exp_f32_e32 v208, v208
	v_exp_f32_e32 v209, v209
	v_exp_f32_e32 v210, v210
	v_exp_f32_e32 v211, v211
	v_add_f32_e32 v208, 1.0, v208
	v_add_f32_e32 v209, 1.0, v209
	v_add_f32_e32 v210, 1.0, v210
	v_add_f32_e32 v211, 1.0, v211
	v_rcp_f32_e32 v208, v208
	v_rcp_f32_e32 v209, v209
	v_rcp_f32_e32 v210, v210
	v_rcp_f32_e32 v211, v211
	v_pk_mul_f32 v[14:15], v[14:15], v[208:209]
	v_pk_mul_f32 v[16:17], v[16:17], v[210:211]
	v_pk_mul_f32 v[14:15], v[14:15], v[228:229]
	v_pk_mul_f32 v[16:17], v[16:17], v[230:231]
	v_pk_mul_f32 v[14:15], v[38:39], v[14:15] op_sel_hi:[0,1]
	v_pk_mul_f32 v[16:17], v[38:39], v[16:17] op_sel_hi:[0,1]
	v_mul_f32_e32 v208, 0xbfb8aa3b, v10
	v_mul_f32_e32 v209, 0xbfb8aa3b, v11
	v_mul_f32_e32 v210, 0xbfb8aa3b, v12
	v_mul_f32_e32 v211, 0xbfb8aa3b, v13
	v_exp_f32_e32 v208, v208
	v_exp_f32_e32 v209, v209
	v_exp_f32_e32 v210, v210
	v_exp_f32_e32 v211, v211
	v_add_f32_e32 v208, 1.0, v208
	v_add_f32_e32 v209, 1.0, v209
	v_add_f32_e32 v210, 1.0, v210
	v_add_f32_e32 v211, 1.0, v211
	v_rcp_f32_e32 v208, v208
	v_rcp_f32_e32 v209, v209
	v_rcp_f32_e32 v210, v210
	v_rcp_f32_e32 v211, v211
	v_pk_mul_f32 v[10:11], v[10:11], v[208:209]
	v_pk_mul_f32 v[12:13], v[12:13], v[210:211]
	v_pk_mul_f32 v[10:11], v[10:11], v[232:233]
	v_pk_mul_f32 v[12:13], v[12:13], v[234:235]
	v_pk_mul_f32 v[10:11], v[38:39], v[10:11] op_sel_hi:[0,1]
	v_pk_mul_f32 v[12:13], v[38:39], v[12:13] op_sel_hi:[0,1]
	v_mul_f32_e32 v208, 0xbfb8aa3b, v6
	v_mul_f32_e32 v209, 0xbfb8aa3b, v7
	v_mul_f32_e32 v210, 0xbfb8aa3b, v8
	v_mul_f32_e32 v211, 0xbfb8aa3b, v9
	v_exp_f32_e32 v208, v208
	v_exp_f32_e32 v209, v209
	v_exp_f32_e32 v210, v210
	v_exp_f32_e32 v211, v211
	v_add_f32_e32 v208, 1.0, v208
	v_add_f32_e32 v209, 1.0, v209
	v_add_f32_e32 v210, 1.0, v210
	v_add_f32_e32 v211, 1.0, v211
	v_rcp_f32_e32 v208, v208
	v_rcp_f32_e32 v209, v209
	v_rcp_f32_e32 v210, v210
	v_rcp_f32_e32 v211, v211
	v_pk_mul_f32 v[6:7], v[6:7], v[208:209]
	v_pk_mul_f32 v[8:9], v[8:9], v[210:211]
	v_pk_mul_f32 v[6:7], v[6:7], v[236:237]
	v_pk_mul_f32 v[8:9], v[8:9], v[238:239]
	v_pk_mul_f32 v[6:7], v[38:39], v[6:7] op_sel_hi:[0,1]
	v_pk_mul_f32 v[8:9], v[38:39], v[8:9] op_sel_hi:[0,1]
	v_mul_f32_e32 v208, 0xbfb8aa3b, v2
	v_mul_f32_e32 v209, 0xbfb8aa3b, v3
	v_mul_f32_e32 v210, 0xbfb8aa3b, v4
	v_mul_f32_e32 v211, 0xbfb8aa3b, v5
	v_exp_f32_e32 v208, v208
	v_exp_f32_e32 v209, v209
	v_exp_f32_e32 v210, v210
	v_exp_f32_e32 v211, v211
	v_add_f32_e32 v208, 1.0, v208
	v_add_f32_e32 v209, 1.0, v209
	v_add_f32_e32 v210, 1.0, v210
	v_add_f32_e32 v211, 1.0, v211
	v_rcp_f32_e32 v208, v208
	v_rcp_f32_e32 v209, v209
	v_rcp_f32_e32 v210, v210
	v_rcp_f32_e32 v211, v211
	v_pk_mul_f32 v[2:3], v[2:3], v[208:209]
	v_pk_mul_f32 v[4:5], v[4:5], v[210:211]
	v_pk_mul_f32 v[2:3], v[2:3], v[240:241]
	v_pk_mul_f32 v[4:5], v[4:5], v[242:243]
	v_pk_mul_f32 v[2:3], v[38:39], v[2:3] op_sel_hi:[0,1]
	v_pk_mul_f32 v[4:5], v[38:39], v[4:5] op_sel_hi:[0,1]
	v_permlane16_swap_b32_e32 v14, v10
	v_permlane16_swap_b32_e32 v15, v11
	v_permlane16_swap_b32_e32 v16, v12
	v_permlane16_swap_b32_e32 v17, v13
	v_lshlrev_b32_e32 v208, 16, v46
	v_and_b32_e32 v209, 0xffff0000, v46
	v_lshlrev_b32_e32 v210, 16, v47
	v_and_b32_e32 v211, 0xffff0000, v47
	v_lshlrev_b32_e32 v212, 16, v48
	v_and_b32_e32 v213, 0xffff0000, v48
	v_lshlrev_b32_e32 v214, 16, v49
	v_and_b32_e32 v215, 0xffff0000, v49
	v_pk_mul_f32 v[208:209], v[208:209], v[14:15]
	v_pk_mul_f32 v[210:211], v[210:211], v[16:17]
	v_pk_mul_f32 v[212:213], v[212:213], v[10:11]
	v_pk_mul_f32 v[214:215], v[214:215], v[12:13]
	v_cvt_pk_bf16_f32 v46, v208, v209
	v_cvt_pk_bf16_f32 v47, v210, v211
	v_cvt_pk_bf16_f32 v48, v212, v213
	v_cvt_pk_bf16_f32 v49, v214, v215
	v_permlane16_swap_b32_e32 v6, v2
	v_permlane16_swap_b32_e32 v7, v3
	v_permlane16_swap_b32_e32 v8, v4
	v_permlane16_swap_b32_e32 v9, v5
	v_lshlrev_b32_e32 v208, 16, v42
	v_and_b32_e32 v209, 0xffff0000, v42
	v_lshlrev_b32_e32 v210, 16, v43
	v_and_b32_e32 v211, 0xffff0000, v43
	v_lshlrev_b32_e32 v212, 16, v44
	v_and_b32_e32 v213, 0xffff0000, v44
	v_lshlrev_b32_e32 v214, 16, v45
	v_and_b32_e32 v215, 0xffff0000, v45
	v_pk_mul_f32 v[208:209], v[208:209], v[6:7]
	v_pk_mul_f32 v[210:211], v[210:211], v[8:9]
	v_pk_mul_f32 v[212:213], v[212:213], v[2:3]
	v_pk_mul_f32 v[214:215], v[214:215], v[4:5]
	v_cvt_pk_bf16_f32 v42, v208, v209
	v_cvt_pk_bf16_f32 v43, v210, v211
	v_cvt_pk_bf16_f32 v44, v212, v213
	v_cvt_pk_bf16_f32 v45, v214, v215
	global_store_dwordx4 v154, v[46:49], s[10:11]
	global_store_dwordx4 v154, v[42:45], s[10:11] offset:256
	s_mov_b64 s[10:11], s[48:49]
	s_mov_b64 s[8:9], s[46:47]
	s_and_b64 vcc, exec, s[40:41]
	s_cbranch_vccz .LBB0_1120
	s_waitcnt vmcnt(0)
	s_cmpk_gt_u32 s19, 0xff
	s_cbranch_scc1 .LBB0_1127
	s_barrier

; #define PG8_WAIT_V(n) asm volatile("s_waitcnt vmcnt(" #n ")" ::: "memory")
; #define PG8_WAIT_L(n) asm volatile("s_waitcnt lgkmcnt(" #n ")" ::: "memory")
; #define PG8_BAR __builtin_amdgcn_s_barrier()
; template <class Epi>
; __device__ __forceinline__ void gemm_phase(PG8_LAS unsigned char* lds, const Gemm g, const StaticOrder& S, const Epi& E) {
;     ...
;   for (;;) {
;     const bool has_next = S.next(ui + 1, nxt);
;     const char* nA = has_next ? (const char*)g.A + (size_t)nxt.pm * tstep : cA; const char* nB = has_next ? (const char*)g.Bt + (size_t)nxt.pn * tstep : cB;
;     for (int t = 0; t < nt; t += 2) {
;       const bool last = (t == nt - 2);
;       const char* a1 = cA + (size_t)(t + 1) * kstep;
;       const char* a2 = last ? nA : cA + (size_t)(t + 2) * kstep; const char* b2 = last ? nB : cB + (size_t)(t + 2) * kstep;
;       const char* a3 = a2 + kstep; const char* b3 = b2 + kstep;
;       PG8_LDB(B0, 0, 0); PG8_SCHED; PG8_LDA(At, 0, 0); PG8_STAGE(PG8_SA(1, 1), a1 + hstep, voffA);
;       PG8_WAIT_L(8); PG8_BAR; PG8_WAIT_L(0); PG8_MMA(0, 0, At, B0); PG8_BAR; PG8_SCHED;
;       PG8_LDB(B1, 0, 1); PG8_STAGE(PG8_SB(0, 0), b2, voffB);
;       PG8_BAR; PG8_WAIT_L(0); PG8_MMA(0, 1, At, B1); PG8_BAR;
;       PG8_LDA(At, 0, 1); PG8_STAGE(PG8_SA(0, 0), a2, voffA);
;       PG8_BAR; PG8_WAIT_L(0); PG8_MMA(1, 0, At, B0); PG8_BAR; PG8_SCHED;
;       PG8_STAGE(PG8_SB(0, 1), b2 + hstep, voffB);
;       PG8_WAIT_V(6); PG8_BAR; PG8_MMA(1, 1, At, B1); PG8_BAR;
;       PG8_LDB(B0, 1, 0); PG8_SCHED; PG8_LDA(At, 1, 0); PG8_STAGE(PG8_SA(0, 1), a2 + hstep, voffA);
;       PG8_WAIT_L(8); PG8_BAR; PG8_WAIT_L(0); PG8_MMA(0, 0, At, B0); PG8_BAR; PG8_SCHED;
;       PG8_LDB(B1, 1, 1); PG8_STAGE(PG8_SB(1, 0), b3, voffB);
;       PG8_BAR; PG8_WAIT_L(0); PG8_MMA(0, 1, At, B1); PG8_BAR;
;       PG8_LDA(At, 1, 1); PG8_STAGE(PG8_SA(1, 0), a3, voffA);
;       PG8_BAR; PG8_WAIT_L(0); PG8_MMA(1, 0, At, B0); PG8_BAR; PG8_SCHED;
;       PG8_STAGE(PG8_SB(1, 1), b3 + hstep, voffB);
;       PG8_WAIT_V(6); PG8_BAR; PG8_MMA(1, 1, At, B1); PG8_BAR;
;     }
;     E(acc, cur, wr, wc, fr, fq);
;     if (!has_next) break;
; #pragma unroll
;     for (int a = 0; a < 2; ++a)
; #pragma unroll
;       for (int b = 0; b < 2; ++b)
; #pragma unroll
;         for (int m = 0; m < 4; ++m)
; #pragma unroll
;           for (int n = 0; n < 2; ++n) acc[a][b][m][n] = (f32x4){0.f, 0.f, 0.f, 0.f};
.LBB0_1229:
	s_ashr_i32 s9, s8, 31
	v_cmp_lt_i64_e32 vcc, s[10:11], v[136:137]
	s_lshl_b64 s[10:11], s[8:9], 19
	s_add_u32 s10, s24, s10
	s_addc_u32 s11, s25, s11
	s_and_b64 s[30:31], vcc, exec
	s_cselect_b32 s9, s11, s47
	s_cselect_b32 s43, s10, s46
	s_ashr_i32 s7, s6, 31
	s_lshl_b64 s[30:31], s[6:7], 19
	s_add_u32 s30, s22, s30
	s_addc_u32 s31, s23, s31
	s_and_b64 s[50:51], vcc, exec
	s_cselect_b32 s7, s31, s49
	s_cselect_b32 s45, s30, s48
	s_add_u32 s46, s46, 0x40080
	s_addc_u32 s47, s47, 0
	s_add_u32 s52, s48, 0x100
	v_mov_b32_e32 v2, 0
	s_addc_u32 s53, s49, 0
	s_mov_b32 s62, -2
	v_mov_b32_e32 v3, v2
	v_mov_b32_e32 v4, v2
	v_mov_b32_e32 v5, v2
	v_mov_b32_e32 v6, v2
	v_mov_b32_e32 v7, v2
	v_mov_b32_e32 v8, v2
	v_mov_b32_e32 v9, v2
	v_mov_b32_e32 v18, v2
	v_mov_b32_e32 v19, v2
	v_mov_b32_e32 v20, v2
	v_mov_b32_e32 v21, v2
	v_mov_b32_e32 v22, v2
	v_mov_b32_e32 v23, v2
	v_mov_b32_e32 v24, v2
	v_mov_b32_e32 v25, v2
	v_mov_b32_e32 v34, v2
	v_mov_b32_e32 v35, v2
	v_mov_b32_e32 v36, v2
	v_mov_b32_e32 v37, v2
	v_mov_b32_e32 v38, v2
	v_mov_b32_e32 v39, v2
	v_mov_b32_e32 v40, v2
	v_mov_b32_e32 v41, v2
	v_mov_b32_e32 v50, v2
	v_mov_b32_e32 v51, v2
	v_mov_b32_e32 v52, v2
	v_mov_b32_e32 v53, v2
	v_mov_b32_e32 v54, v2
	v_mov_b32_e32 v55, v2
	v_mov_b32_e32 v56, v2
	v_mov_b32_e32 v57, v2
	v_mov_b32_e32 v10, v2
	v_mov_b32_e32 v11, v2
	v_mov_b32_e32 v12, v2
	v_mov_b32_e32 v13, v2
	v_mov_b32_e32 v14, v2
	v_mov_b32_e32 v15, v2
	v_mov_b32_e32 v16, v2
	v_mov_b32_e32 v17, v2
	v_mov_b32_e32 v26, v2
	v_mov_b32_e32 v27, v2
	v_mov_b32_e32 v28, v2
	v_mov_b32_e32 v29, v2
	v_mov_b32_e32 v30, v2
	v_mov_b32_e32 v31, v2
	v_mov_b32_e32 v32, v2
	v_mov_b32_e32 v33, v2
	v_mov_b32_e32 v42, v2
	v_mov_b32_e32 v43, v2
	v_mov_b32_e32 v44, v2
	v_mov_b32_e32 v45, v2
	v_mov_b32_e32 v46, v2
	v_mov_b32_e32 v47, v2
	v_mov_b32_e32 v48, v2
	v_mov_b32_e32 v49, v2
	v_mov_b32_e32 v58, v2
	v_mov_b32_e32 v59, v2
	v_mov_b32_e32 v60, v2
	v_mov_b32_e32 v61, v2
	v_mov_b32_e32 v62, v2
	v_mov_b32_e32 v63, v2
	v_mov_b32_e32 v64, v2
	v_mov_b32_e32 v65, v2
	v_mov_b32_e32 v66, v2
	v_mov_b32_e32 v67, v2
	v_mov_b32_e32 v68, v2
	v_mov_b32_e32 v69, v2
	v_mov_b32_e32 v70, v2
	v_mov_b32_e32 v71, v2
	v_mov_b32_e32 v72, v2
	v_mov_b32_e32 v73, v2
	v_mov_b32_e32 v82, v2
	v_mov_b32_e32 v83, v2
	v_mov_b32_e32 v84, v2
	v_mov_b32_e32 v85, v2
	v_mov_b32_e32 v86, v2
	v_mov_b32_e32 v87, v2
	v_mov_b32_e32 v88, v2
	v_mov_b32_e32 v89, v2
	v_mov_b32_e32 v98, v2
	v_mov_b32_e32 v99, v2
	v_mov_b32_e32 v100, v2
	v_mov_b32_e32 v101, v2
	v_mov_b32_e32 v102, v2
	v_mov_b32_e32 v103, v2
	v_mov_b32_e32 v104, v2
	v_mov_b32_e32 v105, v2
	v_mov_b32_e32 v114, v2
	v_mov_b32_e32 v115, v2
	v_mov_b32_e32 v116, v2
	v_mov_b32_e32 v117, v2
	v_mov_b32_e32 v118, v2
	v_mov_b32_e32 v119, v2
	v_mov_b32_e32 v120, v2
	v_mov_b32_e32 v121, v2
	v_mov_b32_e32 v74, v2
	v_mov_b32_e32 v75, v2
	v_mov_b32_e32 v76, v2
	v_mov_b32_e32 v77, v2
	v_mov_b32_e32 v78, v2
	v_mov_b32_e32 v79, v2
	v_mov_b32_e32 v80, v2
	v_mov_b32_e32 v81, v2
	v_mov_b32_e32 v90, v2
	v_mov_b32_e32 v91, v2
	v_mov_b32_e32 v92, v2
	v_mov_b32_e32 v93, v2
	v_mov_b32_e32 v94, v2
	v_mov_b32_e32 v95, v2
	v_mov_b32_e32 v96, v2
	v_mov_b32_e32 v97, v2
	v_mov_b32_e32 v106, v2
	v_mov_b32_e32 v107, v2
	v_mov_b32_e32 v108, v2
	v_mov_b32_e32 v109, v2
	v_mov_b32_e32 v110, v2
	v_mov_b32_e32 v111, v2
	v_mov_b32_e32 v112, v2
	v_mov_b32_e32 v113, v2
	v_mov_b32_e32 v122, v2
	v_mov_b32_e32 v123, v2
	v_mov_b32_e32 v124, v2
	v_mov_b32_e32 v125, v2
	v_mov_b32_e32 v126, v2
	v_mov_b32_e32 v127, v2
	v_mov_b32_e32 v128, v2
	v_mov_b32_e32 v129, v2
	v_readfirstlane_b32 s100, v168
	s_lshr_b32 s100, s100, 6
	s_cmp_ge_u32 s100, 4
	s_cbranch_scc0 .Lgp_4
	s_setprio 1
.Lgp_4:
.LBB0_1230:
	s_add_u32 s48, s46, 0xfffc0080
	s_addc_u32 s49, s47, -1
	s_add_i32 s63, 0, 0x10000
	v_add_u32_e32 v0, s63, v166
	ds_read_b128 v[158:161], v0
	ds_read_b128 v[162:165], v0 offset:1024
	ds_read_b128 v[188:191], v0 offset:2048
	ds_read_b128 v[192:195], v0 offset:3072
	s_cmp_eq_u32 s62, 12
	s_cselect_b32 s51, s9, s49
	s_cselect_b32 s50, s43, s48
	s_cselect_b32 s49, s7, s53
	s_cselect_b32 s48, s45, s52
	v_lshl_add_u64 v[178:179], s[46:47], 0, v[154:155]
	s_add_i32 m0, s54, 0xc000
	ds_read_b128 v[196:199], v167
	ds_read_b128 v[200:203], v167 offset:1024
	ds_read_b128 v[204:207], v167 offset:2048
	ds_read_b128 v[208:211], v167 offset:3072
	ds_read_b128 v[212:215], v167 offset:4096
	ds_read_b128 v[216:219], v167 offset:5120
	ds_read_b128 v[220:223], v167 offset:6144
	ds_read_b128 v[224:227], v167 offset:7168
	global_load_lds_dwordx4 v[178:179], off
	v_lshl_add_u64 v[178:179], s[46:47], 0, v[156:157]
	s_add_i32 m0, s54, 0xe000
	s_nop 0
	global_load_lds_dwordx4 v[178:179], off
	s_waitcnt lgkmcnt(8)
	s_barrier
	s_waitcnt lgkmcnt(0)
	s_waitcnt lgkmcnt(0)
	v_mfma_f32_16x16x32_bf16 v[126:129], v[158:161], v[196:199], v[126:129]
	v_mfma_f32_16x16x32_bf16 v[122:125], v[188:191], v[196:199], v[122:125]
	v_mfma_f32_16x16x32_bf16 v[110:113], v[158:161], v[204:207], v[110:113]
	v_mfma_f32_16x16x32_bf16 v[106:109], v[188:191], v[204:207], v[106:109]
	v_mfma_f32_16x16x32_bf16 v[94:97], v[158:161], v[212:215], v[94:97]
	v_mfma_f32_16x16x32_bf16 v[90:93], v[188:191], v[212:215], v[90:93]
	v_mfma_f32_16x16x32_bf16 v[78:81], v[158:161], v[220:223], v[78:81]
	v_mfma_f32_16x16x32_bf16 v[74:77], v[188:191], v[220:223], v[74:77]
	v_mfma_f32_16x16x32_bf16 v[126:129], v[162:165], v[200:203], v[126:129]
	v_mfma_f32_16x16x32_bf16 v[122:125], v[192:195], v[200:203], v[122:125]
	v_mfma_f32_16x16x32_bf16 v[110:113], v[162:165], v[208:211], v[110:113]
	v_mfma_f32_16x16x32_bf16 v[106:109], v[192:195], v[208:211], v[106:109]
	v_mfma_f32_16x16x32_bf16 v[94:97], v[162:165], v[216:219], v[94:97]
	v_mfma_f32_16x16x32_bf16 v[90:93], v[192:195], v[216:219], v[90:93]
	v_mfma_f32_16x16x32_bf16 v[78:81], v[162:165], v[224:227], v[78:81]
	v_mfma_f32_16x16x32_bf16 v[74:77], v[192:195], v[224:227], v[74:77]
	s_barrier
; #define PG8_STAGE(bufoff, gbase, voff) do { _Pragma("unroll") for (int _i = 0; _i < 2; ++_i) \
;     __builtin_amdgcn_global_load_lds((const unsigned*)((const char*)(gbase) + (voff)[_i]), (PG8_LAS unsigned*)(lds + (bufoff) + ldsw + _i * 8192), 16, 0, 0); } while (0)
; #define PG8_LDA(dst, b, h) do { _Pragma("unroll") for (int m = 0; m < 4; ++m) _Pragma("unroll") for (int k = 0; k < 2; ++k) dst[m][k] = *(const PG8_LAS bf16x8*)(lds + PG8_SA(b, h) + aoff + m * 2048 + k * 1024); } while (0)
; #define PG8_LDB(dst, b, h) do { _Pragma("unroll") for (int n = 0; n < 2; ++n) _Pragma("unroll") for (int k = 0; k < 2; ++k) dst[n][k] = *(const PG8_LAS bf16x8*)(lds + PG8_SB(b, h) + boff + n * 2048 + k * 1024); } while (0)
; #define PG8_MMA(ai, bj, At, Bt) do { __builtin_amdgcn_s_setprio(1); _Pragma("unroll") for (int m = 0; m < 4; ++m) _Pragma("unroll") for (int n = 0; n < 2; ++n) _Pragma("unroll") for (int k = 0; k < 2; ++k) \
;     acc[ai][bj][m][n] = __builtin_amdgcn_mfma_f32_16x16x32_bf16(Bt[n][k], At[m][k], acc[ai][bj][m][n], 0, 0, 0); __builtin_amdgcn_s_setprio(0); } while (0)
; #define PG8_WAIT_V(n) asm volatile("s_waitcnt vmcnt(" #n ")" ::: "memory")
; #define PG8_WAIT_L(n) asm volatile("s_waitcnt lgkmcnt(" #n ")" ::: "memory")
; #define PG8_BAR __builtin_amdgcn_s_barrier()
; #define PG8_SCHED __builtin_amdgcn_sched_barrier(0)
; template <class Epi>
; __device__ __forceinline__ void gemm_phase(PG8_LAS unsigned char* lds, const Gemm g, const StaticOrder& S, const Epi& E) {
;     ...
;       PG8_LDB(B1, 0, 1); PG8_STAGE(PG8_SB(0, 0), b2, voffB);
;       PG8_BAR; PG8_WAIT_L(0); PG8_MMA(0, 1, At, B1); PG8_BAR;
;       PG8_LDA(At, 0, 1); PG8_STAGE(PG8_SA(0, 0), a2, voffA);
;       PG8_BAR; PG8_WAIT_L(0); PG8_MMA(1, 0, At, B0); PG8_BAR; PG8_SCHED;
;       PG8_STAGE(PG8_SB(0, 1), b2 + hstep, voffB);
;       PG8_WAIT_V(6); PG8_BAR; PG8_MMA(1, 1, At, B1); PG8_BAR;
;       PG8_LDB(B0, 1, 0); PG8_SCHED; PG8_LDA(At, 1, 0); PG8_STAGE(PG8_SA(0, 1), a2 + hstep, voffA);
;       PG8_WAIT_L(8); PG8_BAR; PG8_WAIT_L(0); PG8_MMA(0, 0, At, B0); PG8_BAR; PG8_SCHED;
;       PG8_LDB(B1, 1, 1); PG8_STAGE(PG8_SB(1, 0), b3, voffB);
	s_add_i32 s66, 0, 0x14000
	s_add_i32 s63, s63, s28
	v_add_u32_e32 v0, s66, v166
	v_lshl_add_u64 v[178:179], s[48:49], 0, v[148:149]
	s_mov_b32 m0, s63
	ds_read_b128 v[228:231], v0
	ds_read_b128 v[232:235], v0 offset:1024
	ds_read_b128 v[236:239], v0 offset:2048
	ds_read_b128 v[240:243], v0 offset:3072
	global_load_lds_dwordx4 v[178:179], off
	v_lshl_add_u64 v[244:245], s[48:49], 0, v[150:151]
	s_add_i32 m0, s63, 0x2000
	s_nop 0
	global_load_lds_dwordx4 v[244:245], off
	s_barrier
	s_waitcnt lgkmcnt(0)
	s_waitcnt lgkmcnt(0)
	v_mfma_f32_16x16x32_bf16 v[118:121], v[228:231], v[196:199], v[118:121]
	v_mfma_f32_16x16x32_bf16 v[114:117], v[236:239], v[196:199], v[114:117]
	v_mfma_f32_16x16x32_bf16 v[102:105], v[228:231], v[204:207], v[102:105]
	v_mfma_f32_16x16x32_bf16 v[98:101], v[236:239], v[204:207], v[98:101]
	v_mfma_f32_16x16x32_bf16 v[86:89], v[228:231], v[212:215], v[86:89]
	v_mfma_f32_16x16x32_bf16 v[82:85], v[236:239], v[212:215], v[82:85]
	v_mfma_f32_16x16x32_bf16 v[70:73], v[228:231], v[220:223], v[70:73]
	v_mfma_f32_16x16x32_bf16 v[66:69], v[236:239], v[220:223], v[66:69]
	v_mfma_f32_16x16x32_bf16 v[118:121], v[232:235], v[200:203], v[118:121]
	v_mfma_f32_16x16x32_bf16 v[114:117], v[240:243], v[200:203], v[114:117]
	v_mfma_f32_16x16x32_bf16 v[102:105], v[232:235], v[208:211], v[102:105]
	v_mfma_f32_16x16x32_bf16 v[98:101], v[240:243], v[208:211], v[98:101]
	v_mfma_f32_16x16x32_bf16 v[86:89], v[232:235], v[216:219], v[86:89]
	v_mfma_f32_16x16x32_bf16 v[82:85], v[240:243], v[216:219], v[82:85]
	v_mfma_f32_16x16x32_bf16 v[70:73], v[232:235], v[224:227], v[70:73]
	v_mfma_f32_16x16x32_bf16 v[66:69], v[240:243], v[224:227], v[66:69]
	s_mov_b32 m0, s54
	v_lshl_add_u64 v[246:247], s[50:51], 0, v[148:149]
	s_barrier
	ds_read_b128 v[196:199], v167 offset:16384
	ds_read_b128 v[200:203], v167 offset:17408
	ds_read_b128 v[204:207], v167 offset:18432
	ds_read_b128 v[208:211], v167 offset:19456
	ds_read_b128 v[212:215], v167 offset:20480
	ds_read_b128 v[216:219], v167 offset:21504
	ds_read_b128 v[220:223], v167 offset:22528
	ds_read_b128 v[224:227], v167 offset:23552
	global_load_lds_dwordx4 v[246:247], off
	v_lshl_add_u64 v[248:249], s[50:51], 0, v[150:151]
	s_mov_b32 m0, s55
	s_nop 0
	global_load_lds_dwordx4 v[248:249], off
	s_barrier
	s_waitcnt lgkmcnt(0)
	s_waitcnt lgkmcnt(0)
	v_mfma_f32_16x16x32_bf16 v[62:65], v[158:161], v[196:199], v[62:65]
	v_mfma_f32_16x16x32_bf16 v[58:61], v[188:191], v[196:199], v[58:61]
	v_mfma_f32_16x16x32_bf16 v[46:49], v[158:161], v[204:207], v[46:49]
	v_mfma_f32_16x16x32_bf16 v[42:45], v[188:191], v[204:207], v[42:45]
	v_mfma_f32_16x16x32_bf16 v[30:33], v[158:161], v[212:215], v[30:33]
	v_mfma_f32_16x16x32_bf16 v[26:29], v[188:191], v[212:215], v[26:29]
	v_mfma_f32_16x16x32_bf16 v[14:17], v[158:161], v[220:223], v[14:17]
	v_mfma_f32_16x16x32_bf16 v[10:13], v[188:191], v[220:223], v[10:13]
	v_mfma_f32_16x16x32_bf16 v[62:65], v[162:165], v[200:203], v[62:65]
	v_mfma_f32_16x16x32_bf16 v[58:61], v[192:195], v[200:203], v[58:61]
	v_mfma_f32_16x16x32_bf16 v[46:49], v[162:165], v[208:211], v[46:49]
	v_mfma_f32_16x16x32_bf16 v[42:45], v[192:195], v[208:211], v[42:45]
	v_mfma_f32_16x16x32_bf16 v[30:33], v[162:165], v[216:219], v[30:33]
	v_mfma_f32_16x16x32_bf16 v[26:29], v[192:195], v[216:219], v[26:29]
	v_mfma_f32_16x16x32_bf16 v[14:17], v[162:165], v[224:227], v[14:17]
	v_mfma_f32_16x16x32_bf16 v[10:13], v[192:195], v[224:227], v[10:13]
	s_barrier
	s_add_u32 s64, s48, 0x40000
	s_addc_u32 s65, s49, 0
	s_add_i32 s63, s66, s28
	v_lshl_add_u64 v[158:159], s[64:65], 0, v[148:149]
	s_mov_b32 m0, s63
	s_nop 0
	global_load_lds_dwordx4 v[158:159], off
	v_lshl_add_u64 v[158:159], s[64:65], 0, v[150:151]
	s_add_i32 m0, s63, 0x2000
	s_nop 0
	global_load_lds_dwordx4 v[158:159], off
	s_waitcnt vmcnt(6)
	s_barrier
	v_mfma_f32_16x16x32_bf16 v[54:57], v[228:231], v[196:199], v[54:57]
	v_mfma_f32_16x16x32_bf16 v[50:53], v[236:239], v[196:199], v[50:53]
	v_mfma_f32_16x16x32_bf16 v[38:41], v[228:231], v[204:207], v[38:41]
	v_mfma_f32_16x16x32_bf16 v[34:37], v[236:239], v[204:207], v[34:37]
	v_mfma_f32_16x16x32_bf16 v[22:25], v[228:231], v[212:215], v[22:25]
	v_mfma_f32_16x16x32_bf16 v[18:21], v[236:239], v[212:215], v[18:21]
	v_mfma_f32_16x16x32_bf16 v[6:9], v[228:231], v[220:223], v[6:9]
	v_mfma_f32_16x16x32_bf16 v[2:5], v[236:239], v[220:223], v[2:5]
	v_mfma_f32_16x16x32_bf16 v[54:57], v[232:235], v[200:203], v[54:57]
	v_mfma_f32_16x16x32_bf16 v[50:53], v[240:243], v[200:203], v[50:53]
	v_mfma_f32_16x16x32_bf16 v[38:41], v[232:235], v[208:211], v[38:41]
	v_mfma_f32_16x16x32_bf16 v[34:37], v[240:243], v[208:211], v[34:37]
	v_mfma_f32_16x16x32_bf16 v[22:25], v[232:235], v[216:219], v[22:25]
	v_mfma_f32_16x16x32_bf16 v[18:21], v[240:243], v[216:219], v[18:21]
	v_mfma_f32_16x16x32_bf16 v[6:9], v[232:235], v[224:227], v[6:9]
	v_mfma_f32_16x16x32_bf16 v[2:5], v[240:243], v[224:227], v[2:5]
	s_add_i32 s63, 0, 0x18000
	v_add_u32_e32 v0, s63, v166
	s_barrier
	ds_read_b128 v[158:161], v0
	ds_read_b128 v[162:165], v0 offset:1024
	ds_read_b128 v[188:191], v0 offset:2048
	ds_read_b128 v[192:195], v0 offset:3072
	s_add_u32 s50, s50, 0x40000
	s_addc_u32 s51, s51, 0
	s_mov_b32 m0, s56
	v_lshl_add_u64 v[228:229], s[50:51], 0, v[148:149]
	ds_read_b128 v[196:199], v167 offset:32768
	ds_read_b128 v[200:203], v167 offset:33792
	ds_read_b128 v[204:207], v167 offset:34816
	ds_read_b128 v[208:211], v167 offset:35840
	ds_read_b128 v[212:215], v167 offset:36864
	ds_read_b128 v[216:219], v167 offset:37888
	ds_read_b128 v[220:223], v167 offset:38912
	ds_read_b128 v[224:227], v167 offset:39936
	global_load_lds_dwordx4 v[228:229], off
	v_lshl_add_u64 v[228:229], s[50:51], 0, v[150:151]
	s_mov_b32 m0, s57
	s_nop 0
	global_load_lds_dwordx4 v[228:229], off
	s_waitcnt lgkmcnt(8)
	s_barrier
; #define PG8_STAGE(bufoff, gbase, voff) do { _Pragma("unroll") for (int _i = 0; _i < 2; ++_i) \
;     __builtin_amdgcn_global_load_lds((const unsigned*)((const char*)(gbase) + (voff)[_i]), (PG8_LAS unsigned*)(lds + (bufoff) + ldsw + _i * 8192), 16, 0, 0); } while (0)
; #define PG8_LDA(dst, b, h) do { _Pragma("unroll") for (int m = 0; m < 4; ++m) _Pragma("unroll") for (int k = 0; k < 2; ++k) dst[m][k] = *(const PG8_LAS bf16x8*)(lds + PG8_SA(b, h) + aoff + m * 2048 + k * 1024); } while (0)
; #define PG8_LDB(dst, b, h) do { _Pragma("unroll") for (int n = 0; n < 2; ++n) _Pragma("unroll") for (int k = 0; k < 2; ++k) dst[n][k] = *(const PG8_LAS bf16x8*)(lds + PG8_SB(b, h) + boff + n * 2048 + k * 1024); } while (0)
; #define PG8_MMA(ai, bj, At, Bt) do { __builtin_amdgcn_s_setprio(1); _Pragma("unroll") for (int m = 0; m < 4; ++m) _Pragma("unroll") for (int n = 0; n < 2; ++n) _Pragma("unroll") for (int k = 0; k < 2; ++k) \
;     acc[ai][bj][m][n] = __builtin_amdgcn_mfma_f32_16x16x32_bf16(Bt[n][k], At[m][k], acc[ai][bj][m][n], 0, 0, 0); __builtin_amdgcn_s_setprio(0); } while (0)
; #define PG8_WAIT_V(n) asm volatile("s_waitcnt vmcnt(" #n ")" ::: "memory")
; #define PG8_WAIT_L(n) asm volatile("s_waitcnt lgkmcnt(" #n ")" ::: "memory")
; #define PG8_BAR __builtin_amdgcn_s_barrier()
; #define PG8_SCHED __builtin_amdgcn_sched_barrier(0)
; template <class Epi>
; __device__ __forceinline__ void gemm_phase(PG8_LAS unsigned char* lds, const Gemm g, const StaticOrder& S, const Epi& E) {
;     ...
;       PG8_WAIT_L(8); PG8_BAR; PG8_WAIT_L(0); PG8_MMA(0, 0, At, B0); PG8_BAR; PG8_SCHED;
;       PG8_LDB(B1, 1, 1); PG8_STAGE(PG8_SB(1, 0), b3, voffB);
;       PG8_BAR; PG8_WAIT_L(0); PG8_MMA(0, 1, At, B1); PG8_BAR;
;       PG8_LDA(At, 1, 1); PG8_STAGE(PG8_SA(1, 0), a3, voffA);
;       PG8_BAR; PG8_WAIT_L(0); PG8_MMA(1, 0, At, B0); PG8_BAR; PG8_SCHED;
;       PG8_STAGE(PG8_SB(1, 1), b3 + hstep, voffB);
;       PG8_WAIT_V(6); PG8_BAR; PG8_MMA(1, 1, At, B1); PG8_BAR;
	s_waitcnt lgkmcnt(0)
	s_waitcnt lgkmcnt(0)
	v_mfma_f32_16x16x32_bf16 v[126:129], v[158:161], v[196:199], v[126:129]
	v_mfma_f32_16x16x32_bf16 v[122:125], v[188:191], v[196:199], v[122:125]
	v_mfma_f32_16x16x32_bf16 v[110:113], v[158:161], v[204:207], v[110:113]
	v_mfma_f32_16x16x32_bf16 v[106:109], v[188:191], v[204:207], v[106:109]
	v_mfma_f32_16x16x32_bf16 v[94:97], v[158:161], v[212:215], v[94:97]
	v_mfma_f32_16x16x32_bf16 v[90:93], v[188:191], v[212:215], v[90:93]
	v_mfma_f32_16x16x32_bf16 v[78:81], v[158:161], v[220:223], v[78:81]
	v_mfma_f32_16x16x32_bf16 v[74:77], v[188:191], v[220:223], v[74:77]
	v_mfma_f32_16x16x32_bf16 v[126:129], v[162:165], v[200:203], v[126:129]
	v_mfma_f32_16x16x32_bf16 v[122:125], v[192:195], v[200:203], v[122:125]
	v_mfma_f32_16x16x32_bf16 v[110:113], v[162:165], v[208:211], v[110:113]
	v_mfma_f32_16x16x32_bf16 v[106:109], v[192:195], v[208:211], v[106:109]
	v_mfma_f32_16x16x32_bf16 v[94:97], v[162:165], v[216:219], v[94:97]
	v_mfma_f32_16x16x32_bf16 v[90:93], v[192:195], v[216:219], v[90:93]
	v_mfma_f32_16x16x32_bf16 v[78:81], v[162:165], v[224:227], v[78:81]
	v_mfma_f32_16x16x32_bf16 v[74:77], v[192:195], v[224:227], v[74:77]
	s_barrier
	s_add_i32 s50, 0, 0x1c000
	s_add_i32 s51, s63, s28
	v_add_u32_e32 v0, s50, v166
	v_lshl_add_u64 v[178:179], v[178:179], 0, s[4:5]
	s_mov_b32 m0, s51
	ds_read_b128 v[228:231], v0
	ds_read_b128 v[232:235], v0 offset:1024
	ds_read_b128 v[236:239], v0 offset:2048
	ds_read_b128 v[240:243], v0 offset:3072
	global_load_lds_dwordx4 v[178:179], off
	v_lshl_add_u64 v[178:179], v[244:245], 0, s[4:5]
	s_add_i32 m0, s51, 0x2000
	s_nop 0
	global_load_lds_dwordx4 v[178:179], off
	s_barrier
	s_waitcnt lgkmcnt(0)
	s_waitcnt lgkmcnt(0)
	v_mfma_f32_16x16x32_bf16 v[118:121], v[228:231], v[196:199], v[118:121]
	v_mfma_f32_16x16x32_bf16 v[114:117], v[236:239], v[196:199], v[114:117]
	v_mfma_f32_16x16x32_bf16 v[102:105], v[228:231], v[204:207], v[102:105]
	v_mfma_f32_16x16x32_bf16 v[98:101], v[236:239], v[204:207], v[98:101]
	v_mfma_f32_16x16x32_bf16 v[86:89], v[228:231], v[212:215], v[86:89]
	v_mfma_f32_16x16x32_bf16 v[82:85], v[236:239], v[212:215], v[82:85]
	v_mfma_f32_16x16x32_bf16 v[70:73], v[228:231], v[220:223], v[70:73]
	v_mfma_f32_16x16x32_bf16 v[66:69], v[236:239], v[220:223], v[66:69]
	v_mfma_f32_16x16x32_bf16 v[118:121], v[232:235], v[200:203], v[118:121]
	v_mfma_f32_16x16x32_bf16 v[114:117], v[240:243], v[200:203], v[114:117]
	v_mfma_f32_16x16x32_bf16 v[102:105], v[232:235], v[208:211], v[102:105]
	v_mfma_f32_16x16x32_bf16 v[98:101], v[240:243], v[208:211], v[98:101]
	v_mfma_f32_16x16x32_bf16 v[86:89], v[232:235], v[216:219], v[86:89]
	v_mfma_f32_16x16x32_bf16 v[82:85], v[240:243], v[216:219], v[82:85]
	v_mfma_f32_16x16x32_bf16 v[70:73], v[232:235], v[224:227], v[70:73]
	v_mfma_f32_16x16x32_bf16 v[66:69], v[240:243], v[224:227], v[66:69]
	s_mov_b32 m0, s59
	v_lshl_add_u64 v[178:179], v[246:247], 0, s[4:5]
	s_barrier
	ds_read_b128 v[196:199], v167 offset:49152
	ds_read_b128 v[200:203], v167 offset:50176
	ds_read_b128 v[204:207], v167 offset:51200
	ds_read_b128 v[208:211], v167 offset:52224
	ds_read_b128 v[212:215], v167 offset:53248
	ds_read_b128 v[216:219], v167 offset:54272
	ds_read_b128 v[220:223], v167 offset:55296
	ds_read_b128 v[224:227], v167 offset:56320
	global_load_lds_dwordx4 v[178:179], off
	v_lshl_add_u64 v[178:179], v[248:249], 0, s[4:5]
	s_mov_b32 m0, s60
	s_nop 0
	global_load_lds_dwordx4 v[178:179], off
	s_barrier
	s_waitcnt lgkmcnt(0)
	s_waitcnt lgkmcnt(0)
	v_mfma_f32_16x16x32_bf16 v[62:65], v[158:161], v[196:199], v[62:65]
	v_mfma_f32_16x16x32_bf16 v[58:61], v[188:191], v[196:199], v[58:61]
	v_mfma_f32_16x16x32_bf16 v[46:49], v[158:161], v[204:207], v[46:49]
	v_mfma_f32_16x16x32_bf16 v[42:45], v[188:191], v[204:207], v[42:45]
	v_mfma_f32_16x16x32_bf16 v[30:33], v[158:161], v[212:215], v[30:33]
	v_mfma_f32_16x16x32_bf16 v[26:29], v[188:191], v[212:215], v[26:29]
	v_mfma_f32_16x16x32_bf16 v[14:17], v[158:161], v[220:223], v[14:17]
	v_mfma_f32_16x16x32_bf16 v[10:13], v[188:191], v[220:223], v[10:13]
	v_mfma_f32_16x16x32_bf16 v[62:65], v[162:165], v[200:203], v[62:65]
	v_mfma_f32_16x16x32_bf16 v[58:61], v[192:195], v[200:203], v[58:61]
	v_mfma_f32_16x16x32_bf16 v[46:49], v[162:165], v[208:211], v[46:49]
	v_mfma_f32_16x16x32_bf16 v[42:45], v[192:195], v[208:211], v[42:45]
	v_mfma_f32_16x16x32_bf16 v[30:33], v[162:165], v[216:219], v[30:33]
	v_mfma_f32_16x16x32_bf16 v[26:29], v[192:195], v[216:219], v[26:29]
	v_mfma_f32_16x16x32_bf16 v[14:17], v[162:165], v[224:227], v[14:17]
	v_mfma_f32_16x16x32_bf16 v[10:13], v[192:195], v[224:227], v[10:13]
	s_barrier
	s_add_u32 s48, s48, 0x40080
	s_addc_u32 s49, s49, 0
	s_add_i32 s50, s50, s28
	v_lshl_add_u64 v[158:159], s[48:49], 0, v[148:149]
	s_mov_b32 m0, s50
	s_nop 0
	global_load_lds_dwordx4 v[158:159], off
	v_lshl_add_u64 v[158:159], s[48:49], 0, v[150:151]
	s_add_i32 m0, s50, 0x2000
	s_nop 0
	global_load_lds_dwordx4 v[158:159], off
	s_waitcnt vmcnt(6)
	s_barrier
	v_mfma_f32_16x16x32_bf16 v[54:57], v[228:231], v[196:199], v[54:57]
	v_mfma_f32_16x16x32_bf16 v[50:53], v[236:239], v[196:199], v[50:53]
	v_mfma_f32_16x16x32_bf16 v[38:41], v[228:231], v[204:207], v[38:41]
	v_mfma_f32_16x16x32_bf16 v[34:37], v[236:239], v[204:207], v[34:37]
	v_mfma_f32_16x16x32_bf16 v[22:25], v[228:231], v[212:215], v[22:25]
	v_mfma_f32_16x16x32_bf16 v[18:21], v[236:239], v[212:215], v[18:21]
	v_mfma_f32_16x16x32_bf16 v[6:9], v[228:231], v[220:223], v[6:9]
	v_mfma_f32_16x16x32_bf16 v[2:5], v[236:239], v[220:223], v[2:5]
	v_mfma_f32_16x16x32_bf16 v[54:57], v[232:235], v[200:203], v[54:57]
	v_mfma_f32_16x16x32_bf16 v[50:53], v[240:243], v[200:203], v[50:53]
	v_mfma_f32_16x16x32_bf16 v[38:41], v[232:235], v[208:211], v[38:41]
	v_mfma_f32_16x16x32_bf16 v[34:37], v[240:243], v[208:211], v[34:37]
	v_mfma_f32_16x16x32_bf16 v[22:25], v[232:235], v[216:219], v[22:25]
	v_mfma_f32_16x16x32_bf16 v[18:21], v[240:243], v[216:219], v[18:21]
	v_mfma_f32_16x16x32_bf16 v[6:9], v[232:235], v[224:227], v[6:9]
	v_mfma_f32_16x16x32_bf16 v[2:5], v[240:243], v[224:227], v[2:5]
	s_add_i32 s62, s62, 2
	s_add_u32 s46, s46, 0x100
	s_addc_u32 s47, s47, 0
	s_add_u32 s52, s52, 0x100
	s_addc_u32 s53, s53, 0
	s_cmp_gt_u32 s62, 13
	s_barrier
;   __device__ __forceinline__ void operator()(const f32x4 (&acc)[2][2][4][2], const pg8::Unit& u, int wr, int wc, int fr, int fq) const {
; #pragma unroll
;     for (int ai = 0; ai < 2; ++ai)
; #pragma unroll
;       for (int m = 0; m < 4; ++m) { const int row = u.pm * 256 + ai * 128 + wr * 64 + m * 16 + fr;
; #pragma unroll
;         for (int bj = 0; bj < 2; ++bj)
; #pragma unroll
;           for (int n = 0; n < 2; ++n) f(row, u.pn * 256 + bj * 128 + wc * 32 + n * 16 + 4 * fq, acc[ai][bj][m][n]); }
	s_cbranch_scc0 .LBB0_1230
	s_cmp_eq_u32 s42, 16
	s_cbranch_scc1 .Lbf_orig_mlin
	s_movk_i32 s7, 0x2000
	v_bfe_u32 v178, v168, 4, 1
	v_mul_u32_u24_e32 v178, 24, v178
	v_lshl_add_u32 v178, v152, 1, v178
	v_mad_u32_u24 v178, v147, s7, v178
	s_lshl_b32 s50, s58, 1
	v_add_u32_e32 v178, s50, v178
	s_lshl_b32 s48, s44, 21
	s_lshl_b32 s50, s42, 9
	s_add_i32 s48, s48, s50
	s_add_u32 s48, s26, s48
	s_addc_u32 s49, s27, 0
	v_readlane_b32 s64, v254, 56
	s_movk_i32 s65, 0x100
	v_cvt_pk_bf16_f32 v125, v124, v125
	v_cvt_pk_bf16_f32 v124, v122, v123
	v_cvt_pk_bf16_f32 v122, v126, v127
	v_cvt_pk_bf16_f32 v123, v128, v129
	v_cvt_pk_bf16_f32 v117, v116, v117
	v_cvt_pk_bf16_f32 v116, v114, v115
	v_cvt_pk_bf16_f32 v114, v118, v119
	v_cvt_pk_bf16_f32 v115, v120, v121
	v_permlane16_swap_b32_e32 v122, v124
	v_permlane16_swap_b32_e32 v123, v125
	v_permlane16_swap_b32_e32 v114, v116
	v_permlane16_swap_b32_e32 v115, v117
	global_store_dwordx4 v178, v[122:125], s[48:49]
	global_store_dwordx4 v178, v[114:117], s[48:49] offset:256
	s_add_u32 s48, s48, 0x20000
	s_addc_u32 s49, s49, 0
	v_cvt_pk_bf16_f32 v109, v108, v109
	v_cvt_pk_bf16_f32 v108, v106, v107
	v_cvt_pk_bf16_f32 v106, v110, v111
	v_cvt_pk_bf16_f32 v107, v112, v113
	v_cvt_pk_bf16_f32 v101, v100, v101
	v_cvt_pk_bf16_f32 v100, v98, v99
	v_cvt_pk_bf16_f32 v98, v102, v103
	v_cvt_pk_bf16_f32 v99, v104, v105
	v_permlane16_swap_b32_e32 v106, v108
	v_permlane16_swap_b32_e32 v107, v109
	v_permlane16_swap_b32_e32 v98, v100
	v_permlane16_swap_b32_e32 v99, v101
	global_store_dwordx4 v178, v[106:109], s[48:49]
	global_store_dwordx4 v178, v[98:101], s[48:49] offset:256
	s_add_u32 s48, s48, 0x20000
	s_addc_u32 s49, s49, 0
	v_cvt_pk_bf16_f32 v93, v92, v93
	v_cvt_pk_bf16_f32 v92, v90, v91
	v_cvt_pk_bf16_f32 v90, v94, v95
	v_cvt_pk_bf16_f32 v91, v96, v97
	v_cvt_pk_bf16_f32 v85, v84, v85
	v_cvt_pk_bf16_f32 v84, v82, v83
	v_cvt_pk_bf16_f32 v82, v86, v87
	v_cvt_pk_bf16_f32 v83, v88, v89
	v_permlane16_swap_b32_e32 v90, v92
	v_permlane16_swap_b32_e32 v91, v93
	v_permlane16_swap_b32_e32 v82, v84
	v_permlane16_swap_b32_e32 v83, v85
	global_store_dwordx4 v178, v[90:93], s[48:49]
	global_store_dwordx4 v178, v[82:85], s[48:49] offset:256
	s_add_u32 s48, s48, 0x20000
	s_addc_u32 s49, s49, 0
	v_cvt_pk_bf16_f32 v77, v76, v77
	v_cvt_pk_bf16_f32 v76, v74, v75
	v_cvt_pk_bf16_f32 v74, v78, v79
	v_cvt_pk_bf16_f32 v75, v80, v81
	v_cvt_pk_bf16_f32 v69, v68, v69
	v_cvt_pk_bf16_f32 v68, v66, v67
	v_cvt_pk_bf16_f32 v66, v70, v71
	v_cvt_pk_bf16_f32 v67, v72, v73
	v_permlane16_swap_b32_e32 v74, v76
	v_permlane16_swap_b32_e32 v75, v77
	v_permlane16_swap_b32_e32 v66, v68
	v_permlane16_swap_b32_e32 v67, v69
	global_store_dwordx4 v178, v[74:77], s[48:49]
	global_store_dwordx4 v178, v[66:69], s[48:49] offset:256
	s_add_u32 s48, s48, 0xa0000
	s_addc_u32 s49, s49, 0
	v_cvt_pk_bf16_f32 v61, v60, v61
	v_cvt_pk_bf16_f32 v60, v58, v59
	v_cvt_pk_bf16_f32 v58, v62, v63
	v_cvt_pk_bf16_f32 v59, v64, v65
	v_cvt_pk_bf16_f32 v53, v52, v53
	v_cvt_pk_bf16_f32 v52, v50, v51
	v_cvt_pk_bf16_f32 v50, v54, v55
	v_cvt_pk_bf16_f32 v51, v56, v57
	v_permlane16_swap_b32_e32 v58, v60
	v_permlane16_swap_b32_e32 v59, v61
	v_permlane16_swap_b32_e32 v50, v52
	v_permlane16_swap_b32_e32 v51, v53
	global_store_dwordx4 v178, v[58:61], s[48:49]
	global_store_dwordx4 v178, v[50:53], s[48:49] offset:256
	s_add_u32 s48, s48, 0x20000
	s_addc_u32 s49, s49, 0
	v_cvt_pk_bf16_f32 v45, v44, v45
	v_cvt_pk_bf16_f32 v44, v42, v43
	v_cvt_pk_bf16_f32 v42, v46, v47
	v_cvt_pk_bf16_f32 v43, v48, v49
	v_cvt_pk_bf16_f32 v37, v36, v37
	v_cvt_pk_bf16_f32 v36, v34, v35
	v_cvt_pk_bf16_f32 v34, v38, v39
	v_cvt_pk_bf16_f32 v35, v40, v41
	v_permlane16_swap_b32_e32 v42, v44
	v_permlane16_swap_b32_e32 v43, v45
	v_permlane16_swap_b32_e32 v34, v36
	v_permlane16_swap_b32_e32 v35, v37
	global_store_dwordx4 v178, v[42:45], s[48:49]
	global_store_dwordx4 v178, v[34:37], s[48:49] offset:256
	s_add_u32 s48, s48, 0x20000
	s_addc_u32 s49, s49, 0
	v_cvt_pk_bf16_f32 v29, v28, v29
	v_cvt_pk_bf16_f32 v28, v26, v27
	v_cvt_pk_bf16_f32 v26, v30, v31
	v_cvt_pk_bf16_f32 v27, v32, v33
	v_cvt_pk_bf16_f32 v21, v20, v21
	v_cvt_pk_bf16_f32 v20, v18, v19
	v_cvt_pk_bf16_f32 v18, v22, v23
	v_cvt_pk_bf16_f32 v19, v24, v25
	v_permlane16_swap_b32_e32 v26, v28
	v_permlane16_swap_b32_e32 v27, v29
	v_permlane16_swap_b32_e32 v18, v20
	v_permlane16_swap_b32_e32 v19, v21
	global_store_dwordx4 v178, v[26:29], s[48:49]
	global_store_dwordx4 v178, v[18:21], s[48:49] offset:256
	s_add_u32 s48, s48, 0x20000
	s_addc_u32 s49, s49, 0
	v_cvt_pk_bf16_f32 v13, v12, v13
	v_cvt_pk_bf16_f32 v12, v10, v11
	v_cvt_pk_bf16_f32 v10, v14, v15
	v_cvt_pk_bf16_f32 v11, v16, v17
	v_cvt_pk_bf16_f32 v5, v4, v5
	v_cvt_pk_bf16_f32 v4, v2, v3
	v_cvt_pk_bf16_f32 v2, v6, v7
	v_cvt_pk_bf16_f32 v3, v8, v9
	v_permlane16_swap_b32_e32 v10, v12
	v_permlane16_swap_b32_e32 v11, v13
	v_permlane16_swap_b32_e32 v2, v4
	v_permlane16_swap_b32_e32 v3, v5
	global_store_dwordx4 v178, v[10:13], s[48:49]
	global_store_dwordx4 v178, v[2:5], s[48:49] offset:256
	s_branch .LBB0_1222

; #define PG8_STAGE(bufoff, gbase, voff) do { _Pragma("unroll") for (int _i = 0; _i < 2; ++_i) \
;     __builtin_amdgcn_global_load_lds((const unsigned*)((const char*)(gbase) + (voff)[_i]), (PG8_LAS unsigned*)(lds + (bufoff) + ldsw + _i * 8192), 16, 0, 0); } while (0)
; #define PG8_LDA(dst, b, h) do { _Pragma("unroll") for (int m = 0; m < 4; ++m) _Pragma("unroll") for (int k = 0; k < 2; ++k) dst[m][k] = *(const PG8_LAS bf16x8*)(lds + PG8_SA(b, h) + aoff + m * 2048 + k * 1024); } while (0)
; #define PG8_LDB(dst, b, h) do { _Pragma("unroll") for (int n = 0; n < 2; ++n) _Pragma("unroll") for (int k = 0; k < 2; ++k) dst[n][k] = *(const PG8_LAS bf16x8*)(lds + PG8_SB(b, h) + boff + n * 2048 + k * 1024); } while (0)
; #define PG8_MMA(ai, bj, At, Bt) do { __builtin_amdgcn_s_setprio(1); _Pragma("unroll") for (int m = 0; m < 4; ++m) _Pragma("unroll") for (int n = 0; n < 2; ++n) _Pragma("unroll") for (int k = 0; k < 2; ++k) \
;     acc[ai][bj][m][n] = __builtin_amdgcn_mfma_f32_16x16x32_bf16(Bt[n][k], At[m][k], acc[ai][bj][m][n], 0, 0, 0); __builtin_amdgcn_s_setprio(0); } while (0)
; #define PG8_WAIT_L(n) asm volatile("s_waitcnt lgkmcnt(" #n ")" ::: "memory")
; #define PG8_BAR __builtin_amdgcn_s_barrier()
; #define PG8_SCHED __builtin_amdgcn_sched_barrier(0)
; template <class Epi>
; __device__ __forceinline__ void gemm_phase(PG8_LAS unsigned char* lds, const Gemm g, const StaticOrder& S, const Epi& E) {
;     ...
;       PG8_LDB(B0, 0, 0); PG8_SCHED; PG8_LDA(At, 0, 0); PG8_STAGE(PG8_SA(1, 1), a1 + hstep, voffA);
;       PG8_WAIT_L(8); PG8_BAR; PG8_WAIT_L(0); PG8_MMA(0, 0, At, B0); PG8_BAR; PG8_SCHED;
;       PG8_LDB(B1, 0, 1); PG8_STAGE(PG8_SB(0, 0), b2, voffB);
;       PG8_BAR; PG8_WAIT_L(0); PG8_MMA(0, 1, At, B1); PG8_BAR;
;       PG8_LDA(At, 0, 1); PG8_STAGE(PG8_SA(0, 0), a2, voffA);
;     ...
; #pragma unroll
;     for (int a = 0; a < 2; ++a)
; #pragma unroll
;       for (int b = 0; b < 2; ++b)
; #pragma unroll
;         for (int m = 0; m < 4; ++m)
; #pragma unroll
;           for (int n = 0; n < 2; ++n) acc[a][b][m][n] = (f32x4){0.f, 0.f, 0.f, 0.f};
;     cur = nxt; cA = nA; cB = nB; ++ui;
.LBB0_1409:
	s_add_u32 s59, s46, 0x100
	v_mov_b32_e32 v2, 0
	s_addc_u32 s60, s47, 0
	s_mov_b32 s61, -2
	v_mov_b32_e32 v3, v2
	v_mov_b32_e32 v4, v2
	v_mov_b32_e32 v5, v2
	v_mov_b32_e32 v6, v2
	v_mov_b32_e32 v7, v2
	v_mov_b32_e32 v8, v2
	v_mov_b32_e32 v9, v2
	v_mov_b32_e32 v18, v2
	v_mov_b32_e32 v19, v2
	v_mov_b32_e32 v20, v2
	v_mov_b32_e32 v21, v2
	v_mov_b32_e32 v22, v2
	v_mov_b32_e32 v23, v2
	v_mov_b32_e32 v24, v2
	v_mov_b32_e32 v25, v2
	v_mov_b32_e32 v34, v2
	v_mov_b32_e32 v35, v2
	v_mov_b32_e32 v36, v2
	v_mov_b32_e32 v37, v2
	v_mov_b32_e32 v38, v2
	v_mov_b32_e32 v39, v2
	v_mov_b32_e32 v40, v2
	v_mov_b32_e32 v41, v2
	v_mov_b32_e32 v50, v2
	v_mov_b32_e32 v51, v2
	v_mov_b32_e32 v52, v2
	v_mov_b32_e32 v53, v2
	v_mov_b32_e32 v54, v2
	v_mov_b32_e32 v55, v2
	v_mov_b32_e32 v56, v2
	v_mov_b32_e32 v57, v2
	v_mov_b32_e32 v10, v2
	v_mov_b32_e32 v11, v2
	v_mov_b32_e32 v12, v2
	v_mov_b32_e32 v13, v2
	v_mov_b32_e32 v14, v2
	v_mov_b32_e32 v15, v2
	v_mov_b32_e32 v16, v2
	v_mov_b32_e32 v17, v2
	v_mov_b32_e32 v26, v2
	v_mov_b32_e32 v27, v2
	v_mov_b32_e32 v28, v2
	v_mov_b32_e32 v29, v2
	v_mov_b32_e32 v30, v2
	v_mov_b32_e32 v31, v2
	v_mov_b32_e32 v32, v2
	v_mov_b32_e32 v33, v2
	v_mov_b32_e32 v42, v2
	v_mov_b32_e32 v43, v2
	v_mov_b32_e32 v44, v2
	v_mov_b32_e32 v45, v2
	v_mov_b32_e32 v46, v2
	v_mov_b32_e32 v47, v2
	v_mov_b32_e32 v48, v2
	v_mov_b32_e32 v49, v2
	v_mov_b32_e32 v58, v2
	v_mov_b32_e32 v59, v2
	v_mov_b32_e32 v60, v2
	v_mov_b32_e32 v61, v2
	v_mov_b32_e32 v62, v2
	v_mov_b32_e32 v63, v2
	v_mov_b32_e32 v64, v2
	v_mov_b32_e32 v65, v2
	v_mov_b32_e32 v66, v2
	v_mov_b32_e32 v67, v2
	v_mov_b32_e32 v68, v2
	v_mov_b32_e32 v69, v2
	v_mov_b32_e32 v70, v2
	v_mov_b32_e32 v71, v2
	v_mov_b32_e32 v72, v2
	v_mov_b32_e32 v73, v2
	v_mov_b32_e32 v82, v2
	v_mov_b32_e32 v83, v2
	v_mov_b32_e32 v84, v2
	v_mov_b32_e32 v85, v2
	v_mov_b32_e32 v86, v2
	v_mov_b32_e32 v87, v2
	v_mov_b32_e32 v88, v2
	v_mov_b32_e32 v89, v2
	v_mov_b32_e32 v98, v2
	v_mov_b32_e32 v99, v2
	v_mov_b32_e32 v100, v2
	v_mov_b32_e32 v101, v2
	v_mov_b32_e32 v102, v2
	v_mov_b32_e32 v103, v2
	v_mov_b32_e32 v104, v2
	v_mov_b32_e32 v105, v2
	v_mov_b32_e32 v114, v2
	v_mov_b32_e32 v115, v2
	v_mov_b32_e32 v116, v2
	v_mov_b32_e32 v117, v2
	v_mov_b32_e32 v118, v2
	v_mov_b32_e32 v119, v2
	v_mov_b32_e32 v120, v2
	v_mov_b32_e32 v121, v2
	v_mov_b32_e32 v74, v2
	v_mov_b32_e32 v75, v2
	v_mov_b32_e32 v76, v2
	v_mov_b32_e32 v77, v2
	v_mov_b32_e32 v78, v2
	v_mov_b32_e32 v79, v2
	v_mov_b32_e32 v80, v2
	v_mov_b32_e32 v81, v2
	v_mov_b32_e32 v90, v2
	v_mov_b32_e32 v91, v2
	v_mov_b32_e32 v92, v2
	v_mov_b32_e32 v93, v2
	v_mov_b32_e32 v94, v2
	v_mov_b32_e32 v95, v2
	v_mov_b32_e32 v96, v2
	v_mov_b32_e32 v97, v2
	v_mov_b32_e32 v106, v2
	v_mov_b32_e32 v107, v2
	v_mov_b32_e32 v108, v2
	v_mov_b32_e32 v109, v2
	v_mov_b32_e32 v110, v2
	v_mov_b32_e32 v111, v2
	v_mov_b32_e32 v112, v2
	v_mov_b32_e32 v113, v2
	v_mov_b32_e32 v122, v2
	v_mov_b32_e32 v123, v2
	v_mov_b32_e32 v124, v2
	v_mov_b32_e32 v125, v2
	v_mov_b32_e32 v126, v2
	v_mov_b32_e32 v127, v2
	v_mov_b32_e32 v128, v2
	v_mov_b32_e32 v129, v2
	v_readfirstlane_b32 s100, v168
	s_lshr_b32 s100, s100, 6
	s_cmp_ge_u32 s100, 4
	s_cbranch_scc0 .Lgp_5
	s_setprio 1
.Lgp_5:
.LBB0_1410:
	s_add_u32 s42, s30, 0x100
	s_addc_u32 s43, s31, 0
	s_add_i32 s62, 0, 0x10000
	v_add_u32_e32 v158, s62, v160
	ds_read_b128 v[154:157], v158
	ds_read_b128 v[164:167], v158 offset:1024
	ds_read_b128 v[188:191], v158 offset:2048
	ds_read_b128 v[192:195], v158 offset:3072
	s_cmp_eq_u32 s61, 16
	s_cselect_b32 s47, s9, s43
	s_cselect_b32 s46, s8, s42
	s_cselect_b32 s45, s11, s60
	s_cselect_b32 s44, s10, s59
	v_lshl_add_u64 v[158:159], s[30:31], 0, v[150:151]
	s_add_i32 m0, s48, 0xc000
	ds_read_b128 v[196:199], v162
	ds_read_b128 v[200:203], v162 offset:1024
	ds_read_b128 v[204:207], v162 offset:2048
	ds_read_b128 v[208:211], v162 offset:3072
	ds_read_b128 v[212:215], v162 offset:4096
	ds_read_b128 v[216:219], v162 offset:5120
	ds_read_b128 v[220:223], v162 offset:6144
	ds_read_b128 v[224:227], v162 offset:7168
	global_load_lds_dwordx4 v[158:159], off
	v_lshl_add_u64 v[158:159], s[30:31], 0, v[152:153]
	s_add_i32 m0, s48, 0xe000
	s_nop 0
	global_load_lds_dwordx4 v[158:159], off
	s_waitcnt lgkmcnt(8)
	s_barrier
	s_waitcnt lgkmcnt(0)
	s_waitcnt lgkmcnt(0)
	v_mfma_f32_16x16x32_bf16 v[126:129], v[154:157], v[196:199], v[126:129]
	v_mfma_f32_16x16x32_bf16 v[122:125], v[188:191], v[196:199], v[122:125]
	v_mfma_f32_16x16x32_bf16 v[110:113], v[154:157], v[204:207], v[110:113]
	v_mfma_f32_16x16x32_bf16 v[106:109], v[188:191], v[204:207], v[106:109]
	v_mfma_f32_16x16x32_bf16 v[94:97], v[154:157], v[212:215], v[94:97]
	v_mfma_f32_16x16x32_bf16 v[90:93], v[188:191], v[212:215], v[90:93]
	v_mfma_f32_16x16x32_bf16 v[78:81], v[154:157], v[220:223], v[78:81]
	v_mfma_f32_16x16x32_bf16 v[74:77], v[188:191], v[220:223], v[74:77]
	v_mfma_f32_16x16x32_bf16 v[126:129], v[164:167], v[200:203], v[126:129]
	v_mfma_f32_16x16x32_bf16 v[122:125], v[192:195], v[200:203], v[122:125]
	v_mfma_f32_16x16x32_bf16 v[110:113], v[164:167], v[208:211], v[110:113]
	v_mfma_f32_16x16x32_bf16 v[106:109], v[192:195], v[208:211], v[106:109]
	v_mfma_f32_16x16x32_bf16 v[94:97], v[164:167], v[216:219], v[94:97]
	v_mfma_f32_16x16x32_bf16 v[90:93], v[192:195], v[216:219], v[90:93]
	v_mfma_f32_16x16x32_bf16 v[78:81], v[164:167], v[224:227], v[78:81]
	v_mfma_f32_16x16x32_bf16 v[74:77], v[192:195], v[224:227], v[74:77]
	s_barrier
	s_add_i32 s63, 0, 0x14000
	v_add_u32_e32 v158, s63, v160
	s_add_i32 s30, s62, s28
	ds_read_b128 v[228:231], v158
	ds_read_b128 v[232:235], v158 offset:1024
	ds_read_b128 v[236:239], v158 offset:2048
	ds_read_b128 v[240:243], v158 offset:3072
	v_lshl_add_u64 v[158:159], s[44:45], 0, v[0:1]
	s_mov_b32 m0, s30
	v_lshl_add_u64 v[178:179], s[44:45], 0, v[148:149]
	global_load_lds_dwordx4 v[158:159], off
	s_add_i32 m0, s30, 0x2000
	s_nop 0
	global_load_lds_dwordx4 v[178:179], off
	s_barrier
; #define PG8_STAGE(bufoff, gbase, voff) do { _Pragma("unroll") for (int _i = 0; _i < 2; ++_i) \
;     __builtin_amdgcn_global_load_lds((const unsigned*)((const char*)(gbase) + (voff)[_i]), (PG8_LAS unsigned*)(lds + (bufoff) + ldsw + _i * 8192), 16, 0, 0); } while (0)
; #define PG8_LDA(dst, b, h) do { _Pragma("unroll") for (int m = 0; m < 4; ++m) _Pragma("unroll") for (int k = 0; k < 2; ++k) dst[m][k] = *(const PG8_LAS bf16x8*)(lds + PG8_SA(b, h) + aoff + m * 2048 + k * 1024); } while (0)
; #define PG8_LDB(dst, b, h) do { _Pragma("unroll") for (int n = 0; n < 2; ++n) _Pragma("unroll") for (int k = 0; k < 2; ++k) dst[n][k] = *(const PG8_LAS bf16x8*)(lds + PG8_SB(b, h) + boff + n * 2048 + k * 1024); } while (0)
; #define PG8_MMA(ai, bj, At, Bt) do { __builtin_amdgcn_s_setprio(1); _Pragma("unroll") for (int m = 0; m < 4; ++m) _Pragma("unroll") for (int n = 0; n < 2; ++n) _Pragma("unroll") for (int k = 0; k < 2; ++k) \
;     acc[ai][bj][m][n] = __builtin_amdgcn_mfma_f32_16x16x32_bf16(Bt[n][k], At[m][k], acc[ai][bj][m][n], 0, 0, 0); __builtin_amdgcn_s_setprio(0); } while (0)
; #define PG8_WAIT_V(n) asm volatile("s_waitcnt vmcnt(" #n ")" ::: "memory")
; #define PG8_WAIT_L(n) asm volatile("s_waitcnt lgkmcnt(" #n ")" ::: "memory")
; #define PG8_BAR __builtin_amdgcn_s_barrier()
; #define PG8_SCHED __builtin_amdgcn_sched_barrier(0)
; template <class Epi>
; __device__ __forceinline__ void gemm_phase(PG8_LAS unsigned char* lds, const Gemm g, const StaticOrder& S, const Epi& E) {
;     ...
;       PG8_BAR; PG8_WAIT_L(0); PG8_MMA(0, 1, At, B1); PG8_BAR;
;       PG8_LDA(At, 0, 1); PG8_STAGE(PG8_SA(0, 0), a2, voffA);
;       PG8_BAR; PG8_WAIT_L(0); PG8_MMA(1, 0, At, B0); PG8_BAR; PG8_SCHED;
;       PG8_STAGE(PG8_SB(0, 1), b2 + hstep, voffB);
;       PG8_WAIT_V(6); PG8_BAR; PG8_MMA(1, 1, At, B1); PG8_BAR;
;       PG8_LDB(B0, 1, 0); PG8_SCHED; PG8_LDA(At, 1, 0); PG8_STAGE(PG8_SA(0, 1), a2 + hstep, voffA);
;       PG8_WAIT_L(8); PG8_BAR; PG8_WAIT_L(0); PG8_MMA(0, 0, At, B0); PG8_BAR; PG8_SCHED;
;       PG8_LDB(B1, 1, 1); PG8_STAGE(PG8_SB(1, 0), b3, voffB);
	s_waitcnt lgkmcnt(0)
	s_waitcnt lgkmcnt(0)
	v_mfma_f32_16x16x32_bf16 v[118:121], v[228:231], v[196:199], v[118:121]
	v_mfma_f32_16x16x32_bf16 v[114:117], v[236:239], v[196:199], v[114:117]
	v_mfma_f32_16x16x32_bf16 v[102:105], v[228:231], v[204:207], v[102:105]
	v_mfma_f32_16x16x32_bf16 v[98:101], v[236:239], v[204:207], v[98:101]
	v_mfma_f32_16x16x32_bf16 v[86:89], v[228:231], v[212:215], v[86:89]
	v_mfma_f32_16x16x32_bf16 v[82:85], v[236:239], v[212:215], v[82:85]
	v_mfma_f32_16x16x32_bf16 v[70:73], v[228:231], v[220:223], v[70:73]
	v_mfma_f32_16x16x32_bf16 v[66:69], v[236:239], v[220:223], v[66:69]
	v_mfma_f32_16x16x32_bf16 v[118:121], v[232:235], v[200:203], v[118:121]
	v_mfma_f32_16x16x32_bf16 v[114:117], v[240:243], v[200:203], v[114:117]
	v_mfma_f32_16x16x32_bf16 v[102:105], v[232:235], v[208:211], v[102:105]
	v_mfma_f32_16x16x32_bf16 v[98:101], v[240:243], v[208:211], v[98:101]
	v_mfma_f32_16x16x32_bf16 v[86:89], v[232:235], v[216:219], v[86:89]
	v_mfma_f32_16x16x32_bf16 v[82:85], v[240:243], v[216:219], v[82:85]
	v_mfma_f32_16x16x32_bf16 v[70:73], v[232:235], v[224:227], v[70:73]
	v_mfma_f32_16x16x32_bf16 v[66:69], v[240:243], v[224:227], v[66:69]
	s_mov_b32 m0, s48
	v_lshl_add_u64 v[244:245], s[46:47], 0, v[0:1]
	s_barrier
	ds_read_b128 v[196:199], v162 offset:16384
	ds_read_b128 v[200:203], v162 offset:17408
	ds_read_b128 v[204:207], v162 offset:18432
	ds_read_b128 v[208:211], v162 offset:19456
	ds_read_b128 v[212:215], v162 offset:20480
	ds_read_b128 v[216:219], v162 offset:21504
	ds_read_b128 v[220:223], v162 offset:22528
	ds_read_b128 v[224:227], v162 offset:23552
	global_load_lds_dwordx4 v[244:245], off
	v_lshl_add_u64 v[246:247], s[46:47], 0, v[148:149]
	s_mov_b32 m0, s49
	s_nop 0
	global_load_lds_dwordx4 v[246:247], off
	s_barrier
	s_waitcnt lgkmcnt(0)
	s_waitcnt lgkmcnt(0)
	v_mfma_f32_16x16x32_bf16 v[62:65], v[154:157], v[196:199], v[62:65]
	v_mfma_f32_16x16x32_bf16 v[58:61], v[188:191], v[196:199], v[58:61]
	v_mfma_f32_16x16x32_bf16 v[46:49], v[154:157], v[204:207], v[46:49]
	v_mfma_f32_16x16x32_bf16 v[42:45], v[188:191], v[204:207], v[42:45]
	v_mfma_f32_16x16x32_bf16 v[30:33], v[154:157], v[212:215], v[30:33]
	v_mfma_f32_16x16x32_bf16 v[26:29], v[188:191], v[212:215], v[26:29]
	v_mfma_f32_16x16x32_bf16 v[14:17], v[154:157], v[220:223], v[14:17]
	v_mfma_f32_16x16x32_bf16 v[10:13], v[188:191], v[220:223], v[10:13]
	v_mfma_f32_16x16x32_bf16 v[62:65], v[164:167], v[200:203], v[62:65]
	v_mfma_f32_16x16x32_bf16 v[58:61], v[192:195], v[200:203], v[58:61]
	v_mfma_f32_16x16x32_bf16 v[46:49], v[164:167], v[208:211], v[46:49]
	v_mfma_f32_16x16x32_bf16 v[42:45], v[192:195], v[208:211], v[42:45]
	v_mfma_f32_16x16x32_bf16 v[30:33], v[164:167], v[216:219], v[30:33]
	v_mfma_f32_16x16x32_bf16 v[26:29], v[192:195], v[216:219], v[26:29]
	v_mfma_f32_16x16x32_bf16 v[14:17], v[164:167], v[224:227], v[14:17]
	v_mfma_f32_16x16x32_bf16 v[10:13], v[192:195], v[224:227], v[10:13]
	s_barrier
	s_add_u32 s30, s44, 0x50000
	s_addc_u32 s31, s45, 0
	s_add_i32 s62, s63, s28
	v_lshl_add_u64 v[154:155], s[30:31], 0, v[0:1]
	s_mov_b32 m0, s62
	s_nop 0
	global_load_lds_dwordx4 v[154:155], off
	v_lshl_add_u64 v[154:155], s[30:31], 0, v[148:149]
	s_add_i32 m0, s62, 0x2000
	s_nop 0
	global_load_lds_dwordx4 v[154:155], off
	s_waitcnt vmcnt(6)
	s_barrier
	v_mfma_f32_16x16x32_bf16 v[54:57], v[228:231], v[196:199], v[54:57]
	v_mfma_f32_16x16x32_bf16 v[50:53], v[236:239], v[196:199], v[50:53]
	v_mfma_f32_16x16x32_bf16 v[38:41], v[228:231], v[204:207], v[38:41]
	v_mfma_f32_16x16x32_bf16 v[34:37], v[236:239], v[204:207], v[34:37]
	v_mfma_f32_16x16x32_bf16 v[22:25], v[228:231], v[212:215], v[22:25]
	v_mfma_f32_16x16x32_bf16 v[18:21], v[236:239], v[212:215], v[18:21]
	v_mfma_f32_16x16x32_bf16 v[6:9], v[228:231], v[220:223], v[6:9]
	v_mfma_f32_16x16x32_bf16 v[2:5], v[236:239], v[220:223], v[2:5]
	v_mfma_f32_16x16x32_bf16 v[54:57], v[232:235], v[200:203], v[54:57]
	v_mfma_f32_16x16x32_bf16 v[50:53], v[240:243], v[200:203], v[50:53]
	v_mfma_f32_16x16x32_bf16 v[38:41], v[232:235], v[208:211], v[38:41]
	v_mfma_f32_16x16x32_bf16 v[34:37], v[240:243], v[208:211], v[34:37]
	v_mfma_f32_16x16x32_bf16 v[22:25], v[232:235], v[216:219], v[22:25]
	v_mfma_f32_16x16x32_bf16 v[18:21], v[240:243], v[216:219], v[18:21]
	v_mfma_f32_16x16x32_bf16 v[6:9], v[232:235], v[224:227], v[6:9]
	v_mfma_f32_16x16x32_bf16 v[2:5], v[240:243], v[224:227], v[2:5]
	s_add_i32 s62, 0, 0x18000
	v_add_u32_e32 v163, s62, v160
	s_barrier
	ds_read_b128 v[154:157], v163
	ds_read_b128 v[164:167], v163 offset:1024
	ds_read_b128 v[188:191], v163 offset:2048
	ds_read_b128 v[192:195], v163 offset:3072
	s_add_u32 s30, s46, 0x50000
	s_addc_u32 s31, s47, 0
	s_mov_b32 m0, s50
	v_lshl_add_u64 v[228:229], s[30:31], 0, v[0:1]
	ds_read_b128 v[196:199], v162 offset:32768
	ds_read_b128 v[200:203], v162 offset:33792
	ds_read_b128 v[204:207], v162 offset:34816
	ds_read_b128 v[208:211], v162 offset:35840
	ds_read_b128 v[212:215], v162 offset:36864
	ds_read_b128 v[216:219], v162 offset:37888
	ds_read_b128 v[220:223], v162 offset:38912
	ds_read_b128 v[224:227], v162 offset:39936
	global_load_lds_dwordx4 v[228:229], off
	v_lshl_add_u64 v[228:229], s[30:31], 0, v[148:149]
	s_mov_b32 m0, s51
	s_nop 0
	global_load_lds_dwordx4 v[228:229], off
	s_waitcnt lgkmcnt(8)
	s_barrier
; #define PG8_STAGE(bufoff, gbase, voff) do { _Pragma("unroll") for (int _i = 0; _i < 2; ++_i) \
;     __builtin_amdgcn_global_load_lds((const unsigned*)((const char*)(gbase) + (voff)[_i]), (PG8_LAS unsigned*)(lds + (bufoff) + ldsw + _i * 8192), 16, 0, 0); } while (0)
; #define PG8_LDA(dst, b, h) do { _Pragma("unroll") for (int m = 0; m < 4; ++m) _Pragma("unroll") for (int k = 0; k < 2; ++k) dst[m][k] = *(const PG8_LAS bf16x8*)(lds + PG8_SA(b, h) + aoff + m * 2048 + k * 1024); } while (0)
; #define PG8_LDB(dst, b, h) do { _Pragma("unroll") for (int n = 0; n < 2; ++n) _Pragma("unroll") for (int k = 0; k < 2; ++k) dst[n][k] = *(const PG8_LAS bf16x8*)(lds + PG8_SB(b, h) + boff + n * 2048 + k * 1024); } while (0)
; #define PG8_MMA(ai, bj, At, Bt) do { __builtin_amdgcn_s_setprio(1); _Pragma("unroll") for (int m = 0; m < 4; ++m) _Pragma("unroll") for (int n = 0; n < 2; ++n) _Pragma("unroll") for (int k = 0; k < 2; ++k) \
;     acc[ai][bj][m][n] = __builtin_amdgcn_mfma_f32_16x16x32_bf16(Bt[n][k], At[m][k], acc[ai][bj][m][n], 0, 0, 0); __builtin_amdgcn_s_setprio(0); } while (0)
; #define PG8_WAIT_V(n) asm volatile("s_waitcnt vmcnt(" #n ")" ::: "memory")
; #define PG8_WAIT_L(n) asm volatile("s_waitcnt lgkmcnt(" #n ")" ::: "memory")
; #define PG8_BAR __builtin_amdgcn_s_barrier()
; #define PG8_SCHED __builtin_amdgcn_sched_barrier(0)
; template <class Epi>
; __device__ __forceinline__ void gemm_phase(PG8_LAS unsigned char* lds, const Gemm g, const StaticOrder& S, const Epi& E) {
;     ...
;       PG8_WAIT_L(8); PG8_BAR; PG8_WAIT_L(0); PG8_MMA(0, 0, At, B0); PG8_BAR; PG8_SCHED;
;       PG8_LDB(B1, 1, 1); PG8_STAGE(PG8_SB(1, 0), b3, voffB);
;       PG8_BAR; PG8_WAIT_L(0); PG8_MMA(0, 1, At, B1); PG8_BAR;
;       PG8_LDA(At, 1, 1); PG8_STAGE(PG8_SA(1, 0), a3, voffA);
;       PG8_BAR; PG8_WAIT_L(0); PG8_MMA(1, 0, At, B0); PG8_BAR; PG8_SCHED;
;       PG8_STAGE(PG8_SB(1, 1), b3 + hstep, voffB);
;       PG8_WAIT_V(6); PG8_BAR; PG8_MMA(1, 1, At, B1); PG8_BAR;
;     }
;     E(acc, cur, wr, wc, fr, fq);
	s_waitcnt lgkmcnt(0)
	s_waitcnt lgkmcnt(0)
	v_mfma_f32_16x16x32_bf16 v[126:129], v[154:157], v[196:199], v[126:129]
	v_mfma_f32_16x16x32_bf16 v[122:125], v[188:191], v[196:199], v[122:125]
	v_mfma_f32_16x16x32_bf16 v[110:113], v[154:157], v[204:207], v[110:113]
	v_mfma_f32_16x16x32_bf16 v[106:109], v[188:191], v[204:207], v[106:109]
	v_mfma_f32_16x16x32_bf16 v[94:97], v[154:157], v[212:215], v[94:97]
	v_mfma_f32_16x16x32_bf16 v[90:93], v[188:191], v[212:215], v[90:93]
	v_mfma_f32_16x16x32_bf16 v[78:81], v[154:157], v[220:223], v[78:81]
	v_mfma_f32_16x16x32_bf16 v[74:77], v[188:191], v[220:223], v[74:77]
	v_mfma_f32_16x16x32_bf16 v[126:129], v[164:167], v[200:203], v[126:129]
	v_mfma_f32_16x16x32_bf16 v[122:125], v[192:195], v[200:203], v[122:125]
	v_mfma_f32_16x16x32_bf16 v[110:113], v[164:167], v[208:211], v[110:113]
	v_mfma_f32_16x16x32_bf16 v[106:109], v[192:195], v[208:211], v[106:109]
	v_mfma_f32_16x16x32_bf16 v[94:97], v[164:167], v[216:219], v[94:97]
	v_mfma_f32_16x16x32_bf16 v[90:93], v[192:195], v[216:219], v[90:93]
	v_mfma_f32_16x16x32_bf16 v[78:81], v[164:167], v[224:227], v[78:81]
	v_mfma_f32_16x16x32_bf16 v[74:77], v[192:195], v[224:227], v[74:77]
	s_barrier
	s_add_i32 s46, 0, 0x1c000
	s_add_i32 s30, s62, s28
	v_add_u32_e32 v163, s46, v160
	v_lshl_add_u64 v[158:159], v[158:159], 0, s[4:5]
	s_mov_b32 m0, s30
	ds_read_b128 v[228:231], v163
	ds_read_b128 v[232:235], v163 offset:1024
	ds_read_b128 v[236:239], v163 offset:2048
	ds_read_b128 v[240:243], v163 offset:3072
	global_load_lds_dwordx4 v[158:159], off
	v_lshl_add_u64 v[158:159], v[178:179], 0, s[4:5]
	s_add_i32 m0, s30, 0x2000
	s_nop 0
	global_load_lds_dwordx4 v[158:159], off
	s_barrier
	s_waitcnt lgkmcnt(0)
	s_waitcnt lgkmcnt(0)
	v_mfma_f32_16x16x32_bf16 v[118:121], v[228:231], v[196:199], v[118:121]
	v_mfma_f32_16x16x32_bf16 v[114:117], v[236:239], v[196:199], v[114:117]
	v_mfma_f32_16x16x32_bf16 v[102:105], v[228:231], v[204:207], v[102:105]
	v_mfma_f32_16x16x32_bf16 v[98:101], v[236:239], v[204:207], v[98:101]
	v_mfma_f32_16x16x32_bf16 v[86:89], v[228:231], v[212:215], v[86:89]
	v_mfma_f32_16x16x32_bf16 v[82:85], v[236:239], v[212:215], v[82:85]
	v_mfma_f32_16x16x32_bf16 v[70:73], v[228:231], v[220:223], v[70:73]
	v_mfma_f32_16x16x32_bf16 v[66:69], v[236:239], v[220:223], v[66:69]
	v_mfma_f32_16x16x32_bf16 v[118:121], v[232:235], v[200:203], v[118:121]
	v_mfma_f32_16x16x32_bf16 v[114:117], v[240:243], v[200:203], v[114:117]
	v_mfma_f32_16x16x32_bf16 v[102:105], v[232:235], v[208:211], v[102:105]
	v_mfma_f32_16x16x32_bf16 v[98:101], v[240:243], v[208:211], v[98:101]
	v_mfma_f32_16x16x32_bf16 v[86:89], v[232:235], v[216:219], v[86:89]
	v_mfma_f32_16x16x32_bf16 v[82:85], v[240:243], v[216:219], v[82:85]
	v_mfma_f32_16x16x32_bf16 v[70:73], v[232:235], v[224:227], v[70:73]
	v_mfma_f32_16x16x32_bf16 v[66:69], v[240:243], v[224:227], v[66:69]
	s_mov_b32 m0, s52
	v_lshl_add_u64 v[158:159], v[244:245], 0, s[4:5]
	s_barrier
	ds_read_b128 v[196:199], v162 offset:49152
	ds_read_b128 v[200:203], v162 offset:50176
	ds_read_b128 v[204:207], v162 offset:51200
	ds_read_b128 v[208:211], v162 offset:52224
	ds_read_b128 v[212:215], v162 offset:53248
	ds_read_b128 v[216:219], v162 offset:54272
	ds_read_b128 v[220:223], v162 offset:55296
	ds_read_b128 v[224:227], v162 offset:56320
	global_load_lds_dwordx4 v[158:159], off
	v_lshl_add_u64 v[158:159], v[246:247], 0, s[4:5]
	s_mov_b32 m0, s53
	s_nop 0
	global_load_lds_dwordx4 v[158:159], off
	s_barrier
	s_waitcnt lgkmcnt(0)
	s_waitcnt lgkmcnt(0)
	v_mfma_f32_16x16x32_bf16 v[62:65], v[154:157], v[196:199], v[62:65]
	v_mfma_f32_16x16x32_bf16 v[58:61], v[188:191], v[196:199], v[58:61]
	v_mfma_f32_16x16x32_bf16 v[46:49], v[154:157], v[204:207], v[46:49]
	v_mfma_f32_16x16x32_bf16 v[42:45], v[188:191], v[204:207], v[42:45]
	v_mfma_f32_16x16x32_bf16 v[30:33], v[154:157], v[212:215], v[30:33]
	v_mfma_f32_16x16x32_bf16 v[26:29], v[188:191], v[212:215], v[26:29]
	v_mfma_f32_16x16x32_bf16 v[14:17], v[154:157], v[220:223], v[14:17]
	v_mfma_f32_16x16x32_bf16 v[10:13], v[188:191], v[220:223], v[10:13]
	v_mfma_f32_16x16x32_bf16 v[62:65], v[164:167], v[200:203], v[62:65]
	v_mfma_f32_16x16x32_bf16 v[58:61], v[192:195], v[200:203], v[58:61]
	v_mfma_f32_16x16x32_bf16 v[46:49], v[164:167], v[208:211], v[46:49]
	v_mfma_f32_16x16x32_bf16 v[42:45], v[192:195], v[208:211], v[42:45]
	v_mfma_f32_16x16x32_bf16 v[30:33], v[164:167], v[216:219], v[30:33]
	v_mfma_f32_16x16x32_bf16 v[26:29], v[192:195], v[216:219], v[26:29]
	v_mfma_f32_16x16x32_bf16 v[14:17], v[164:167], v[224:227], v[14:17]
	v_mfma_f32_16x16x32_bf16 v[10:13], v[192:195], v[224:227], v[10:13]
	s_barrier
	s_add_u32 s30, s44, 0x50080
	s_addc_u32 s31, s45, 0
	s_add_i32 s44, s46, s28
	v_lshl_add_u64 v[154:155], s[30:31], 0, v[0:1]
	s_mov_b32 m0, s44
	s_nop 0
	global_load_lds_dwordx4 v[154:155], off
	v_lshl_add_u64 v[154:155], s[30:31], 0, v[148:149]
	s_add_i32 m0, s44, 0x2000
	s_nop 0
	global_load_lds_dwordx4 v[154:155], off
	s_waitcnt vmcnt(6)
	s_barrier
	v_mfma_f32_16x16x32_bf16 v[54:57], v[228:231], v[196:199], v[54:57]
	v_mfma_f32_16x16x32_bf16 v[50:53], v[236:239], v[196:199], v[50:53]
	v_mfma_f32_16x16x32_bf16 v[38:41], v[228:231], v[204:207], v[38:41]
	v_mfma_f32_16x16x32_bf16 v[34:37], v[236:239], v[204:207], v[34:37]
	v_mfma_f32_16x16x32_bf16 v[22:25], v[228:231], v[212:215], v[22:25]
	v_mfma_f32_16x16x32_bf16 v[18:21], v[236:239], v[212:215], v[18:21]
	v_mfma_f32_16x16x32_bf16 v[6:9], v[228:231], v[220:223], v[6:9]
	v_mfma_f32_16x16x32_bf16 v[2:5], v[236:239], v[220:223], v[2:5]
	v_mfma_f32_16x16x32_bf16 v[54:57], v[232:235], v[200:203], v[54:57]
	v_mfma_f32_16x16x32_bf16 v[50:53], v[240:243], v[200:203], v[50:53]
	v_mfma_f32_16x16x32_bf16 v[38:41], v[232:235], v[208:211], v[38:41]
	v_mfma_f32_16x16x32_bf16 v[34:37], v[240:243], v[208:211], v[34:37]
	v_mfma_f32_16x16x32_bf16 v[22:25], v[232:235], v[216:219], v[22:25]
	v_mfma_f32_16x16x32_bf16 v[18:21], v[240:243], v[216:219], v[18:21]
	v_mfma_f32_16x16x32_bf16 v[6:9], v[232:235], v[224:227], v[6:9]
	v_mfma_f32_16x16x32_bf16 v[2:5], v[240:243], v[224:227], v[2:5]
	s_add_i32 s61, s61, 2
	s_add_u32 s59, s59, 0x100
	s_addc_u32 s60, s60, 0
	s_cmp_gt_u32 s61, 17
	s_mov_b64 s[30:31], s[42:43]
	s_barrier
	s_cbranch_scc0 .LBB0_1410
	v_readlane_b32 s80, v254, 5
	v_readlane_b32 s81, v254, 6
	v_readlane_b32 s82, v254, 7
	v_readlane_b32 s83, v254, 8
	s_cmp_ge_i32 s58, 65
	s_cselect_b32 s68, 1, 0
	s_mul_i32 s69, s68, 65
	s_sub_i32 s69, s58, s69
	s_cmp_eq_u32 s69, 0
	s_cbranch_scc1 .LepiC_ctx
	s_add_i32 s69, s69, -1
	s_lshl_b32 s69, s69, 8
	s_lshl_b32 s70, s68, 14
	s_add_i32 s69, s69, s70
	s_lshl_b32 s69, s69, 12
	s_add_u32 s70, s80, s69
	s_addc_u32 s71, s81, 0
	s_mul_i32 s68, s68, 0x3000
	s_branch .LepiC_go

; #define PG8_STAGE(bufoff, gbase, voff) do { _Pragma("unroll") for (int _i = 0; _i < 2; ++_i) \
;     __builtin_amdgcn_global_load_lds((const unsigned*)((const char*)(gbase) + (voff)[_i]), (PG8_LAS unsigned*)(lds + (bufoff) + ldsw + _i * 8192), 16, 0, 0); } while (0)
; #define PG8_LDA(dst, b, h) do { _Pragma("unroll") for (int m = 0; m < 4; ++m) _Pragma("unroll") for (int k = 0; k < 2; ++k) dst[m][k] = *(const PG8_LAS bf16x8*)(lds + PG8_SA(b, h) + aoff + m * 2048 + k * 1024); } while (0)
; #define PG8_LDB(dst, b, h) do { _Pragma("unroll") for (int n = 0; n < 2; ++n) _Pragma("unroll") for (int k = 0; k < 2; ++k) dst[n][k] = *(const PG8_LAS bf16x8*)(lds + PG8_SB(b, h) + boff + n * 2048 + k * 1024); } while (0)
; #define PG8_MMA(ai, bj, At, Bt) do { __builtin_amdgcn_s_setprio(1); _Pragma("unroll") for (int m = 0; m < 4; ++m) _Pragma("unroll") for (int n = 0; n < 2; ++n) _Pragma("unroll") for (int k = 0; k < 2; ++k) \
;     acc[ai][bj][m][n] = __builtin_amdgcn_mfma_f32_16x16x32_bf16(Bt[n][k], At[m][k], acc[ai][bj][m][n], 0, 0, 0); __builtin_amdgcn_s_setprio(0); } while (0)
; #define PG8_WAIT_L(n) asm volatile("s_waitcnt lgkmcnt(" #n ")" ::: "memory")
; #define PG8_BAR __builtin_amdgcn_s_barrier()
; template <class Epi>
; __device__ __forceinline__ void gemm_phase(PG8_LAS unsigned char* lds, const Gemm g, const StaticOrder& S, const Epi& E) {
;     ...
;     const bool has_next = S.next(ui + 1, nxt);
;     const char* nA = has_next ? (const char*)g.A + (size_t)nxt.pm * tstep : cA; const char* nB = has_next ? (const char*)g.Bt + (size_t)nxt.pn * tstep : cB;
;     for (int t = 0; t < nt; t += 2) {
;       const bool last = (t == nt - 2);
;       const char* a1 = cA + (size_t)(t + 1) * kstep;
;       const char* a2 = last ? nA : cA + (size_t)(t + 2) * kstep; const char* b2 = last ? nB : cB + (size_t)(t + 2) * kstep;
;       const char* a3 = a2 + kstep; const char* b3 = b2 + kstep;
;       PG8_LDB(B0, 0, 0); PG8_SCHED; PG8_LDA(At, 0, 0); PG8_STAGE(PG8_SA(1, 1), a1 + hstep, voffA);
;       PG8_WAIT_L(8); PG8_BAR; PG8_WAIT_L(0); PG8_MMA(0, 0, At, B0); PG8_BAR; PG8_SCHED;
;     ...
; #pragma unroll
;     for (int a = 0; a < 2; ++a)
; #pragma unroll
;       for (int b = 0; b < 2; ++b)
; #pragma unroll
;         for (int m = 0; m < 4; ++m)
; #pragma unroll
;           for (int n = 0; n < 2; ++n) acc[a][b][m][n] = (f32x4){0.f, 0.f, 0.f, 0.f};
;     cur = nxt; cA = nA; cB = nB; ++ui;
.LBB0_1592:
	s_ashr_i32 s9, s8, 31
	v_cmp_lt_i64_e32 vcc, s[10:11], v[144:145]
	s_lshl_b64 s[10:11], s[8:9], 19
	s_add_u32 s10, s24, s10
	s_addc_u32 s11, s25, s11
	s_and_b64 s[12:13], vcc, exec
	s_cselect_b32 s9, s11, s45
	s_cselect_b32 s31, s10, s44
	s_ashr_i32 s7, s6, 31
	s_lshl_b64 s[12:13], s[6:7], 19
	s_add_u32 s12, s22, s12
	s_addc_u32 s13, s23, s13
	s_and_b64 s[48:49], vcc, exec
	s_cselect_b32 s7, s13, s47
	s_cselect_b32 s43, s12, s46
	s_add_u32 s44, s44, 0x40080
	s_addc_u32 s45, s45, 0
	s_add_u32 s56, s46, 0x100
	v_mov_b32_e32 v2, 0
	s_addc_u32 s57, s47, 0
	s_mov_b32 s58, -2
	v_mov_b32_e32 v3, v2
	v_mov_b32_e32 v4, v2
	v_mov_b32_e32 v5, v2
	v_mov_b32_e32 v6, v2
	v_mov_b32_e32 v7, v2
	v_mov_b32_e32 v8, v2
	v_mov_b32_e32 v9, v2
	v_mov_b32_e32 v18, v2
	v_mov_b32_e32 v19, v2
	v_mov_b32_e32 v20, v2
	v_mov_b32_e32 v21, v2
	v_mov_b32_e32 v22, v2
	v_mov_b32_e32 v23, v2
	v_mov_b32_e32 v24, v2
	v_mov_b32_e32 v25, v2
	v_mov_b32_e32 v34, v2
	v_mov_b32_e32 v35, v2
	v_mov_b32_e32 v36, v2
	v_mov_b32_e32 v37, v2
	v_mov_b32_e32 v38, v2
	v_mov_b32_e32 v39, v2
	v_mov_b32_e32 v40, v2
	v_mov_b32_e32 v41, v2
	v_mov_b32_e32 v50, v2
	v_mov_b32_e32 v51, v2
	v_mov_b32_e32 v52, v2
	v_mov_b32_e32 v53, v2
	v_mov_b32_e32 v54, v2
	v_mov_b32_e32 v55, v2
	v_mov_b32_e32 v56, v2
	v_mov_b32_e32 v57, v2
	v_mov_b32_e32 v10, v2
	v_mov_b32_e32 v11, v2
	v_mov_b32_e32 v12, v2
	v_mov_b32_e32 v13, v2
	v_mov_b32_e32 v14, v2
	v_mov_b32_e32 v15, v2
	v_mov_b32_e32 v16, v2
	v_mov_b32_e32 v17, v2
	v_mov_b32_e32 v26, v2
	v_mov_b32_e32 v27, v2
	v_mov_b32_e32 v28, v2
	v_mov_b32_e32 v29, v2
	v_mov_b32_e32 v30, v2
	v_mov_b32_e32 v31, v2
	v_mov_b32_e32 v32, v2
	v_mov_b32_e32 v33, v2
	v_mov_b32_e32 v42, v2
	v_mov_b32_e32 v43, v2
	v_mov_b32_e32 v44, v2
	v_mov_b32_e32 v45, v2
	v_mov_b32_e32 v46, v2
	v_mov_b32_e32 v47, v2
	v_mov_b32_e32 v48, v2
	v_mov_b32_e32 v49, v2
	v_mov_b32_e32 v58, v2
	v_mov_b32_e32 v59, v2
	v_mov_b32_e32 v60, v2
	v_mov_b32_e32 v61, v2
	v_mov_b32_e32 v62, v2
	v_mov_b32_e32 v63, v2
	v_mov_b32_e32 v64, v2
	v_mov_b32_e32 v65, v2
	v_mov_b32_e32 v66, v2
	v_mov_b32_e32 v67, v2
	v_mov_b32_e32 v68, v2
	v_mov_b32_e32 v69, v2
	v_mov_b32_e32 v70, v2
	v_mov_b32_e32 v71, v2
	v_mov_b32_e32 v72, v2
	v_mov_b32_e32 v73, v2
	v_mov_b32_e32 v82, v2
	v_mov_b32_e32 v83, v2
	v_mov_b32_e32 v84, v2
	v_mov_b32_e32 v85, v2
	v_mov_b32_e32 v86, v2
	v_mov_b32_e32 v87, v2
	v_mov_b32_e32 v88, v2
	v_mov_b32_e32 v89, v2
	v_mov_b32_e32 v98, v2
	v_mov_b32_e32 v99, v2
	v_mov_b32_e32 v100, v2
	v_mov_b32_e32 v101, v2
	v_mov_b32_e32 v102, v2
	v_mov_b32_e32 v103, v2
	v_mov_b32_e32 v104, v2
	v_mov_b32_e32 v105, v2
	v_mov_b32_e32 v114, v2
	v_mov_b32_e32 v115, v2
	v_mov_b32_e32 v116, v2
	v_mov_b32_e32 v117, v2
	v_mov_b32_e32 v118, v2
	v_mov_b32_e32 v119, v2
	v_mov_b32_e32 v120, v2
	v_mov_b32_e32 v121, v2
	v_mov_b32_e32 v74, v2
	v_mov_b32_e32 v75, v2
	v_mov_b32_e32 v76, v2
	v_mov_b32_e32 v77, v2
	v_mov_b32_e32 v78, v2
	v_mov_b32_e32 v79, v2
	v_mov_b32_e32 v80, v2
	v_mov_b32_e32 v81, v2
	v_mov_b32_e32 v90, v2
	v_mov_b32_e32 v91, v2
	v_mov_b32_e32 v92, v2
	v_mov_b32_e32 v93, v2
	v_mov_b32_e32 v94, v2
	v_mov_b32_e32 v95, v2
	v_mov_b32_e32 v96, v2
	v_mov_b32_e32 v97, v2
	v_mov_b32_e32 v106, v2
	v_mov_b32_e32 v107, v2
	v_mov_b32_e32 v108, v2
	v_mov_b32_e32 v109, v2
	v_mov_b32_e32 v110, v2
	v_mov_b32_e32 v111, v2
	v_mov_b32_e32 v112, v2
	v_mov_b32_e32 v113, v2
	v_mov_b32_e32 v122, v2
	v_mov_b32_e32 v123, v2
	v_mov_b32_e32 v124, v2
	v_mov_b32_e32 v125, v2
	v_mov_b32_e32 v126, v2
	v_mov_b32_e32 v127, v2
	v_mov_b32_e32 v128, v2
	v_mov_b32_e32 v129, v2
	v_readfirstlane_b32 s100, v168
	s_lshr_b32 s100, s100, 6
	s_cmp_ge_u32 s100, 4
	s_cbranch_scc0 .Lgp_6
	s_setprio 1
.Lgp_6:
.LBB0_1593:
	s_add_u32 s46, s44, 0xfffc0080
	s_addc_u32 s47, s45, -1
	s_add_i32 s59, 0, 0x10000
	v_add_u32_e32 v0, s59, v164
	ds_read_b128 v[156:159], v0
	ds_read_b128 v[160:163], v0 offset:1024
	ds_read_b128 v[188:191], v0 offset:2048
	ds_read_b128 v[192:195], v0 offset:3072
	s_cmp_eq_u32 s58, 12
	s_cselect_b32 s49, s9, s47
	s_cselect_b32 s48, s31, s46
	s_cselect_b32 s47, s7, s57
	s_cselect_b32 s46, s43, s56
	v_lshl_add_u64 v[228:229], s[44:45], 0, v[152:153]
	s_add_i32 m0, s28, 0xc000
	ds_read_b128 v[196:199], v166
	ds_read_b128 v[200:203], v166 offset:1024
	ds_read_b128 v[204:207], v166 offset:2048
	ds_read_b128 v[208:211], v166 offset:3072
	ds_read_b128 v[212:215], v166 offset:4096
	ds_read_b128 v[216:219], v166 offset:5120
	ds_read_b128 v[220:223], v166 offset:6144
	ds_read_b128 v[224:227], v166 offset:7168
	global_load_lds_dwordx4 v[228:229], off
	v_lshl_add_u64 v[228:229], s[44:45], 0, v[154:155]
	s_add_i32 m0, s28, 0xe000
	s_nop 0
	global_load_lds_dwordx4 v[228:229], off
	s_waitcnt lgkmcnt(8)
	s_barrier
	s_waitcnt lgkmcnt(0)
	s_waitcnt lgkmcnt(0)
	v_mfma_f32_16x16x32_bf16 v[126:129], v[156:159], v[196:199], v[126:129]
	v_mfma_f32_16x16x32_bf16 v[122:125], v[188:191], v[196:199], v[122:125]
	v_mfma_f32_16x16x32_bf16 v[110:113], v[156:159], v[204:207], v[110:113]
	v_mfma_f32_16x16x32_bf16 v[106:109], v[188:191], v[204:207], v[106:109]
	v_mfma_f32_16x16x32_bf16 v[94:97], v[156:159], v[212:215], v[94:97]
	v_mfma_f32_16x16x32_bf16 v[90:93], v[188:191], v[212:215], v[90:93]
	v_mfma_f32_16x16x32_bf16 v[78:81], v[156:159], v[220:223], v[78:81]
	v_mfma_f32_16x16x32_bf16 v[74:77], v[188:191], v[220:223], v[74:77]
	v_mfma_f32_16x16x32_bf16 v[126:129], v[160:163], v[200:203], v[126:129]
	v_mfma_f32_16x16x32_bf16 v[122:125], v[192:195], v[200:203], v[122:125]
	v_mfma_f32_16x16x32_bf16 v[110:113], v[160:163], v[208:211], v[110:113]
	v_mfma_f32_16x16x32_bf16 v[106:109], v[192:195], v[208:211], v[106:109]
	v_mfma_f32_16x16x32_bf16 v[94:97], v[160:163], v[216:219], v[94:97]
	v_mfma_f32_16x16x32_bf16 v[90:93], v[192:195], v[216:219], v[90:93]
	v_mfma_f32_16x16x32_bf16 v[78:81], v[160:163], v[224:227], v[78:81]
	v_mfma_f32_16x16x32_bf16 v[74:77], v[192:195], v[224:227], v[74:77]
	s_barrier
; #define PG8_STAGE(bufoff, gbase, voff) do { _Pragma("unroll") for (int _i = 0; _i < 2; ++_i) \
;     __builtin_amdgcn_global_load_lds((const unsigned*)((const char*)(gbase) + (voff)[_i]), (PG8_LAS unsigned*)(lds + (bufoff) + ldsw + _i * 8192), 16, 0, 0); } while (0)
; #define PG8_LDA(dst, b, h) do { _Pragma("unroll") for (int m = 0; m < 4; ++m) _Pragma("unroll") for (int k = 0; k < 2; ++k) dst[m][k] = *(const PG8_LAS bf16x8*)(lds + PG8_SA(b, h) + aoff + m * 2048 + k * 1024); } while (0)
; #define PG8_LDB(dst, b, h) do { _Pragma("unroll") for (int n = 0; n < 2; ++n) _Pragma("unroll") for (int k = 0; k < 2; ++k) dst[n][k] = *(const PG8_LAS bf16x8*)(lds + PG8_SB(b, h) + boff + n * 2048 + k * 1024); } while (0)
; #define PG8_MMA(ai, bj, At, Bt) do { __builtin_amdgcn_s_setprio(1); _Pragma("unroll") for (int m = 0; m < 4; ++m) _Pragma("unroll") for (int n = 0; n < 2; ++n) _Pragma("unroll") for (int k = 0; k < 2; ++k) \
;     acc[ai][bj][m][n] = __builtin_amdgcn_mfma_f32_16x16x32_bf16(Bt[n][k], At[m][k], acc[ai][bj][m][n], 0, 0, 0); __builtin_amdgcn_s_setprio(0); } while (0)
; #define PG8_WAIT_V(n) asm volatile("s_waitcnt vmcnt(" #n ")" ::: "memory")
; #define PG8_WAIT_L(n) asm volatile("s_waitcnt lgkmcnt(" #n ")" ::: "memory")
; #define PG8_BAR __builtin_amdgcn_s_barrier()
; #define PG8_SCHED __builtin_amdgcn_sched_barrier(0)
; template <class Epi>
; __device__ __forceinline__ void gemm_phase(PG8_LAS unsigned char* lds, const Gemm g, const StaticOrder& S, const Epi& E) {
;     ...
;       PG8_LDB(B1, 0, 1); PG8_STAGE(PG8_SB(0, 0), b2, voffB);
;       PG8_BAR; PG8_WAIT_L(0); PG8_MMA(0, 1, At, B1); PG8_BAR;
;       PG8_LDA(At, 0, 1); PG8_STAGE(PG8_SA(0, 0), a2, voffA);
;       PG8_BAR; PG8_WAIT_L(0); PG8_MMA(1, 0, At, B0); PG8_BAR; PG8_SCHED;
;       PG8_STAGE(PG8_SB(0, 1), b2 + hstep, voffB);
;       PG8_WAIT_V(6); PG8_BAR; PG8_MMA(1, 1, At, B1); PG8_BAR;
;       PG8_LDB(B0, 1, 0); PG8_SCHED; PG8_LDA(At, 1, 0); PG8_STAGE(PG8_SA(0, 1), a2 + hstep, voffA);
	s_add_i32 s62, 0, 0x14000
	s_add_i32 s59, s59, s19
	v_add_u32_e32 v0, s62, v164
	v_lshl_add_u64 v[244:245], s[46:47], 0, v[148:149]
	s_mov_b32 m0, s59
	ds_read_b128 v[228:231], v0
	ds_read_b128 v[232:235], v0 offset:1024
	ds_read_b128 v[236:239], v0 offset:2048
	ds_read_b128 v[240:243], v0 offset:3072
	global_load_lds_dwordx4 v[244:245], off
	v_lshl_add_u64 v[246:247], s[46:47], 0, v[150:151]
	s_add_i32 m0, s59, 0x2000
	s_nop 0
	global_load_lds_dwordx4 v[246:247], off
	s_barrier
	s_waitcnt lgkmcnt(0)
	s_waitcnt lgkmcnt(0)
	v_mfma_f32_16x16x32_bf16 v[118:121], v[228:231], v[196:199], v[118:121]
	v_mfma_f32_16x16x32_bf16 v[114:117], v[236:239], v[196:199], v[114:117]
	v_mfma_f32_16x16x32_bf16 v[102:105], v[228:231], v[204:207], v[102:105]
	v_mfma_f32_16x16x32_bf16 v[98:101], v[236:239], v[204:207], v[98:101]
	v_mfma_f32_16x16x32_bf16 v[86:89], v[228:231], v[212:215], v[86:89]
	v_mfma_f32_16x16x32_bf16 v[82:85], v[236:239], v[212:215], v[82:85]
	v_mfma_f32_16x16x32_bf16 v[70:73], v[228:231], v[220:223], v[70:73]
	v_mfma_f32_16x16x32_bf16 v[66:69], v[236:239], v[220:223], v[66:69]
	v_mfma_f32_16x16x32_bf16 v[118:121], v[232:235], v[200:203], v[118:121]
	v_mfma_f32_16x16x32_bf16 v[114:117], v[240:243], v[200:203], v[114:117]
	v_mfma_f32_16x16x32_bf16 v[102:105], v[232:235], v[208:211], v[102:105]
	v_mfma_f32_16x16x32_bf16 v[98:101], v[240:243], v[208:211], v[98:101]
	v_mfma_f32_16x16x32_bf16 v[86:89], v[232:235], v[216:219], v[86:89]
	v_mfma_f32_16x16x32_bf16 v[82:85], v[240:243], v[216:219], v[82:85]
	v_mfma_f32_16x16x32_bf16 v[70:73], v[232:235], v[224:227], v[70:73]
	v_mfma_f32_16x16x32_bf16 v[66:69], v[240:243], v[224:227], v[66:69]
	s_mov_b32 m0, s28
	v_lshl_add_u64 v[248:249], s[48:49], 0, v[148:149]
	s_barrier
	ds_read_b128 v[196:199], v166 offset:16384
	ds_read_b128 v[200:203], v166 offset:17408
	ds_read_b128 v[204:207], v166 offset:18432
	ds_read_b128 v[208:211], v166 offset:19456
	ds_read_b128 v[212:215], v166 offset:20480
	ds_read_b128 v[216:219], v166 offset:21504
	ds_read_b128 v[220:223], v166 offset:22528
	ds_read_b128 v[224:227], v166 offset:23552
	global_load_lds_dwordx4 v[248:249], off
	v_lshl_add_u64 v[178:179], s[48:49], 0, v[150:151]
	s_mov_b32 m0, s50
	s_nop 0
	global_load_lds_dwordx4 v[178:179], off
	s_barrier
	s_waitcnt lgkmcnt(0)
	s_waitcnt lgkmcnt(0)
	v_mfma_f32_16x16x32_bf16 v[62:65], v[156:159], v[196:199], v[62:65]
	v_mfma_f32_16x16x32_bf16 v[58:61], v[188:191], v[196:199], v[58:61]
	v_mfma_f32_16x16x32_bf16 v[46:49], v[156:159], v[204:207], v[46:49]
	v_mfma_f32_16x16x32_bf16 v[42:45], v[188:191], v[204:207], v[42:45]
	v_mfma_f32_16x16x32_bf16 v[30:33], v[156:159], v[212:215], v[30:33]
	v_mfma_f32_16x16x32_bf16 v[26:29], v[188:191], v[212:215], v[26:29]
	v_mfma_f32_16x16x32_bf16 v[14:17], v[156:159], v[220:223], v[14:17]
	v_mfma_f32_16x16x32_bf16 v[10:13], v[188:191], v[220:223], v[10:13]
	v_mfma_f32_16x16x32_bf16 v[62:65], v[160:163], v[200:203], v[62:65]
	v_mfma_f32_16x16x32_bf16 v[58:61], v[192:195], v[200:203], v[58:61]
	v_mfma_f32_16x16x32_bf16 v[46:49], v[160:163], v[208:211], v[46:49]
	v_mfma_f32_16x16x32_bf16 v[42:45], v[192:195], v[208:211], v[42:45]
	v_mfma_f32_16x16x32_bf16 v[30:33], v[160:163], v[216:219], v[30:33]
	v_mfma_f32_16x16x32_bf16 v[26:29], v[192:195], v[216:219], v[26:29]
	v_mfma_f32_16x16x32_bf16 v[14:17], v[160:163], v[224:227], v[14:17]
	v_mfma_f32_16x16x32_bf16 v[10:13], v[192:195], v[224:227], v[10:13]
	s_barrier
	s_add_u32 s60, s46, 0x40000
	s_addc_u32 s61, s47, 0
	s_add_i32 s59, s62, s19
	v_lshl_add_u64 v[156:157], s[60:61], 0, v[148:149]
	s_mov_b32 m0, s59
	s_nop 0
	global_load_lds_dwordx4 v[156:157], off
	v_lshl_add_u64 v[156:157], s[60:61], 0, v[150:151]
	s_add_i32 m0, s59, 0x2000
	s_nop 0
	global_load_lds_dwordx4 v[156:157], off
	s_waitcnt vmcnt(6)
	s_barrier
	v_mfma_f32_16x16x32_bf16 v[54:57], v[228:231], v[196:199], v[54:57]
	v_mfma_f32_16x16x32_bf16 v[50:53], v[236:239], v[196:199], v[50:53]
	v_mfma_f32_16x16x32_bf16 v[38:41], v[228:231], v[204:207], v[38:41]
	v_mfma_f32_16x16x32_bf16 v[34:37], v[236:239], v[204:207], v[34:37]
	v_mfma_f32_16x16x32_bf16 v[22:25], v[228:231], v[212:215], v[22:25]
	v_mfma_f32_16x16x32_bf16 v[18:21], v[236:239], v[212:215], v[18:21]
	v_mfma_f32_16x16x32_bf16 v[6:9], v[228:231], v[220:223], v[6:9]
	v_mfma_f32_16x16x32_bf16 v[2:5], v[236:239], v[220:223], v[2:5]
	v_mfma_f32_16x16x32_bf16 v[54:57], v[232:235], v[200:203], v[54:57]
	v_mfma_f32_16x16x32_bf16 v[50:53], v[240:243], v[200:203], v[50:53]
	v_mfma_f32_16x16x32_bf16 v[38:41], v[232:235], v[208:211], v[38:41]
	v_mfma_f32_16x16x32_bf16 v[34:37], v[240:243], v[208:211], v[34:37]
	v_mfma_f32_16x16x32_bf16 v[22:25], v[232:235], v[216:219], v[22:25]
	v_mfma_f32_16x16x32_bf16 v[18:21], v[240:243], v[216:219], v[18:21]
	v_mfma_f32_16x16x32_bf16 v[6:9], v[232:235], v[224:227], v[6:9]
	v_mfma_f32_16x16x32_bf16 v[2:5], v[240:243], v[224:227], v[2:5]
	s_add_i32 s59, 0, 0x18000
	v_add_u32_e32 v0, s59, v164
	s_barrier
	ds_read_b128 v[156:159], v0
	ds_read_b128 v[160:163], v0 offset:1024
	ds_read_b128 v[188:191], v0 offset:2048
	ds_read_b128 v[192:195], v0 offset:3072
	s_add_u32 s48, s48, 0x40000
	s_addc_u32 s49, s49, 0
	s_mov_b32 m0, s51
	v_lshl_add_u64 v[228:229], s[48:49], 0, v[148:149]
	ds_read_b128 v[196:199], v166 offset:32768
	ds_read_b128 v[200:203], v166 offset:33792
	ds_read_b128 v[204:207], v166 offset:34816
	ds_read_b128 v[208:211], v166 offset:35840
	ds_read_b128 v[212:215], v166 offset:36864
	ds_read_b128 v[216:219], v166 offset:37888
	ds_read_b128 v[220:223], v166 offset:38912
	ds_read_b128 v[224:227], v166 offset:39936
	global_load_lds_dwordx4 v[228:229], off
	v_lshl_add_u64 v[228:229], s[48:49], 0, v[150:151]
	s_mov_b32 m0, s52
	s_nop 0
	global_load_lds_dwordx4 v[228:229], off
	s_waitcnt lgkmcnt(8)
	s_barrier
; #define PG8_STAGE(bufoff, gbase, voff) do { _Pragma("unroll") for (int _i = 0; _i < 2; ++_i) \
;     __builtin_amdgcn_global_load_lds((const unsigned*)((const char*)(gbase) + (voff)[_i]), (PG8_LAS unsigned*)(lds + (bufoff) + ldsw + _i * 8192), 16, 0, 0); } while (0)
; #define PG8_LDA(dst, b, h) do { _Pragma("unroll") for (int m = 0; m < 4; ++m) _Pragma("unroll") for (int k = 0; k < 2; ++k) dst[m][k] = *(const PG8_LAS bf16x8*)(lds + PG8_SA(b, h) + aoff + m * 2048 + k * 1024); } while (0)
; #define PG8_LDB(dst, b, h) do { _Pragma("unroll") for (int n = 0; n < 2; ++n) _Pragma("unroll") for (int k = 0; k < 2; ++k) dst[n][k] = *(const PG8_LAS bf16x8*)(lds + PG8_SB(b, h) + boff + n * 2048 + k * 1024); } while (0)
; #define PG8_MMA(ai, bj, At, Bt) do { __builtin_amdgcn_s_setprio(1); _Pragma("unroll") for (int m = 0; m < 4; ++m) _Pragma("unroll") for (int n = 0; n < 2; ++n) _Pragma("unroll") for (int k = 0; k < 2; ++k) \
;     acc[ai][bj][m][n] = __builtin_amdgcn_mfma_f32_16x16x32_bf16(Bt[n][k], At[m][k], acc[ai][bj][m][n], 0, 0, 0); __builtin_amdgcn_s_setprio(0); } while (0)
; #define PG8_WAIT_V(n) asm volatile("s_waitcnt vmcnt(" #n ")" ::: "memory")
; #define PG8_WAIT_L(n) asm volatile("s_waitcnt lgkmcnt(" #n ")" ::: "memory")
; #define PG8_BAR __builtin_amdgcn_s_barrier()
; #define PG8_SCHED __builtin_amdgcn_sched_barrier(0)
; template <class Epi>
; __device__ __forceinline__ void gemm_phase(PG8_LAS unsigned char* lds, const Gemm g, const StaticOrder& S, const Epi& E) {
;     ...
;       PG8_LDB(B0, 1, 0); PG8_SCHED; PG8_LDA(At, 1, 0); PG8_STAGE(PG8_SA(0, 1), a2 + hstep, voffA);
;       PG8_WAIT_L(8); PG8_BAR; PG8_WAIT_L(0); PG8_MMA(0, 0, At, B0); PG8_BAR; PG8_SCHED;
;       PG8_LDB(B1, 1, 1); PG8_STAGE(PG8_SB(1, 0), b3, voffB);
;       PG8_BAR; PG8_WAIT_L(0); PG8_MMA(0, 1, At, B1); PG8_BAR;
;       PG8_LDA(At, 1, 1); PG8_STAGE(PG8_SA(1, 0), a3, voffA);
;       PG8_BAR; PG8_WAIT_L(0); PG8_MMA(1, 0, At, B0); PG8_BAR; PG8_SCHED;
;       PG8_STAGE(PG8_SB(1, 1), b3 + hstep, voffB);
;       PG8_WAIT_V(6); PG8_BAR; PG8_MMA(1, 1, At, B1); PG8_BAR;
	s_waitcnt lgkmcnt(0)
	s_waitcnt lgkmcnt(0)
	v_mfma_f32_16x16x32_bf16 v[126:129], v[156:159], v[196:199], v[126:129]
	v_mfma_f32_16x16x32_bf16 v[122:125], v[188:191], v[196:199], v[122:125]
	v_mfma_f32_16x16x32_bf16 v[110:113], v[156:159], v[204:207], v[110:113]
	v_mfma_f32_16x16x32_bf16 v[106:109], v[188:191], v[204:207], v[106:109]
	v_mfma_f32_16x16x32_bf16 v[94:97], v[156:159], v[212:215], v[94:97]
	v_mfma_f32_16x16x32_bf16 v[90:93], v[188:191], v[212:215], v[90:93]
	v_mfma_f32_16x16x32_bf16 v[78:81], v[156:159], v[220:223], v[78:81]
	v_mfma_f32_16x16x32_bf16 v[74:77], v[188:191], v[220:223], v[74:77]
	v_mfma_f32_16x16x32_bf16 v[126:129], v[160:163], v[200:203], v[126:129]
	v_mfma_f32_16x16x32_bf16 v[122:125], v[192:195], v[200:203], v[122:125]
	v_mfma_f32_16x16x32_bf16 v[110:113], v[160:163], v[208:211], v[110:113]
	v_mfma_f32_16x16x32_bf16 v[106:109], v[192:195], v[208:211], v[106:109]
	v_mfma_f32_16x16x32_bf16 v[94:97], v[160:163], v[216:219], v[94:97]
	v_mfma_f32_16x16x32_bf16 v[90:93], v[192:195], v[216:219], v[90:93]
	v_mfma_f32_16x16x32_bf16 v[78:81], v[160:163], v[224:227], v[78:81]
	v_mfma_f32_16x16x32_bf16 v[74:77], v[192:195], v[224:227], v[74:77]
	s_barrier
	s_add_i32 s48, 0, 0x1c000
	s_add_i32 s49, s59, s19
	v_add_u32_e32 v0, s48, v164
	v_lshl_add_u64 v[244:245], v[244:245], 0, s[4:5]
	s_mov_b32 m0, s49
	ds_read_b128 v[228:231], v0
	ds_read_b128 v[232:235], v0 offset:1024
	ds_read_b128 v[236:239], v0 offset:2048
	ds_read_b128 v[240:243], v0 offset:3072
	global_load_lds_dwordx4 v[244:245], off
	v_lshl_add_u64 v[244:245], v[246:247], 0, s[4:5]
	s_add_i32 m0, s49, 0x2000
	s_nop 0
	global_load_lds_dwordx4 v[244:245], off
	s_barrier
	s_waitcnt lgkmcnt(0)
	s_waitcnt lgkmcnt(0)
	v_mfma_f32_16x16x32_bf16 v[118:121], v[228:231], v[196:199], v[118:121]
	v_mfma_f32_16x16x32_bf16 v[114:117], v[236:239], v[196:199], v[114:117]
	v_mfma_f32_16x16x32_bf16 v[102:105], v[228:231], v[204:207], v[102:105]
	v_mfma_f32_16x16x32_bf16 v[98:101], v[236:239], v[204:207], v[98:101]
	v_mfma_f32_16x16x32_bf16 v[86:89], v[228:231], v[212:215], v[86:89]
	v_mfma_f32_16x16x32_bf16 v[82:85], v[236:239], v[212:215], v[82:85]
	v_mfma_f32_16x16x32_bf16 v[70:73], v[228:231], v[220:223], v[70:73]
	v_mfma_f32_16x16x32_bf16 v[66:69], v[236:239], v[220:223], v[66:69]
	v_mfma_f32_16x16x32_bf16 v[118:121], v[232:235], v[200:203], v[118:121]
	v_mfma_f32_16x16x32_bf16 v[114:117], v[240:243], v[200:203], v[114:117]
	v_mfma_f32_16x16x32_bf16 v[102:105], v[232:235], v[208:211], v[102:105]
	v_mfma_f32_16x16x32_bf16 v[98:101], v[240:243], v[208:211], v[98:101]
	v_mfma_f32_16x16x32_bf16 v[86:89], v[232:235], v[216:219], v[86:89]
	v_mfma_f32_16x16x32_bf16 v[82:85], v[240:243], v[216:219], v[82:85]
	v_mfma_f32_16x16x32_bf16 v[70:73], v[232:235], v[224:227], v[70:73]
	v_mfma_f32_16x16x32_bf16 v[66:69], v[240:243], v[224:227], v[66:69]
	s_mov_b32 m0, s53
	v_lshl_add_u64 v[244:245], v[248:249], 0, s[4:5]
	s_barrier
	ds_read_b128 v[196:199], v166 offset:49152
	ds_read_b128 v[200:203], v166 offset:50176
	ds_read_b128 v[204:207], v166 offset:51200
	ds_read_b128 v[208:211], v166 offset:52224
	ds_read_b128 v[212:215], v166 offset:53248
	ds_read_b128 v[216:219], v166 offset:54272
	ds_read_b128 v[220:223], v166 offset:55296
	ds_read_b128 v[224:227], v166 offset:56320
	global_load_lds_dwordx4 v[244:245], off
	v_lshl_add_u64 v[178:179], v[178:179], 0, s[4:5]
	s_mov_b32 m0, s54
	s_nop 0
	global_load_lds_dwordx4 v[178:179], off
	s_barrier
	s_waitcnt lgkmcnt(0)
	s_waitcnt lgkmcnt(0)
	v_mfma_f32_16x16x32_bf16 v[62:65], v[156:159], v[196:199], v[62:65]
	v_mfma_f32_16x16x32_bf16 v[58:61], v[188:191], v[196:199], v[58:61]
	v_mfma_f32_16x16x32_bf16 v[46:49], v[156:159], v[204:207], v[46:49]
	v_mfma_f32_16x16x32_bf16 v[42:45], v[188:191], v[204:207], v[42:45]
	v_mfma_f32_16x16x32_bf16 v[30:33], v[156:159], v[212:215], v[30:33]
	v_mfma_f32_16x16x32_bf16 v[26:29], v[188:191], v[212:215], v[26:29]
	v_mfma_f32_16x16x32_bf16 v[14:17], v[156:159], v[220:223], v[14:17]
	v_mfma_f32_16x16x32_bf16 v[10:13], v[188:191], v[220:223], v[10:13]
	v_mfma_f32_16x16x32_bf16 v[62:65], v[160:163], v[200:203], v[62:65]
	v_mfma_f32_16x16x32_bf16 v[58:61], v[192:195], v[200:203], v[58:61]
	v_mfma_f32_16x16x32_bf16 v[46:49], v[160:163], v[208:211], v[46:49]
	v_mfma_f32_16x16x32_bf16 v[42:45], v[192:195], v[208:211], v[42:45]
	v_mfma_f32_16x16x32_bf16 v[30:33], v[160:163], v[216:219], v[30:33]
	v_mfma_f32_16x16x32_bf16 v[26:29], v[192:195], v[216:219], v[26:29]
	v_mfma_f32_16x16x32_bf16 v[14:17], v[160:163], v[224:227], v[14:17]
	v_mfma_f32_16x16x32_bf16 v[10:13], v[192:195], v[224:227], v[10:13]
	s_barrier
	s_add_u32 s46, s46, 0x40080
	s_addc_u32 s47, s47, 0
	s_add_i32 s48, s48, s19
	v_lshl_add_u64 v[156:157], s[46:47], 0, v[148:149]
	s_mov_b32 m0, s48
	s_nop 0
	global_load_lds_dwordx4 v[156:157], off
	v_lshl_add_u64 v[156:157], s[46:47], 0, v[150:151]
	s_add_i32 m0, s48, 0x2000
	s_nop 0
	global_load_lds_dwordx4 v[156:157], off
	s_waitcnt vmcnt(6)
	s_barrier
	v_mfma_f32_16x16x32_bf16 v[54:57], v[228:231], v[196:199], v[54:57]
	v_mfma_f32_16x16x32_bf16 v[50:53], v[236:239], v[196:199], v[50:53]
	v_mfma_f32_16x16x32_bf16 v[38:41], v[228:231], v[204:207], v[38:41]
	v_mfma_f32_16x16x32_bf16 v[34:37], v[236:239], v[204:207], v[34:37]
	v_mfma_f32_16x16x32_bf16 v[22:25], v[228:231], v[212:215], v[22:25]
	v_mfma_f32_16x16x32_bf16 v[18:21], v[236:239], v[212:215], v[18:21]
	v_mfma_f32_16x16x32_bf16 v[6:9], v[228:231], v[220:223], v[6:9]
	v_mfma_f32_16x16x32_bf16 v[2:5], v[236:239], v[220:223], v[2:5]
	v_mfma_f32_16x16x32_bf16 v[54:57], v[232:235], v[200:203], v[54:57]
	v_mfma_f32_16x16x32_bf16 v[50:53], v[240:243], v[200:203], v[50:53]
	v_mfma_f32_16x16x32_bf16 v[38:41], v[232:235], v[208:211], v[38:41]
	v_mfma_f32_16x16x32_bf16 v[34:37], v[240:243], v[208:211], v[34:37]
	v_mfma_f32_16x16x32_bf16 v[22:25], v[232:235], v[216:219], v[22:25]
	v_mfma_f32_16x16x32_bf16 v[18:21], v[240:243], v[216:219], v[18:21]
	v_mfma_f32_16x16x32_bf16 v[6:9], v[232:235], v[224:227], v[6:9]
	v_mfma_f32_16x16x32_bf16 v[2:5], v[240:243], v[224:227], v[2:5]
	s_add_i32 s58, s58, 2
	s_add_u32 s44, s44, 0x100
	s_addc_u32 s45, s45, 0
	s_add_u32 s56, s56, 0x100
	s_addc_u32 s57, s57, 0
	s_cmp_gt_u32 s58, 13
	s_barrier
;   __device__ __forceinline__ void operator()(const f32x4 (&acc)[2][2][4][2], const pg8::Unit& u, int wr, int wc, int fr, int fq) const {
; #pragma unroll
;     for (int ai = 0; ai < 2; ++ai)
; #pragma unroll
;       for (int m = 0; m < 4; ++m) { const int row = u.pm * 256 + ai * 128 + wr * 64 + m * 16 + fr;
; #pragma unroll
;         for (int bj = 0; bj < 2; ++bj)
; #pragma unroll
;           for (int n = 0; n < 2; ++n) f(row, u.pn * 256 + bj * 128 + wc * 32 + n * 16 + 4 * fq, acc[ai][bj][m][n]); }
	s_cbranch_scc0 .LBB0_1593
	s_movk_i32 s7, 0xa00
	v_bfe_u32 v228, v168, 4, 1
	v_mul_u32_u24_e32 v228, 24, v228
	v_lshl_add_u32 v228, v165, 1, v228
	v_mad_u32_u24 v228, v147, s7, v228
	s_mul_i32 s44, s42, 0xa0000
	s_lshl_b32 s46, s30, 9
	s_add_i32 s44, s44, s46
	s_cmp_lt_u32 s30, 5
	s_cselect_b32 s46, s2, s26
	s_cselect_b32 s47, s3, s27
	s_cselect_b32 s48, 0, 0xa00
	s_sub_u32 s44, s44, s48
	s_add_u32 s44, s46, s44
	s_addc_u32 s45, s47, 0
	v_cvt_pk_bf16_f32 v125, v124, v125
	v_cvt_pk_bf16_f32 v124, v122, v123
	v_cvt_pk_bf16_f32 v122, v126, v127
	v_cvt_pk_bf16_f32 v123, v128, v129
	v_cvt_pk_bf16_f32 v117, v116, v117
	v_cvt_pk_bf16_f32 v116, v114, v115
	v_cvt_pk_bf16_f32 v114, v118, v119
	v_cvt_pk_bf16_f32 v115, v120, v121
	v_permlane16_swap_b32_e32 v122, v124
	v_permlane16_swap_b32_e32 v123, v125
	v_permlane16_swap_b32_e32 v114, v116
	v_permlane16_swap_b32_e32 v115, v117
	global_store_dwordx4 v228, v[122:125], s[44:45]
	global_store_dwordx4 v228, v[114:117], s[44:45] offset:256
	s_add_u32 s44, s44, 0xa000
	s_addc_u32 s45, s45, 0
	v_cvt_pk_bf16_f32 v109, v108, v109
	v_cvt_pk_bf16_f32 v108, v106, v107
	v_cvt_pk_bf16_f32 v106, v110, v111
	v_cvt_pk_bf16_f32 v107, v112, v113
	v_cvt_pk_bf16_f32 v101, v100, v101
	v_cvt_pk_bf16_f32 v100, v98, v99
	v_cvt_pk_bf16_f32 v98, v102, v103
	v_cvt_pk_bf16_f32 v99, v104, v105
	v_permlane16_swap_b32_e32 v106, v108
	v_permlane16_swap_b32_e32 v107, v109
	v_permlane16_swap_b32_e32 v98, v100
	v_permlane16_swap_b32_e32 v99, v101
	global_store_dwordx4 v228, v[106:109], s[44:45]
	global_store_dwordx4 v228, v[98:101], s[44:45] offset:256
	s_add_u32 s44, s44, 0xa000
	s_addc_u32 s45, s45, 0
	v_cvt_pk_bf16_f32 v93, v92, v93
	v_cvt_pk_bf16_f32 v92, v90, v91
	v_cvt_pk_bf16_f32 v90, v94, v95
	v_cvt_pk_bf16_f32 v91, v96, v97
	v_cvt_pk_bf16_f32 v85, v84, v85
	v_cvt_pk_bf16_f32 v84, v82, v83
	v_cvt_pk_bf16_f32 v82, v86, v87
	v_cvt_pk_bf16_f32 v83, v88, v89
	v_permlane16_swap_b32_e32 v90, v92
	v_permlane16_swap_b32_e32 v91, v93
	v_permlane16_swap_b32_e32 v82, v84
	v_permlane16_swap_b32_e32 v83, v85
	global_store_dwordx4 v228, v[90:93], s[44:45]
	global_store_dwordx4 v228, v[82:85], s[44:45] offset:256
	s_add_u32 s44, s44, 0xa000
	s_addc_u32 s45, s45, 0
	v_cvt_pk_bf16_f32 v77, v76, v77
	v_cvt_pk_bf16_f32 v76, v74, v75
	v_cvt_pk_bf16_f32 v74, v78, v79
	v_cvt_pk_bf16_f32 v75, v80, v81
	v_cvt_pk_bf16_f32 v69, v68, v69
	v_cvt_pk_bf16_f32 v68, v66, v67
	v_cvt_pk_bf16_f32 v66, v70, v71
	v_cvt_pk_bf16_f32 v67, v72, v73
	v_permlane16_swap_b32_e32 v74, v76
	v_permlane16_swap_b32_e32 v75, v77
	v_permlane16_swap_b32_e32 v66, v68
	v_permlane16_swap_b32_e32 v67, v69
	global_store_dwordx4 v228, v[74:77], s[44:45]
	global_store_dwordx4 v228, v[66:69], s[44:45] offset:256
	s_add_u32 s44, s44, 0x32000
	s_addc_u32 s45, s45, 0
	v_cvt_pk_bf16_f32 v61, v60, v61
	v_cvt_pk_bf16_f32 v60, v58, v59
	v_cvt_pk_bf16_f32 v58, v62, v63
	v_cvt_pk_bf16_f32 v59, v64, v65
	v_cvt_pk_bf16_f32 v53, v52, v53
	v_cvt_pk_bf16_f32 v52, v50, v51
	v_cvt_pk_bf16_f32 v50, v54, v55
	v_cvt_pk_bf16_f32 v51, v56, v57
	v_permlane16_swap_b32_e32 v58, v60
	v_permlane16_swap_b32_e32 v59, v61
	v_permlane16_swap_b32_e32 v50, v52
	v_permlane16_swap_b32_e32 v51, v53
	global_store_dwordx4 v228, v[58:61], s[44:45]
	global_store_dwordx4 v228, v[50:53], s[44:45] offset:256
	s_add_u32 s44, s44, 0xa000
	s_addc_u32 s45, s45, 0
	v_cvt_pk_bf16_f32 v45, v44, v45
	v_cvt_pk_bf16_f32 v44, v42, v43
	v_cvt_pk_bf16_f32 v42, v46, v47
	v_cvt_pk_bf16_f32 v43, v48, v49
	v_cvt_pk_bf16_f32 v37, v36, v37
	v_cvt_pk_bf16_f32 v36, v34, v35
	v_cvt_pk_bf16_f32 v34, v38, v39
	v_cvt_pk_bf16_f32 v35, v40, v41
	v_permlane16_swap_b32_e32 v42, v44
	v_permlane16_swap_b32_e32 v43, v45
	v_permlane16_swap_b32_e32 v34, v36
	v_permlane16_swap_b32_e32 v35, v37
	global_store_dwordx4 v228, v[42:45], s[44:45]
	global_store_dwordx4 v228, v[34:37], s[44:45] offset:256
	s_add_u32 s44, s44, 0xa000
	s_addc_u32 s45, s45, 0
	v_cvt_pk_bf16_f32 v29, v28, v29
	v_cvt_pk_bf16_f32 v28, v26, v27
	v_cvt_pk_bf16_f32 v26, v30, v31
	v_cvt_pk_bf16_f32 v27, v32, v33
	v_cvt_pk_bf16_f32 v21, v20, v21
	v_cvt_pk_bf16_f32 v20, v18, v19
	v_cvt_pk_bf16_f32 v18, v22, v23
	v_cvt_pk_bf16_f32 v19, v24, v25
	v_permlane16_swap_b32_e32 v26, v28
	v_permlane16_swap_b32_e32 v27, v29
	v_permlane16_swap_b32_e32 v18, v20
	v_permlane16_swap_b32_e32 v19, v21
	global_store_dwordx4 v228, v[26:29], s[44:45]
	global_store_dwordx4 v228, v[18:21], s[44:45] offset:256
	s_add_u32 s44, s44, 0xa000
	s_addc_u32 s45, s45, 0
	v_cvt_pk_bf16_f32 v13, v12, v13
	v_cvt_pk_bf16_f32 v12, v10, v11
	v_cvt_pk_bf16_f32 v10, v14, v15
	v_cvt_pk_bf16_f32 v11, v16, v17
	v_cvt_pk_bf16_f32 v5, v4, v5
	v_cvt_pk_bf16_f32 v4, v2, v3
	v_cvt_pk_bf16_f32 v2, v6, v7
	v_cvt_pk_bf16_f32 v3, v8, v9
	v_permlane16_swap_b32_e32 v10, v12
	v_permlane16_swap_b32_e32 v11, v13
	v_permlane16_swap_b32_e32 v2, v4
	v_permlane16_swap_b32_e32 v3, v5
	global_store_dwordx4 v228, v[10:13], s[44:45]
	global_store_dwordx4 v228, v[2:5], s[44:45] offset:256
	s_branch .Llin_latch
